# attention x6 loops: per-step-pair counter updates merged into one per trip, leftover dead scalar ops removed
# baseline (speedup 1.0000x reference)
.Lst0_u6_loop:
	s_add_i32 s46, s58, 0
	s_mov_b32 m0, s46
	s_nop 0
	global_load_lds_dwordx4 v198, s[98:99]
	s_add_i32 m0, s46, 0x400
	s_nop 0
	global_load_lds_dwordx4 v194, s[98:99]
	s_add_i32 s48, s58, 0x8000
	s_add_i32 m0, s48, 0xc000
	s_nop 0
	global_load_lds_dwordx4 v196, s[100:101]
	s_add_i32 m0, s48, 0xc400
	s_nop 0
	global_load_lds_dwordx4 v192, s[100:101]
	ds_read_b128 v[96:99], v205 offset:16384
	ds_read_b128 v[100:103], v205 offset:24576
	s_waitcnt lgkmcnt(0)
	v_mfma_f32_32x32x16_bf16 v[112:127], v[96:99], v[160:163], 0
	ds_read_b128 v[128:131], v211 offset:16384
	ds_read_b128 v[132:135], v211 offset:24576
	ds_read_b128 v[136:139], v212 offset:16384
	v_exp_f32_e32 v140, v48
	v_exp_f32_e32 v141, v49
	v_exp_f32_e32 v142, v50
	v_exp_f32_e32 v143, v51
	ds_read_b128 v[48:51], v212 offset:24576
	v_mfma_f32_32x32x16_bf16 v[96:111], v[100:103], v[160:163], 0
	v_exp_f32_e32 v144, v52
	v_exp_f32_e32 v145, v53
	v_exp_f32_e32 v146, v54
	v_exp_f32_e32 v147, v55
	s_waitcnt lgkmcnt(0)
	v_mfma_f32_32x32x16_bf16 v[112:127], v[128:131], v[164:167], v[112:127]
	ds_read_b128 v[52:55], v213 offset:16384
	v_exp_f32_e32 v148, v56
	v_exp_f32_e32 v149, v57
	v_exp_f32_e32 v150, v58
	v_exp_f32_e32 v151, v59
	v_mfma_f32_32x32x16_bf16 v[96:111], v[132:135], v[164:167], v[96:111]
	ds_read_b128 v[56:59], v213 offset:24576
	v_exp_f32_e32 v128, v60
	v_exp_f32_e32 v129, v61
	v_exp_f32_e32 v130, v62
	v_exp_f32_e32 v131, v63
	v_mfma_f32_32x32x16_bf16 v[112:127], v[136:139], v[168:171], v[112:127]
	ds_read_b128 v[60:63], v206 offset:49152
	v_exp_f32_e32 v132, v32
	v_exp_f32_e32 v133, v33
	v_exp_f32_e32 v134, v34
	v_exp_f32_e32 v135, v35
	v_mfma_f32_32x32x16_bf16 v[96:111], v[48:51], v[168:171], v[96:111]
	ds_read_b128 v[32:35], v206 offset:53248
	v_exp_f32_e32 v136, v36
	v_exp_f32_e32 v137, v37
	v_exp_f32_e32 v138, v38
	v_exp_f32_e32 v139, v39
	s_waitcnt lgkmcnt(0)
	v_mfma_f32_32x32x16_bf16 v[112:127], v[52:55], v[172:175], v[112:127]
	ds_read_b128 v[36:39], v206 offset:57344
	v_exp_f32_e32 v152, v40
	v_exp_f32_e32 v153, v41
	v_exp_f32_e32 v154, v42
	v_exp_f32_e32 v155, v43
	v_mfma_f32_32x32x16_bf16 v[96:111], v[56:59], v[172:175], v[96:111]
	ds_read_b128 v[40:43], v206 offset:61440
	v_exp_f32_e32 v156, v44
	v_exp_f32_e32 v157, v45
	v_exp_f32_e32 v158, v46
	v_exp_f32_e32 v159, v47
	v_cvt_pk_bf16_f32 v44, v140, v141
	v_cvt_pk_bf16_f32 v45, v142, v143
	v_cvt_pk_bf16_f32 v46, v144, v145
	v_cvt_pk_bf16_f32 v47, v146, v147
	s_nop 1
	v_mfma_f32_32x32x16_bf16 v[80:95], v[60:63], v[44:47], v[80:95]
	ds_read_b128 v[48:51], v207 offset:49152
	v_cvt_pk_bf16_f32 v52, v148, v149
	v_cvt_pk_bf16_f32 v53, v150, v151
	v_cvt_pk_bf16_f32 v54, v128, v129
	v_cvt_pk_bf16_f32 v55, v130, v131
	v_mfma_f32_32x32x16_bf16 v[64:79], v[32:35], v[44:47], v[64:79]
	ds_read_b128 v[56:59], v207 offset:53248
	v_pk_add_f32 v[62:63], v[146:147], v[142:143]
	v_pk_add_f32 v[60:61], v[144:145], v[140:141]
	s_waitcnt lgkmcnt(0)
	v_mfma_f32_32x32x16_bf16 v[16:31], v[36:39], v[44:47], v[16:31]
	ds_read_b128 v[32:35], v207 offset:57344
	v_add_f32_e64 v62, v150, v62
	v_add_f32_e64 v63, v151, v63
	v_add_f32_e64 v60, v148, v60
	v_add_f32_e64 v61, v149, v61
	v_pk_add_f32 v[62:63], v[130:131], v[62:63]
	v_pk_add_f32 v[60:61], v[128:129], v[60:61]
	v_mfma_f32_32x32x16_bf16 v[0:15], v[40:43], v[44:47], v[0:15]
	ds_read_b128 v[36:39], v207 offset:61440
	v_mfma_f32_32x32x16_bf16 v[80:95], v[48:51], v[52:55], v[80:95]
	ds_read_b128 v[40:43], v208 offset:49152
	v_cvt_pk_bf16_f32 v44, v132, v133
	v_cvt_pk_bf16_f32 v45, v134, v135
	v_cvt_pk_bf16_f32 v46, v136, v137
	v_cvt_pk_bf16_f32 v47, v138, v139
	v_mfma_f32_32x32x16_bf16 v[64:79], v[56:59], v[52:55], v[64:79]
	ds_read_b128 v[48:51], v208 offset:53248
	v_add_f32_e64 v62, v134, v62
	v_add_f32_e64 v63, v135, v63
	v_add_f32_e64 v60, v132, v60
	v_add_f32_e64 v61, v133, v61
	v_pk_add_f32 v[62:63], v[138:139], v[62:63]
	v_pk_add_f32 v[60:61], v[136:137], v[60:61]
	s_waitcnt lgkmcnt(0)
	v_mfma_f32_32x32x16_bf16 v[16:31], v[32:35], v[52:55], v[16:31]
	ds_read_b128 v[56:59], v208 offset:57344
	v_add_f32_e64 v62, v154, v62
	v_add_f32_e64 v63, v155, v63
	v_add_f32_e64 v60, v152, v60
	v_add_f32_e64 v61, v153, v61
	v_pk_add_f32 v[130:131], v[158:159], v[62:63]
	v_pk_add_f32 v[128:129], v[156:157], v[60:61]
	v_mfma_f32_32x32x16_bf16 v[0:15], v[36:39], v[52:55], v[0:15]
	ds_read_b128 v[32:35], v208 offset:61440
	v_mfma_f32_32x32x16_bf16 v[80:95], v[40:43], v[44:47], v[80:95]
	ds_read_b128 v[36:39], v209 offset:49152
	v_cvt_pk_bf16_f32 v52, v152, v153
	v_cvt_pk_bf16_f32 v53, v154, v155
	v_cvt_pk_bf16_f32 v54, v156, v157
	v_cvt_pk_bf16_f32 v55, v158, v159
	v_mfma_f32_32x32x16_bf16 v[64:79], v[48:51], v[44:47], v[64:79]
	ds_read_b128 v[40:43], v209 offset:53248
	s_waitcnt lgkmcnt(0)
	v_mfma_f32_32x32x16_bf16 v[16:31], v[56:59], v[44:47], v[16:31]
	ds_read_b128 v[48:51], v209 offset:57344
	v_mfma_f32_32x32x16_bf16 v[0:15], v[32:35], v[44:47], v[0:15]
	ds_read_b128 v[56:59], v209 offset:61440
	v_mfma_f32_32x32x16_bf16 v[80:95], v[36:39], v[52:55], v[80:95]
	v_mfma_f32_32x32x16_bf16 v[64:79], v[40:43], v[52:55], v[64:79]
	s_waitcnt lgkmcnt(0)
	v_mfma_f32_32x32x16_bf16 v[16:31], v[48:51], v[52:55], v[16:31]
	v_mfma_f32_32x32x16_bf16 v[0:15], v[56:59], v[52:55], v[0:15]
	s_waitcnt vmcnt(4) lgkmcnt(0)
	s_barrier
	s_add_u32 s68, s98, 0x18000
	s_addc_u32 s69, s99, 0
	s_add_i32 s49, 0x4000, s57
	s_mov_b32 m0, s49
	s_nop 0
	global_load_lds_dwordx4 v198, s[68:69]
	s_add_i32 m0, s49, 0x400
	s_nop 0
	global_load_lds_dwordx4 v194, s[68:69]
	s_add_u32 s44, s100, 0x80
	s_addc_u32 s45, s101, 0
	s_add_i32 s49, s58, 0xc000
	s_add_i32 m0, s49, 0xc000
	s_nop 0
	global_load_lds_dwordx4 v196, s[44:45]
	s_add_i32 m0, s49, 0xc400
	s_nop 0
	global_load_lds_dwordx4 v192, s[44:45]
	v_exp_f32_e32 v144, v112
	ds_read_b128 v[32:35], v205 offset:32768
	ds_read_b128 v[36:39], v205 offset:40960
	s_waitcnt lgkmcnt(0)
	v_mfma_f32_32x32x16_bf16 v[48:63], v[32:35], v[160:163], 0
	ds_read_b128 v[132:135], v211 offset:32768
	ds_read_b128 v[136:139], v211 offset:40960
	ds_read_b128 v[140:143], v212 offset:32768
	v_exp_f32_e32 v145, v113
	v_exp_f32_e32 v146, v114
	v_exp_f32_e32 v147, v115
	ds_read_b128 v[112:115], v212 offset:40960
	v_mfma_f32_32x32x16_bf16 v[32:47], v[36:39], v[160:163], 0
	v_exp_f32_e32 v148, v116
	v_exp_f32_e32 v149, v117
	v_exp_f32_e32 v150, v118
	v_exp_f32_e32 v151, v119
	s_waitcnt lgkmcnt(0)
	v_mfma_f32_32x32x16_bf16 v[48:63], v[132:135], v[164:167], v[48:63]
	ds_read_b128 v[116:119], v213 offset:32768
	v_exp_f32_e32 v152, v120
	v_exp_f32_e32 v153, v121
	v_exp_f32_e32 v154, v122
	v_exp_f32_e32 v155, v123
	v_mfma_f32_32x32x16_bf16 v[32:47], v[136:139], v[164:167], v[32:47]
	ds_read_b128 v[120:123], v213 offset:40960
	v_exp_f32_e32 v156, v124
	v_exp_f32_e32 v157, v125
	v_exp_f32_e32 v158, v126
	v_exp_f32_e32 v159, v127
	v_mfma_f32_32x32x16_bf16 v[48:63], v[140:143], v[168:171], v[48:63]
	ds_read_b128 v[124:127], v236
	v_exp_f32_e32 v136, v96
	v_exp_f32_e32 v137, v97
	v_exp_f32_e32 v138, v98
	v_exp_f32_e32 v139, v99
	v_mfma_f32_32x32x16_bf16 v[32:47], v[112:115], v[168:171], v[32:47]
	ds_read_b128 v[96:99], v236 offset:4096
	v_exp_f32_e32 v140, v100
	v_exp_f32_e32 v141, v101
	v_exp_f32_e32 v142, v102
	v_exp_f32_e32 v143, v103
	s_waitcnt lgkmcnt(0)
	v_mfma_f32_32x32x16_bf16 v[48:63], v[116:119], v[172:175], v[48:63]
	ds_read_b128 v[100:103], v236 offset:8192
	v_exp_f32_e32 v178, v104
	v_exp_f32_e32 v179, v105
	v_exp_f32_e32 v180, v106
	v_exp_f32_e32 v181, v107
	v_mfma_f32_32x32x16_bf16 v[32:47], v[120:123], v[172:175], v[32:47]
	ds_read_b128 v[104:107], v236 offset:12288
	v_exp_f32_e32 v182, v108
	v_exp_f32_e32 v183, v109
	v_exp_f32_e32 v184, v110
	v_exp_f32_e32 v185, v111
	v_cvt_pk_bf16_f32 v108, v144, v145
	v_cvt_pk_bf16_f32 v109, v146, v147
	v_cvt_pk_bf16_f32 v110, v148, v149
	v_cvt_pk_bf16_f32 v111, v150, v151
	s_nop 1
	v_mfma_f32_32x32x16_bf16 v[80:95], v[124:127], v[108:111], v[80:95]
	ds_read_b128 v[112:115], v237
	v_cvt_pk_bf16_f32 v116, v152, v153
	v_cvt_pk_bf16_f32 v117, v154, v155
	v_cvt_pk_bf16_f32 v118, v156, v157
	v_cvt_pk_bf16_f32 v119, v158, v159
	v_mfma_f32_32x32x16_bf16 v[64:79], v[96:99], v[108:111], v[64:79]
	ds_read_b128 v[120:123], v237 offset:4096
	v_pk_add_f32 v[126:127], v[150:151], v[146:147]
	v_pk_add_f32 v[124:125], v[148:149], v[144:145]
	s_waitcnt lgkmcnt(0)
	v_mfma_f32_32x32x16_bf16 v[16:31], v[100:103], v[108:111], v[16:31]
	ds_read_b128 v[132:135], v237 offset:8192
	v_add_f32_e64 v98, v154, v126
	v_add_f32_e64 v99, v155, v127
	v_add_f32_e64 v96, v152, v124
	v_add_f32_e64 v97, v153, v125
	v_pk_add_f32 v[98:99], v[158:159], v[98:99]
	v_pk_add_f32 v[96:97], v[156:157], v[96:97]
	v_mfma_f32_32x32x16_bf16 v[0:15], v[104:107], v[108:111], v[0:15]
	ds_read_b128 v[100:103], v237 offset:12288
	v_mfma_f32_32x32x16_bf16 v[80:95], v[112:115], v[116:119], v[80:95]
	ds_read_b128 v[104:107], v238
	v_cvt_pk_bf16_f32 v108, v136, v137
	v_cvt_pk_bf16_f32 v109, v138, v139
	v_cvt_pk_bf16_f32 v110, v140, v141
	v_cvt_pk_bf16_f32 v111, v142, v143
	v_mfma_f32_32x32x16_bf16 v[64:79], v[120:123], v[116:119], v[64:79]
	ds_read_b128 v[112:115], v238 offset:4096
	v_add_f32_e64 v98, v138, v98
	v_add_f32_e64 v99, v139, v99
	v_add_f32_e64 v96, v136, v96
	v_add_f32_e64 v97, v137, v97
	v_pk_add_f32 v[98:99], v[142:143], v[98:99]
	v_pk_add_f32 v[96:97], v[140:141], v[96:97]
	s_waitcnt lgkmcnt(0)
	v_mfma_f32_32x32x16_bf16 v[16:31], v[132:135], v[116:119], v[16:31]
	ds_read_b128 v[120:123], v238 offset:8192
	v_add_f32_e64 v98, v180, v98
	v_add_f32_e64 v99, v181, v99
	v_add_f32_e64 v96, v178, v96
	v_add_f32_e64 v97, v179, v97
	v_pk_add_f32 v[98:99], v[184:185], v[98:99]
	v_pk_add_f32 v[96:97], v[182:183], v[96:97]
	v_mfma_f32_32x32x16_bf16 v[0:15], v[100:103], v[116:119], v[0:15]
	ds_read_b128 v[124:127], v238 offset:12288
	v_mfma_f32_32x32x16_bf16 v[80:95], v[104:107], v[108:111], v[80:95]
	ds_read_b128 v[100:103], v239
	v_cvt_pk_bf16_f32 v116, v178, v179
	v_cvt_pk_bf16_f32 v117, v180, v181
	v_cvt_pk_bf16_f32 v118, v182, v183
	v_cvt_pk_bf16_f32 v119, v184, v185
	v_mfma_f32_32x32x16_bf16 v[64:79], v[112:115], v[108:111], v[64:79]
	ds_read_b128 v[104:107], v239 offset:4096
	s_waitcnt lgkmcnt(0)
	v_mfma_f32_32x32x16_bf16 v[16:31], v[120:123], v[108:111], v[16:31]
	ds_read_b128 v[112:115], v239 offset:8192
	v_mfma_f32_32x32x16_bf16 v[0:15], v[124:127], v[108:111], v[0:15]
	ds_read_b128 v[120:123], v239 offset:12288
	v_mfma_f32_32x32x16_bf16 v[80:95], v[100:103], v[116:119], v[80:95]
	v_mfma_f32_32x32x16_bf16 v[64:79], v[104:107], v[116:119], v[64:79]
	s_waitcnt lgkmcnt(0)
	v_mfma_f32_32x32x16_bf16 v[16:31], v[112:115], v[116:119], v[16:31]
	v_mfma_f32_32x32x16_bf16 v[0:15], v[120:123], v[116:119], v[0:15]
	s_waitcnt vmcnt(4) lgkmcnt(0)
	v_add_f32_e32 v100, v128, v129
	v_add_f32_e32 v101, v130, v131
	v_add_f32_e32 v100, v100, v101
	v_add_f32_e32 v96, v96, v97
	v_add_f32_e32 v97, v98, v99
	s_barrier
	v_add_f32_e32 v100, v177, v100
	v_add_f32_e32 v96, v96, v97
	v_add_f32_e32 v177, v100, v96
	s_add_u32 s98, s98, 0x30000
	s_addc_u32 s99, s99, 0
	s_add_u32 s100, s100, 0x100
	s_addc_u32 s101, s101, 0
	s_add_i32 s46, s58, 0x8000
	s_mov_b32 m0, s46
	s_nop 0
	global_load_lds_dwordx4 v198, s[98:99]
	s_add_i32 m0, s46, 0x400
	s_nop 0
	global_load_lds_dwordx4 v194, s[98:99]
	s_add_i32 s48, s58, 0
	s_add_i32 m0, s48, 0xc000
	s_nop 0
	global_load_lds_dwordx4 v196, s[100:101]
	s_add_i32 m0, s48, 0xc400
	s_nop 0
	global_load_lds_dwordx4 v192, s[100:101]
	ds_read_b128 v[96:99], v205
	ds_read_b128 v[100:103], v205 offset:8192
	s_waitcnt lgkmcnt(0)
	v_mfma_f32_32x32x16_bf16 v[112:127], v[96:99], v[160:163], 0
	ds_read_b128 v[128:131], v211
	ds_read_b128 v[132:135], v211 offset:8192
	ds_read_b128 v[136:139], v212
	v_exp_f32_e32 v140, v48
	v_exp_f32_e32 v141, v49
	v_exp_f32_e32 v142, v50
	v_exp_f32_e32 v143, v51
	ds_read_b128 v[48:51], v212 offset:8192
	v_mfma_f32_32x32x16_bf16 v[96:111], v[100:103], v[160:163], 0
	v_exp_f32_e32 v144, v52
	v_exp_f32_e32 v145, v53
	v_exp_f32_e32 v146, v54
	v_exp_f32_e32 v147, v55
	s_waitcnt lgkmcnt(0)
	v_mfma_f32_32x32x16_bf16 v[112:127], v[128:131], v[164:167], v[112:127]
	ds_read_b128 v[52:55], v213
	v_exp_f32_e32 v148, v56
	v_exp_f32_e32 v149, v57
	v_exp_f32_e32 v150, v58
	v_exp_f32_e32 v151, v59
	v_mfma_f32_32x32x16_bf16 v[96:111], v[132:135], v[164:167], v[96:111]
	ds_read_b128 v[56:59], v213 offset:8192
	v_exp_f32_e32 v128, v60
	v_exp_f32_e32 v129, v61
	v_exp_f32_e32 v130, v62
	v_exp_f32_e32 v131, v63
	v_mfma_f32_32x32x16_bf16 v[112:127], v[136:139], v[168:171], v[112:127]
	ds_read_b128 v[60:63], v236 offset:16384
	v_exp_f32_e32 v132, v32
	v_exp_f32_e32 v133, v33
	v_exp_f32_e32 v134, v34
	v_exp_f32_e32 v135, v35
	v_mfma_f32_32x32x16_bf16 v[96:111], v[48:51], v[168:171], v[96:111]
	ds_read_b128 v[32:35], v236 offset:20480
	v_exp_f32_e32 v136, v36
	v_exp_f32_e32 v137, v37
	v_exp_f32_e32 v138, v38
	v_exp_f32_e32 v139, v39
	s_waitcnt lgkmcnt(0)
	v_mfma_f32_32x32x16_bf16 v[112:127], v[52:55], v[172:175], v[112:127]
	ds_read_b128 v[36:39], v236 offset:24576
	v_exp_f32_e32 v152, v40
	v_exp_f32_e32 v153, v41
	v_exp_f32_e32 v154, v42
	v_exp_f32_e32 v155, v43
	v_mfma_f32_32x32x16_bf16 v[96:111], v[56:59], v[172:175], v[96:111]
	ds_read_b128 v[40:43], v236 offset:28672
	v_exp_f32_e32 v156, v44
	v_exp_f32_e32 v157, v45
	v_exp_f32_e32 v158, v46
	v_exp_f32_e32 v159, v47
	v_cvt_pk_bf16_f32 v44, v140, v141
	v_cvt_pk_bf16_f32 v45, v142, v143
	v_cvt_pk_bf16_f32 v46, v144, v145
	v_cvt_pk_bf16_f32 v47, v146, v147
	s_nop 1
	v_mfma_f32_32x32x16_bf16 v[80:95], v[60:63], v[44:47], v[80:95]
	ds_read_b128 v[48:51], v237 offset:16384
	v_cvt_pk_bf16_f32 v52, v148, v149
	v_cvt_pk_bf16_f32 v53, v150, v151
	v_cvt_pk_bf16_f32 v54, v128, v129
	v_cvt_pk_bf16_f32 v55, v130, v131
	v_mfma_f32_32x32x16_bf16 v[64:79], v[32:35], v[44:47], v[64:79]
	ds_read_b128 v[56:59], v237 offset:20480
	v_pk_add_f32 v[62:63], v[146:147], v[142:143]
	v_pk_add_f32 v[60:61], v[144:145], v[140:141]
	s_waitcnt lgkmcnt(0)
	v_mfma_f32_32x32x16_bf16 v[16:31], v[36:39], v[44:47], v[16:31]
	ds_read_b128 v[32:35], v237 offset:24576
	v_add_f32_e64 v62, v150, v62
	v_add_f32_e64 v63, v151, v63
	v_add_f32_e64 v60, v148, v60
	v_add_f32_e64 v61, v149, v61
	v_pk_add_f32 v[62:63], v[130:131], v[62:63]
	v_pk_add_f32 v[60:61], v[128:129], v[60:61]
	v_mfma_f32_32x32x16_bf16 v[0:15], v[40:43], v[44:47], v[0:15]
	ds_read_b128 v[36:39], v237 offset:28672
	v_mfma_f32_32x32x16_bf16 v[80:95], v[48:51], v[52:55], v[80:95]
	ds_read_b128 v[40:43], v238 offset:16384
	v_cvt_pk_bf16_f32 v44, v132, v133
	v_cvt_pk_bf16_f32 v45, v134, v135
	v_cvt_pk_bf16_f32 v46, v136, v137
	v_cvt_pk_bf16_f32 v47, v138, v139
	v_mfma_f32_32x32x16_bf16 v[64:79], v[56:59], v[52:55], v[64:79]
	ds_read_b128 v[48:51], v238 offset:20480
	v_add_f32_e64 v62, v134, v62
	v_add_f32_e64 v63, v135, v63
	v_add_f32_e64 v60, v132, v60
	v_add_f32_e64 v61, v133, v61
	v_pk_add_f32 v[62:63], v[138:139], v[62:63]
	v_pk_add_f32 v[60:61], v[136:137], v[60:61]
	s_waitcnt lgkmcnt(0)
	v_mfma_f32_32x32x16_bf16 v[16:31], v[32:35], v[52:55], v[16:31]
	ds_read_b128 v[56:59], v238 offset:24576
	v_add_f32_e64 v62, v154, v62
	v_add_f32_e64 v63, v155, v63
	v_add_f32_e64 v60, v152, v60
	v_add_f32_e64 v61, v153, v61
	v_pk_add_f32 v[130:131], v[158:159], v[62:63]
	v_pk_add_f32 v[128:129], v[156:157], v[60:61]
	v_mfma_f32_32x32x16_bf16 v[0:15], v[36:39], v[52:55], v[0:15]
	ds_read_b128 v[32:35], v238 offset:28672
	v_mfma_f32_32x32x16_bf16 v[80:95], v[40:43], v[44:47], v[80:95]
	ds_read_b128 v[36:39], v239 offset:16384
	v_cvt_pk_bf16_f32 v52, v152, v153
	v_cvt_pk_bf16_f32 v53, v154, v155
	v_cvt_pk_bf16_f32 v54, v156, v157
	v_cvt_pk_bf16_f32 v55, v158, v159
	v_mfma_f32_32x32x16_bf16 v[64:79], v[48:51], v[44:47], v[64:79]
	ds_read_b128 v[40:43], v239 offset:20480
	s_waitcnt lgkmcnt(0)
	v_mfma_f32_32x32x16_bf16 v[16:31], v[56:59], v[44:47], v[16:31]
	ds_read_b128 v[48:51], v239 offset:24576
	v_mfma_f32_32x32x16_bf16 v[0:15], v[32:35], v[44:47], v[0:15]
	ds_read_b128 v[56:59], v239 offset:28672
	v_mfma_f32_32x32x16_bf16 v[80:95], v[36:39], v[52:55], v[80:95]
	v_mfma_f32_32x32x16_bf16 v[64:79], v[40:43], v[52:55], v[64:79]
	s_waitcnt lgkmcnt(0)
	v_mfma_f32_32x32x16_bf16 v[16:31], v[48:51], v[52:55], v[16:31]
	v_mfma_f32_32x32x16_bf16 v[0:15], v[56:59], v[52:55], v[0:15]
	s_waitcnt vmcnt(4) lgkmcnt(0)
	s_barrier
	s_add_u32 s68, s98, 0x18000
	s_addc_u32 s69, s99, 0
	s_add_i32 s49, 0, s57
	s_mov_b32 m0, s49
	s_nop 0
	global_load_lds_dwordx4 v198, s[68:69]
	s_add_i32 m0, s49, 0x400
	s_nop 0
	global_load_lds_dwordx4 v194, s[68:69]
	s_add_u32 s44, s100, 0x80
	s_addc_u32 s45, s101, 0
	s_add_i32 s49, s58, 0x4000
	s_add_i32 m0, s49, 0xc000
	s_nop 0
	global_load_lds_dwordx4 v196, s[44:45]
	s_add_i32 m0, s49, 0xc400
	s_nop 0
	global_load_lds_dwordx4 v192, s[44:45]
	v_exp_f32_e32 v144, v112
	ds_read_b128 v[32:35], v205 offset:16384
	ds_read_b128 v[36:39], v205 offset:24576
	s_waitcnt lgkmcnt(0)
	v_mfma_f32_32x32x16_bf16 v[48:63], v[32:35], v[160:163], 0
	ds_read_b128 v[132:135], v211 offset:16384
	ds_read_b128 v[136:139], v211 offset:24576
	ds_read_b128 v[140:143], v212 offset:16384
	v_exp_f32_e32 v145, v113
	v_exp_f32_e32 v146, v114
	v_exp_f32_e32 v147, v115
	ds_read_b128 v[112:115], v212 offset:24576
	v_mfma_f32_32x32x16_bf16 v[32:47], v[36:39], v[160:163], 0
	v_exp_f32_e32 v148, v116
	v_exp_f32_e32 v149, v117
	v_exp_f32_e32 v150, v118
	v_exp_f32_e32 v151, v119
	s_waitcnt lgkmcnt(0)
	v_mfma_f32_32x32x16_bf16 v[48:63], v[132:135], v[164:167], v[48:63]
	ds_read_b128 v[116:119], v213 offset:16384
	v_exp_f32_e32 v152, v120
	v_exp_f32_e32 v153, v121
	v_exp_f32_e32 v154, v122
	v_exp_f32_e32 v155, v123
	v_mfma_f32_32x32x16_bf16 v[32:47], v[136:139], v[164:167], v[32:47]
	ds_read_b128 v[120:123], v213 offset:24576
	v_exp_f32_e32 v156, v124
	v_exp_f32_e32 v157, v125
	v_exp_f32_e32 v158, v126
	v_exp_f32_e32 v159, v127
	v_mfma_f32_32x32x16_bf16 v[48:63], v[140:143], v[168:171], v[48:63]
	ds_read_b128 v[124:127], v236 offset:32768
	v_exp_f32_e32 v136, v96
	v_exp_f32_e32 v137, v97
	v_exp_f32_e32 v138, v98
	v_exp_f32_e32 v139, v99
	v_mfma_f32_32x32x16_bf16 v[32:47], v[112:115], v[168:171], v[32:47]
	ds_read_b128 v[96:99], v236 offset:36864
	v_exp_f32_e32 v140, v100
	v_exp_f32_e32 v141, v101
	v_exp_f32_e32 v142, v102
	v_exp_f32_e32 v143, v103
	s_waitcnt lgkmcnt(0)
	v_mfma_f32_32x32x16_bf16 v[48:63], v[116:119], v[172:175], v[48:63]
	ds_read_b128 v[100:103], v236 offset:40960
	v_exp_f32_e32 v178, v104
	v_exp_f32_e32 v179, v105
	v_exp_f32_e32 v180, v106
	v_exp_f32_e32 v181, v107
	v_mfma_f32_32x32x16_bf16 v[32:47], v[120:123], v[172:175], v[32:47]
	ds_read_b128 v[104:107], v236 offset:45056
	v_exp_f32_e32 v182, v108
	v_exp_f32_e32 v183, v109
	v_exp_f32_e32 v184, v110
	v_exp_f32_e32 v185, v111
	v_cvt_pk_bf16_f32 v108, v144, v145
	v_cvt_pk_bf16_f32 v109, v146, v147
	v_cvt_pk_bf16_f32 v110, v148, v149
	v_cvt_pk_bf16_f32 v111, v150, v151
	s_nop 1
	v_mfma_f32_32x32x16_bf16 v[80:95], v[124:127], v[108:111], v[80:95]
	ds_read_b128 v[112:115], v237 offset:32768
	v_cvt_pk_bf16_f32 v116, v152, v153
	v_cvt_pk_bf16_f32 v117, v154, v155
	v_cvt_pk_bf16_f32 v118, v156, v157
	v_cvt_pk_bf16_f32 v119, v158, v159
	v_mfma_f32_32x32x16_bf16 v[64:79], v[96:99], v[108:111], v[64:79]
	ds_read_b128 v[120:123], v237 offset:36864
	v_pk_add_f32 v[126:127], v[150:151], v[146:147]
	v_pk_add_f32 v[124:125], v[148:149], v[144:145]
	s_waitcnt lgkmcnt(0)
	v_mfma_f32_32x32x16_bf16 v[16:31], v[100:103], v[108:111], v[16:31]
	ds_read_b128 v[132:135], v237 offset:40960
	v_add_f32_e64 v98, v154, v126
	v_add_f32_e64 v99, v155, v127
	v_add_f32_e64 v96, v152, v124
	v_add_f32_e64 v97, v153, v125
	v_pk_add_f32 v[98:99], v[158:159], v[98:99]
	v_pk_add_f32 v[96:97], v[156:157], v[96:97]
	v_mfma_f32_32x32x16_bf16 v[0:15], v[104:107], v[108:111], v[0:15]
	ds_read_b128 v[100:103], v237 offset:45056
	v_mfma_f32_32x32x16_bf16 v[80:95], v[112:115], v[116:119], v[80:95]
	ds_read_b128 v[104:107], v238 offset:32768
	v_cvt_pk_bf16_f32 v108, v136, v137
	v_cvt_pk_bf16_f32 v109, v138, v139
	v_cvt_pk_bf16_f32 v110, v140, v141
	v_cvt_pk_bf16_f32 v111, v142, v143
	v_mfma_f32_32x32x16_bf16 v[64:79], v[120:123], v[116:119], v[64:79]
	ds_read_b128 v[112:115], v238 offset:36864
	v_add_f32_e64 v98, v138, v98
	v_add_f32_e64 v99, v139, v99
	v_add_f32_e64 v96, v136, v96
	v_add_f32_e64 v97, v137, v97
	v_pk_add_f32 v[98:99], v[142:143], v[98:99]
	v_pk_add_f32 v[96:97], v[140:141], v[96:97]
	s_waitcnt lgkmcnt(0)
	v_mfma_f32_32x32x16_bf16 v[16:31], v[132:135], v[116:119], v[16:31]
	ds_read_b128 v[120:123], v238 offset:40960
	v_add_f32_e64 v98, v180, v98
	v_add_f32_e64 v99, v181, v99
	v_add_f32_e64 v96, v178, v96
	v_add_f32_e64 v97, v179, v97
	v_pk_add_f32 v[98:99], v[184:185], v[98:99]
	v_pk_add_f32 v[96:97], v[182:183], v[96:97]
	v_mfma_f32_32x32x16_bf16 v[0:15], v[100:103], v[116:119], v[0:15]
	ds_read_b128 v[124:127], v238 offset:45056
	v_mfma_f32_32x32x16_bf16 v[80:95], v[104:107], v[108:111], v[80:95]
	ds_read_b128 v[100:103], v239 offset:32768
	v_cvt_pk_bf16_f32 v116, v178, v179
	v_cvt_pk_bf16_f32 v117, v180, v181
	v_cvt_pk_bf16_f32 v118, v182, v183
	v_cvt_pk_bf16_f32 v119, v184, v185
	v_mfma_f32_32x32x16_bf16 v[64:79], v[112:115], v[108:111], v[64:79]
	ds_read_b128 v[104:107], v239 offset:36864
	s_waitcnt lgkmcnt(0)
	v_mfma_f32_32x32x16_bf16 v[16:31], v[120:123], v[108:111], v[16:31]
	ds_read_b128 v[112:115], v239 offset:40960
	v_mfma_f32_32x32x16_bf16 v[0:15], v[124:127], v[108:111], v[0:15]
	ds_read_b128 v[120:123], v239 offset:45056
	v_mfma_f32_32x32x16_bf16 v[80:95], v[100:103], v[116:119], v[80:95]
	v_mfma_f32_32x32x16_bf16 v[64:79], v[104:107], v[116:119], v[64:79]
	s_waitcnt lgkmcnt(0)
	v_mfma_f32_32x32x16_bf16 v[16:31], v[112:115], v[116:119], v[16:31]
	v_mfma_f32_32x32x16_bf16 v[0:15], v[120:123], v[116:119], v[0:15]
	s_waitcnt vmcnt(4) lgkmcnt(0)
	v_add_f32_e32 v100, v128, v129
	v_add_f32_e32 v101, v130, v131
	v_add_f32_e32 v100, v100, v101
	v_add_f32_e32 v96, v96, v97
	v_add_f32_e32 v97, v98, v99
	s_barrier
	v_add_f32_e32 v100, v177, v100
	v_add_f32_e32 v96, v96, v97
	v_add_f32_e32 v177, v100, v96
	s_add_u32 s98, s98, 0x30000
	s_addc_u32 s99, s99, 0
	s_add_u32 s100, s100, 0x100
	s_addc_u32 s101, s101, 0
	s_add_i32 s46, s58, 0x4000
	s_mov_b32 m0, s46
	s_nop 0
	global_load_lds_dwordx4 v198, s[98:99]
	s_add_i32 m0, s46, 0x400
	s_nop 0
	global_load_lds_dwordx4 v194, s[98:99]
	s_add_i32 s48, s58, 0x8000
	s_add_i32 m0, s48, 0xc000
	s_nop 0
	global_load_lds_dwordx4 v196, s[100:101]
	s_add_i32 m0, s48, 0xc400
	s_nop 0
	global_load_lds_dwordx4 v192, s[100:101]
	ds_read_b128 v[96:99], v205 offset:32768
	ds_read_b128 v[100:103], v205 offset:40960
	s_waitcnt lgkmcnt(0)
	v_mfma_f32_32x32x16_bf16 v[112:127], v[96:99], v[160:163], 0
	ds_read_b128 v[128:131], v211 offset:32768
	ds_read_b128 v[132:135], v211 offset:40960
	ds_read_b128 v[136:139], v212 offset:32768
	v_exp_f32_e32 v140, v48
	v_exp_f32_e32 v141, v49
	v_exp_f32_e32 v142, v50
	v_exp_f32_e32 v143, v51
	ds_read_b128 v[48:51], v212 offset:40960
	v_mfma_f32_32x32x16_bf16 v[96:111], v[100:103], v[160:163], 0
	v_exp_f32_e32 v144, v52
	v_exp_f32_e32 v145, v53
	v_exp_f32_e32 v146, v54
	v_exp_f32_e32 v147, v55
	s_waitcnt lgkmcnt(0)
	v_mfma_f32_32x32x16_bf16 v[112:127], v[128:131], v[164:167], v[112:127]
	ds_read_b128 v[52:55], v213 offset:32768
	v_exp_f32_e32 v148, v56
	v_exp_f32_e32 v149, v57
	v_exp_f32_e32 v150, v58
	v_exp_f32_e32 v151, v59
	v_mfma_f32_32x32x16_bf16 v[96:111], v[132:135], v[164:167], v[96:111]
	ds_read_b128 v[56:59], v213 offset:40960
	v_exp_f32_e32 v128, v60
	v_exp_f32_e32 v129, v61
	v_exp_f32_e32 v130, v62
	v_exp_f32_e32 v131, v63
	v_mfma_f32_32x32x16_bf16 v[112:127], v[136:139], v[168:171], v[112:127]
	ds_read_b128 v[60:63], v206 offset:49152
	v_exp_f32_e32 v132, v32
	v_exp_f32_e32 v133, v33
	v_exp_f32_e32 v134, v34
	v_exp_f32_e32 v135, v35
	v_mfma_f32_32x32x16_bf16 v[96:111], v[48:51], v[168:171], v[96:111]
	ds_read_b128 v[32:35], v206 offset:53248
	v_exp_f32_e32 v136, v36
	v_exp_f32_e32 v137, v37
	v_exp_f32_e32 v138, v38
	v_exp_f32_e32 v139, v39
	s_waitcnt lgkmcnt(0)
	v_mfma_f32_32x32x16_bf16 v[112:127], v[52:55], v[172:175], v[112:127]
	ds_read_b128 v[36:39], v206 offset:57344
	v_exp_f32_e32 v152, v40
	v_exp_f32_e32 v153, v41
	v_exp_f32_e32 v154, v42
	v_exp_f32_e32 v155, v43
	v_mfma_f32_32x32x16_bf16 v[96:111], v[56:59], v[172:175], v[96:111]
	ds_read_b128 v[40:43], v206 offset:61440
	v_exp_f32_e32 v156, v44
	v_exp_f32_e32 v157, v45
	v_exp_f32_e32 v158, v46
	v_exp_f32_e32 v159, v47
	v_cvt_pk_bf16_f32 v44, v140, v141
	v_cvt_pk_bf16_f32 v45, v142, v143
	v_cvt_pk_bf16_f32 v46, v144, v145
	v_cvt_pk_bf16_f32 v47, v146, v147
	s_nop 1
	v_mfma_f32_32x32x16_bf16 v[80:95], v[60:63], v[44:47], v[80:95]
	ds_read_b128 v[48:51], v207 offset:49152
	v_cvt_pk_bf16_f32 v52, v148, v149
	v_cvt_pk_bf16_f32 v53, v150, v151
	v_cvt_pk_bf16_f32 v54, v128, v129
	v_cvt_pk_bf16_f32 v55, v130, v131
	v_mfma_f32_32x32x16_bf16 v[64:79], v[32:35], v[44:47], v[64:79]
	ds_read_b128 v[56:59], v207 offset:53248
	v_pk_add_f32 v[62:63], v[146:147], v[142:143]
	v_pk_add_f32 v[60:61], v[144:145], v[140:141]
	s_waitcnt lgkmcnt(0)
	v_mfma_f32_32x32x16_bf16 v[16:31], v[36:39], v[44:47], v[16:31]
	ds_read_b128 v[32:35], v207 offset:57344
	v_add_f32_e64 v62, v150, v62
	v_add_f32_e64 v63, v151, v63
	v_add_f32_e64 v60, v148, v60
	v_add_f32_e64 v61, v149, v61
	v_pk_add_f32 v[62:63], v[130:131], v[62:63]
	v_pk_add_f32 v[60:61], v[128:129], v[60:61]
	v_mfma_f32_32x32x16_bf16 v[0:15], v[40:43], v[44:47], v[0:15]
	ds_read_b128 v[36:39], v207 offset:61440
	v_mfma_f32_32x32x16_bf16 v[80:95], v[48:51], v[52:55], v[80:95]
	ds_read_b128 v[40:43], v208 offset:49152
	v_cvt_pk_bf16_f32 v44, v132, v133
	v_cvt_pk_bf16_f32 v45, v134, v135
	v_cvt_pk_bf16_f32 v46, v136, v137
	v_cvt_pk_bf16_f32 v47, v138, v139
	v_mfma_f32_32x32x16_bf16 v[64:79], v[56:59], v[52:55], v[64:79]
	ds_read_b128 v[48:51], v208 offset:53248
	v_add_f32_e64 v62, v134, v62
	v_add_f32_e64 v63, v135, v63
	v_add_f32_e64 v60, v132, v60
	v_add_f32_e64 v61, v133, v61
	v_pk_add_f32 v[62:63], v[138:139], v[62:63]
	v_pk_add_f32 v[60:61], v[136:137], v[60:61]
	s_waitcnt lgkmcnt(0)
	v_mfma_f32_32x32x16_bf16 v[16:31], v[32:35], v[52:55], v[16:31]
	ds_read_b128 v[56:59], v208 offset:57344
	v_add_f32_e64 v62, v154, v62
	v_add_f32_e64 v63, v155, v63
	v_add_f32_e64 v60, v152, v60
	v_add_f32_e64 v61, v153, v61
	v_pk_add_f32 v[130:131], v[158:159], v[62:63]
	v_pk_add_f32 v[128:129], v[156:157], v[60:61]
	v_mfma_f32_32x32x16_bf16 v[0:15], v[36:39], v[52:55], v[0:15]
	ds_read_b128 v[32:35], v208 offset:61440
	v_mfma_f32_32x32x16_bf16 v[80:95], v[40:43], v[44:47], v[80:95]
	ds_read_b128 v[36:39], v209 offset:49152
	v_cvt_pk_bf16_f32 v52, v152, v153
	v_cvt_pk_bf16_f32 v53, v154, v155
	v_cvt_pk_bf16_f32 v54, v156, v157
	v_cvt_pk_bf16_f32 v55, v158, v159
	v_mfma_f32_32x32x16_bf16 v[64:79], v[48:51], v[44:47], v[64:79]
	ds_read_b128 v[40:43], v209 offset:53248
	s_waitcnt lgkmcnt(0)
	v_mfma_f32_32x32x16_bf16 v[16:31], v[56:59], v[44:47], v[16:31]
	ds_read_b128 v[48:51], v209 offset:57344
	v_mfma_f32_32x32x16_bf16 v[0:15], v[32:35], v[44:47], v[0:15]
	ds_read_b128 v[56:59], v209 offset:61440
	v_mfma_f32_32x32x16_bf16 v[80:95], v[36:39], v[52:55], v[80:95]
	v_mfma_f32_32x32x16_bf16 v[64:79], v[40:43], v[52:55], v[64:79]
	s_waitcnt lgkmcnt(0)
	v_mfma_f32_32x32x16_bf16 v[16:31], v[48:51], v[52:55], v[16:31]
	v_mfma_f32_32x32x16_bf16 v[0:15], v[56:59], v[52:55], v[0:15]
	s_waitcnt vmcnt(4) lgkmcnt(0)
	s_barrier
	s_add_u32 s68, s98, 0x18000
	s_addc_u32 s69, s99, 0
	s_add_i32 s49, 0x8000, s57
	s_mov_b32 m0, s49
	s_nop 0
	global_load_lds_dwordx4 v198, s[68:69]
	s_add_i32 m0, s49, 0x400
	s_nop 0
	global_load_lds_dwordx4 v194, s[68:69]
	s_add_u32 s44, s100, 0x80
	s_addc_u32 s45, s101, 0
	s_add_i32 s49, s58, 0xc000
	s_add_i32 m0, s49, 0xc000
	s_nop 0
	global_load_lds_dwordx4 v196, s[44:45]
	s_add_i32 m0, s49, 0xc400
	s_nop 0
	global_load_lds_dwordx4 v192, s[44:45]
	v_exp_f32_e32 v144, v112
	ds_read_b128 v[32:35], v205
	ds_read_b128 v[36:39], v205 offset:8192
	s_waitcnt lgkmcnt(0)
	v_mfma_f32_32x32x16_bf16 v[48:63], v[32:35], v[160:163], 0
	ds_read_b128 v[132:135], v211
	ds_read_b128 v[136:139], v211 offset:8192
	ds_read_b128 v[140:143], v212
	v_exp_f32_e32 v145, v113
	v_exp_f32_e32 v146, v114
	v_exp_f32_e32 v147, v115
	ds_read_b128 v[112:115], v212 offset:8192
	v_mfma_f32_32x32x16_bf16 v[32:47], v[36:39], v[160:163], 0
	v_exp_f32_e32 v148, v116
	v_exp_f32_e32 v149, v117
	v_exp_f32_e32 v150, v118
	v_exp_f32_e32 v151, v119
	s_waitcnt lgkmcnt(0)
	v_mfma_f32_32x32x16_bf16 v[48:63], v[132:135], v[164:167], v[48:63]
	ds_read_b128 v[116:119], v213
	v_exp_f32_e32 v152, v120
	v_exp_f32_e32 v153, v121
	v_exp_f32_e32 v154, v122
	v_exp_f32_e32 v155, v123
	v_mfma_f32_32x32x16_bf16 v[32:47], v[136:139], v[164:167], v[32:47]
	ds_read_b128 v[120:123], v213 offset:8192
	v_exp_f32_e32 v156, v124
	v_exp_f32_e32 v157, v125
	v_exp_f32_e32 v158, v126
	v_exp_f32_e32 v159, v127
	v_mfma_f32_32x32x16_bf16 v[48:63], v[140:143], v[168:171], v[48:63]
	ds_read_b128 v[124:127], v236
	v_exp_f32_e32 v136, v96
	v_exp_f32_e32 v137, v97
	v_exp_f32_e32 v138, v98
	v_exp_f32_e32 v139, v99
	v_mfma_f32_32x32x16_bf16 v[32:47], v[112:115], v[168:171], v[32:47]
	ds_read_b128 v[96:99], v236 offset:4096
	v_exp_f32_e32 v140, v100
	v_exp_f32_e32 v141, v101
	v_exp_f32_e32 v142, v102
	v_exp_f32_e32 v143, v103
	s_waitcnt lgkmcnt(0)
	v_mfma_f32_32x32x16_bf16 v[48:63], v[116:119], v[172:175], v[48:63]
	ds_read_b128 v[100:103], v236 offset:8192
	v_exp_f32_e32 v178, v104
	v_exp_f32_e32 v179, v105
	v_exp_f32_e32 v180, v106
	v_exp_f32_e32 v181, v107
	v_mfma_f32_32x32x16_bf16 v[32:47], v[120:123], v[172:175], v[32:47]
	ds_read_b128 v[104:107], v236 offset:12288
	v_exp_f32_e32 v182, v108
	v_exp_f32_e32 v183, v109
	v_exp_f32_e32 v184, v110
	v_exp_f32_e32 v185, v111
	v_cvt_pk_bf16_f32 v108, v144, v145
	v_cvt_pk_bf16_f32 v109, v146, v147
	v_cvt_pk_bf16_f32 v110, v148, v149
	v_cvt_pk_bf16_f32 v111, v150, v151
	s_nop 1
	v_mfma_f32_32x32x16_bf16 v[80:95], v[124:127], v[108:111], v[80:95]
	ds_read_b128 v[112:115], v237
	v_cvt_pk_bf16_f32 v116, v152, v153
	v_cvt_pk_bf16_f32 v117, v154, v155
	v_cvt_pk_bf16_f32 v118, v156, v157
	v_cvt_pk_bf16_f32 v119, v158, v159
	v_mfma_f32_32x32x16_bf16 v[64:79], v[96:99], v[108:111], v[64:79]
	ds_read_b128 v[120:123], v237 offset:4096
	v_pk_add_f32 v[126:127], v[150:151], v[146:147]
	v_pk_add_f32 v[124:125], v[148:149], v[144:145]
	s_waitcnt lgkmcnt(0)
	v_mfma_f32_32x32x16_bf16 v[16:31], v[100:103], v[108:111], v[16:31]
	ds_read_b128 v[132:135], v237 offset:8192
	v_add_f32_e64 v98, v154, v126
	v_add_f32_e64 v99, v155, v127
	v_add_f32_e64 v96, v152, v124
	v_add_f32_e64 v97, v153, v125
	v_pk_add_f32 v[98:99], v[158:159], v[98:99]
	v_pk_add_f32 v[96:97], v[156:157], v[96:97]
	v_mfma_f32_32x32x16_bf16 v[0:15], v[104:107], v[108:111], v[0:15]
	ds_read_b128 v[100:103], v237 offset:12288
	v_mfma_f32_32x32x16_bf16 v[80:95], v[112:115], v[116:119], v[80:95]
	ds_read_b128 v[104:107], v238
	v_cvt_pk_bf16_f32 v108, v136, v137
	v_cvt_pk_bf16_f32 v109, v138, v139
	v_cvt_pk_bf16_f32 v110, v140, v141
	v_cvt_pk_bf16_f32 v111, v142, v143
	v_mfma_f32_32x32x16_bf16 v[64:79], v[120:123], v[116:119], v[64:79]
	ds_read_b128 v[112:115], v238 offset:4096
	v_add_f32_e64 v98, v138, v98
	v_add_f32_e64 v99, v139, v99
	v_add_f32_e64 v96, v136, v96
	v_add_f32_e64 v97, v137, v97
	v_pk_add_f32 v[98:99], v[142:143], v[98:99]
	v_pk_add_f32 v[96:97], v[140:141], v[96:97]
	s_waitcnt lgkmcnt(0)
	v_mfma_f32_32x32x16_bf16 v[16:31], v[132:135], v[116:119], v[16:31]
	ds_read_b128 v[120:123], v238 offset:8192
	v_add_f32_e64 v98, v180, v98
	v_add_f32_e64 v99, v181, v99
	v_add_f32_e64 v96, v178, v96
	v_add_f32_e64 v97, v179, v97
	v_pk_add_f32 v[98:99], v[184:185], v[98:99]
	v_pk_add_f32 v[96:97], v[182:183], v[96:97]
	v_mfma_f32_32x32x16_bf16 v[0:15], v[100:103], v[116:119], v[0:15]
	ds_read_b128 v[124:127], v238 offset:12288
	v_mfma_f32_32x32x16_bf16 v[80:95], v[104:107], v[108:111], v[80:95]
	ds_read_b128 v[100:103], v239
	v_cvt_pk_bf16_f32 v116, v178, v179
	v_cvt_pk_bf16_f32 v117, v180, v181
	v_cvt_pk_bf16_f32 v118, v182, v183
	v_cvt_pk_bf16_f32 v119, v184, v185
	v_mfma_f32_32x32x16_bf16 v[64:79], v[112:115], v[108:111], v[64:79]
	ds_read_b128 v[104:107], v239 offset:4096
	s_waitcnt lgkmcnt(0)
	v_mfma_f32_32x32x16_bf16 v[16:31], v[120:123], v[108:111], v[16:31]
	ds_read_b128 v[112:115], v239 offset:8192
	v_mfma_f32_32x32x16_bf16 v[0:15], v[124:127], v[108:111], v[0:15]
	ds_read_b128 v[120:123], v239 offset:12288
	v_mfma_f32_32x32x16_bf16 v[80:95], v[100:103], v[116:119], v[80:95]
	v_mfma_f32_32x32x16_bf16 v[64:79], v[104:107], v[116:119], v[64:79]
	s_waitcnt lgkmcnt(0)
	v_mfma_f32_32x32x16_bf16 v[16:31], v[112:115], v[116:119], v[16:31]
	v_mfma_f32_32x32x16_bf16 v[0:15], v[120:123], v[116:119], v[0:15]
	s_waitcnt vmcnt(4) lgkmcnt(0)
	v_add_f32_e32 v100, v128, v129
	v_add_f32_e32 v101, v130, v131
	v_add_f32_e32 v100, v100, v101
	v_add_f32_e32 v96, v96, v97
	v_add_f32_e32 v97, v98, v99
	s_barrier
	v_add_f32_e32 v100, v177, v100
	v_add_f32_e32 v96, v96, v97
	v_add_f32_e32 v177, v100, v96
	s_add_u32 s98, s98, 0x30000
	s_addc_u32 s99, s99, 0
	s_add_u32 s100, s100, 0x100
	s_addc_u32 s101, s101, 0
	s_add_i32 s46, s58, 0
	s_mov_b32 m0, s46
	s_nop 0
	global_load_lds_dwordx4 v198, s[98:99]
	s_add_i32 m0, s46, 0x400
	s_nop 0
	global_load_lds_dwordx4 v194, s[98:99]
	s_add_i32 s48, s58, 0
	s_add_i32 m0, s48, 0xc000
	s_nop 0
	global_load_lds_dwordx4 v196, s[100:101]
	s_add_i32 m0, s48, 0xc400
	s_nop 0
	global_load_lds_dwordx4 v192, s[100:101]
	ds_read_b128 v[96:99], v205 offset:16384
	ds_read_b128 v[100:103], v205 offset:24576
	s_waitcnt lgkmcnt(0)
	v_mfma_f32_32x32x16_bf16 v[112:127], v[96:99], v[160:163], 0
	ds_read_b128 v[128:131], v211 offset:16384
	ds_read_b128 v[132:135], v211 offset:24576
	ds_read_b128 v[136:139], v212 offset:16384
	v_exp_f32_e32 v140, v48
	v_exp_f32_e32 v141, v49
	v_exp_f32_e32 v142, v50
	v_exp_f32_e32 v143, v51
	ds_read_b128 v[48:51], v212 offset:24576
	v_mfma_f32_32x32x16_bf16 v[96:111], v[100:103], v[160:163], 0
	v_exp_f32_e32 v144, v52
	v_exp_f32_e32 v145, v53
	v_exp_f32_e32 v146, v54
	v_exp_f32_e32 v147, v55
	s_waitcnt lgkmcnt(0)
	v_mfma_f32_32x32x16_bf16 v[112:127], v[128:131], v[164:167], v[112:127]
	ds_read_b128 v[52:55], v213 offset:16384
	v_exp_f32_e32 v148, v56
	v_exp_f32_e32 v149, v57
	v_exp_f32_e32 v150, v58
	v_exp_f32_e32 v151, v59
	v_mfma_f32_32x32x16_bf16 v[96:111], v[132:135], v[164:167], v[96:111]
	ds_read_b128 v[56:59], v213 offset:24576
	v_exp_f32_e32 v128, v60
	v_exp_f32_e32 v129, v61
	v_exp_f32_e32 v130, v62
	v_exp_f32_e32 v131, v63
	v_mfma_f32_32x32x16_bf16 v[112:127], v[136:139], v[168:171], v[112:127]
	ds_read_b128 v[60:63], v236 offset:16384
	v_exp_f32_e32 v132, v32
	v_exp_f32_e32 v133, v33
	v_exp_f32_e32 v134, v34
	v_exp_f32_e32 v135, v35
	v_mfma_f32_32x32x16_bf16 v[96:111], v[48:51], v[168:171], v[96:111]
	ds_read_b128 v[32:35], v236 offset:20480
	v_exp_f32_e32 v136, v36
	v_exp_f32_e32 v137, v37
	v_exp_f32_e32 v138, v38
	v_exp_f32_e32 v139, v39
	s_waitcnt lgkmcnt(0)
	v_mfma_f32_32x32x16_bf16 v[112:127], v[52:55], v[172:175], v[112:127]
	ds_read_b128 v[36:39], v236 offset:24576
	v_exp_f32_e32 v152, v40
	v_exp_f32_e32 v153, v41
	v_exp_f32_e32 v154, v42
	v_exp_f32_e32 v155, v43
	v_mfma_f32_32x32x16_bf16 v[96:111], v[56:59], v[172:175], v[96:111]
	ds_read_b128 v[40:43], v236 offset:28672
	v_exp_f32_e32 v156, v44
	v_exp_f32_e32 v157, v45
	v_exp_f32_e32 v158, v46
	v_exp_f32_e32 v159, v47
	v_cvt_pk_bf16_f32 v44, v140, v141
	v_cvt_pk_bf16_f32 v45, v142, v143
	v_cvt_pk_bf16_f32 v46, v144, v145
	v_cvt_pk_bf16_f32 v47, v146, v147
	s_nop 1
	v_mfma_f32_32x32x16_bf16 v[80:95], v[60:63], v[44:47], v[80:95]
	ds_read_b128 v[48:51], v237 offset:16384
	v_cvt_pk_bf16_f32 v52, v148, v149
	v_cvt_pk_bf16_f32 v53, v150, v151
	v_cvt_pk_bf16_f32 v54, v128, v129
	v_cvt_pk_bf16_f32 v55, v130, v131
	v_mfma_f32_32x32x16_bf16 v[64:79], v[32:35], v[44:47], v[64:79]
	ds_read_b128 v[56:59], v237 offset:20480
	v_pk_add_f32 v[62:63], v[146:147], v[142:143]
	v_pk_add_f32 v[60:61], v[144:145], v[140:141]
	s_waitcnt lgkmcnt(0)
	v_mfma_f32_32x32x16_bf16 v[16:31], v[36:39], v[44:47], v[16:31]
	ds_read_b128 v[32:35], v237 offset:24576
	v_add_f32_e64 v62, v150, v62
	v_add_f32_e64 v63, v151, v63
	v_add_f32_e64 v60, v148, v60
	v_add_f32_e64 v61, v149, v61
	v_pk_add_f32 v[62:63], v[130:131], v[62:63]
	v_pk_add_f32 v[60:61], v[128:129], v[60:61]
	v_mfma_f32_32x32x16_bf16 v[0:15], v[40:43], v[44:47], v[0:15]
	ds_read_b128 v[36:39], v237 offset:28672
	v_mfma_f32_32x32x16_bf16 v[80:95], v[48:51], v[52:55], v[80:95]
	ds_read_b128 v[40:43], v238 offset:16384
	v_cvt_pk_bf16_f32 v44, v132, v133
	v_cvt_pk_bf16_f32 v45, v134, v135
	v_cvt_pk_bf16_f32 v46, v136, v137
	v_cvt_pk_bf16_f32 v47, v138, v139
	v_mfma_f32_32x32x16_bf16 v[64:79], v[56:59], v[52:55], v[64:79]
	ds_read_b128 v[48:51], v238 offset:20480
	v_add_f32_e64 v62, v134, v62
	v_add_f32_e64 v63, v135, v63
	v_add_f32_e64 v60, v132, v60
	v_add_f32_e64 v61, v133, v61
	v_pk_add_f32 v[62:63], v[138:139], v[62:63]
	v_pk_add_f32 v[60:61], v[136:137], v[60:61]
	s_waitcnt lgkmcnt(0)
	v_mfma_f32_32x32x16_bf16 v[16:31], v[32:35], v[52:55], v[16:31]
	ds_read_b128 v[56:59], v238 offset:24576
	v_add_f32_e64 v62, v154, v62
	v_add_f32_e64 v63, v155, v63
	v_add_f32_e64 v60, v152, v60
	v_add_f32_e64 v61, v153, v61
	v_pk_add_f32 v[130:131], v[158:159], v[62:63]
	v_pk_add_f32 v[128:129], v[156:157], v[60:61]
	v_mfma_f32_32x32x16_bf16 v[0:15], v[36:39], v[52:55], v[0:15]
	ds_read_b128 v[32:35], v238 offset:28672
	v_mfma_f32_32x32x16_bf16 v[80:95], v[40:43], v[44:47], v[80:95]
	ds_read_b128 v[36:39], v239 offset:16384
	v_cvt_pk_bf16_f32 v52, v152, v153
	v_cvt_pk_bf16_f32 v53, v154, v155
	v_cvt_pk_bf16_f32 v54, v156, v157
	v_cvt_pk_bf16_f32 v55, v158, v159
	v_mfma_f32_32x32x16_bf16 v[64:79], v[48:51], v[44:47], v[64:79]
	ds_read_b128 v[40:43], v239 offset:20480
	s_waitcnt lgkmcnt(0)
	v_mfma_f32_32x32x16_bf16 v[16:31], v[56:59], v[44:47], v[16:31]
	ds_read_b128 v[48:51], v239 offset:24576
	v_mfma_f32_32x32x16_bf16 v[0:15], v[32:35], v[44:47], v[0:15]
	ds_read_b128 v[56:59], v239 offset:28672
	v_mfma_f32_32x32x16_bf16 v[80:95], v[36:39], v[52:55], v[80:95]
	v_mfma_f32_32x32x16_bf16 v[64:79], v[40:43], v[52:55], v[64:79]
	s_waitcnt lgkmcnt(0)
	v_mfma_f32_32x32x16_bf16 v[16:31], v[48:51], v[52:55], v[16:31]
	v_mfma_f32_32x32x16_bf16 v[0:15], v[56:59], v[52:55], v[0:15]
	s_waitcnt vmcnt(4) lgkmcnt(0)
	s_barrier
	s_add_u32 s68, s98, 0x18000
	s_addc_u32 s69, s99, 0
	s_add_i32 s49, 0x4000, s57
	s_mov_b32 m0, s49
	s_nop 0
	global_load_lds_dwordx4 v198, s[68:69]
	s_add_i32 m0, s49, 0x400
	s_nop 0
	global_load_lds_dwordx4 v194, s[68:69]
	s_add_u32 s44, s100, 0x80
	s_addc_u32 s45, s101, 0
	s_add_i32 s49, s58, 0x4000
	s_add_i32 m0, s49, 0xc000
	s_nop 0
	global_load_lds_dwordx4 v196, s[44:45]
	s_add_i32 m0, s49, 0xc400
	s_nop 0
	global_load_lds_dwordx4 v192, s[44:45]
	v_exp_f32_e32 v144, v112
	ds_read_b128 v[32:35], v205 offset:32768
	ds_read_b128 v[36:39], v205 offset:40960
	s_waitcnt lgkmcnt(0)
	v_mfma_f32_32x32x16_bf16 v[48:63], v[32:35], v[160:163], 0
	ds_read_b128 v[132:135], v211 offset:32768
	ds_read_b128 v[136:139], v211 offset:40960
	ds_read_b128 v[140:143], v212 offset:32768
	v_exp_f32_e32 v145, v113
	v_exp_f32_e32 v146, v114
	v_exp_f32_e32 v147, v115
	ds_read_b128 v[112:115], v212 offset:40960
	v_mfma_f32_32x32x16_bf16 v[32:47], v[36:39], v[160:163], 0
	v_exp_f32_e32 v148, v116
	v_exp_f32_e32 v149, v117
	v_exp_f32_e32 v150, v118
	v_exp_f32_e32 v151, v119
	s_waitcnt lgkmcnt(0)
	v_mfma_f32_32x32x16_bf16 v[48:63], v[132:135], v[164:167], v[48:63]
	ds_read_b128 v[116:119], v213 offset:32768
	v_exp_f32_e32 v152, v120
	v_exp_f32_e32 v153, v121
	v_exp_f32_e32 v154, v122
	v_exp_f32_e32 v155, v123
	v_mfma_f32_32x32x16_bf16 v[32:47], v[136:139], v[164:167], v[32:47]
	ds_read_b128 v[120:123], v213 offset:40960
	v_exp_f32_e32 v156, v124
	v_exp_f32_e32 v157, v125
	v_exp_f32_e32 v158, v126
	v_exp_f32_e32 v159, v127
	v_mfma_f32_32x32x16_bf16 v[48:63], v[140:143], v[168:171], v[48:63]
	ds_read_b128 v[124:127], v236 offset:32768
	v_exp_f32_e32 v136, v96
	v_exp_f32_e32 v137, v97
	v_exp_f32_e32 v138, v98
	v_exp_f32_e32 v139, v99
	v_mfma_f32_32x32x16_bf16 v[32:47], v[112:115], v[168:171], v[32:47]
	ds_read_b128 v[96:99], v236 offset:36864
	v_exp_f32_e32 v140, v100
	v_exp_f32_e32 v141, v101
	v_exp_f32_e32 v142, v102
	v_exp_f32_e32 v143, v103
	s_waitcnt lgkmcnt(0)
	v_mfma_f32_32x32x16_bf16 v[48:63], v[116:119], v[172:175], v[48:63]
	ds_read_b128 v[100:103], v236 offset:40960
	v_exp_f32_e32 v178, v104
	v_exp_f32_e32 v179, v105
	v_exp_f32_e32 v180, v106
	v_exp_f32_e32 v181, v107
	v_mfma_f32_32x32x16_bf16 v[32:47], v[120:123], v[172:175], v[32:47]
	ds_read_b128 v[104:107], v236 offset:45056
	v_exp_f32_e32 v182, v108
	v_exp_f32_e32 v183, v109
	v_exp_f32_e32 v184, v110
	v_exp_f32_e32 v185, v111
	v_cvt_pk_bf16_f32 v108, v144, v145
	v_cvt_pk_bf16_f32 v109, v146, v147
	v_cvt_pk_bf16_f32 v110, v148, v149
	v_cvt_pk_bf16_f32 v111, v150, v151
	s_nop 1
	v_mfma_f32_32x32x16_bf16 v[80:95], v[124:127], v[108:111], v[80:95]
	ds_read_b128 v[112:115], v237 offset:32768
	v_cvt_pk_bf16_f32 v116, v152, v153
	v_cvt_pk_bf16_f32 v117, v154, v155
	v_cvt_pk_bf16_f32 v118, v156, v157
	v_cvt_pk_bf16_f32 v119, v158, v159
	v_mfma_f32_32x32x16_bf16 v[64:79], v[96:99], v[108:111], v[64:79]
	ds_read_b128 v[120:123], v237 offset:36864
	v_pk_add_f32 v[126:127], v[150:151], v[146:147]
	v_pk_add_f32 v[124:125], v[148:149], v[144:145]
	s_waitcnt lgkmcnt(0)
	v_mfma_f32_32x32x16_bf16 v[16:31], v[100:103], v[108:111], v[16:31]
	ds_read_b128 v[132:135], v237 offset:40960
	v_add_f32_e64 v98, v154, v126
	v_add_f32_e64 v99, v155, v127
	v_add_f32_e64 v96, v152, v124
	v_add_f32_e64 v97, v153, v125
	v_pk_add_f32 v[98:99], v[158:159], v[98:99]
	v_pk_add_f32 v[96:97], v[156:157], v[96:97]
	v_mfma_f32_32x32x16_bf16 v[0:15], v[104:107], v[108:111], v[0:15]
	ds_read_b128 v[100:103], v237 offset:45056
	v_mfma_f32_32x32x16_bf16 v[80:95], v[112:115], v[116:119], v[80:95]
	ds_read_b128 v[104:107], v238 offset:32768
	v_cvt_pk_bf16_f32 v108, v136, v137
	v_cvt_pk_bf16_f32 v109, v138, v139
	v_cvt_pk_bf16_f32 v110, v140, v141
	v_cvt_pk_bf16_f32 v111, v142, v143
	v_mfma_f32_32x32x16_bf16 v[64:79], v[120:123], v[116:119], v[64:79]
	ds_read_b128 v[112:115], v238 offset:36864
	v_add_f32_e64 v98, v138, v98
	v_add_f32_e64 v99, v139, v99
	v_add_f32_e64 v96, v136, v96
	v_add_f32_e64 v97, v137, v97
	v_pk_add_f32 v[98:99], v[142:143], v[98:99]
	v_pk_add_f32 v[96:97], v[140:141], v[96:97]
	s_waitcnt lgkmcnt(0)
	v_mfma_f32_32x32x16_bf16 v[16:31], v[132:135], v[116:119], v[16:31]
	ds_read_b128 v[120:123], v238 offset:40960
	v_add_f32_e64 v98, v180, v98
	v_add_f32_e64 v99, v181, v99
	v_add_f32_e64 v96, v178, v96
	v_add_f32_e64 v97, v179, v97
	v_pk_add_f32 v[98:99], v[184:185], v[98:99]
	v_pk_add_f32 v[96:97], v[182:183], v[96:97]
	v_mfma_f32_32x32x16_bf16 v[0:15], v[100:103], v[116:119], v[0:15]
	ds_read_b128 v[124:127], v238 offset:45056
	v_mfma_f32_32x32x16_bf16 v[80:95], v[104:107], v[108:111], v[80:95]
	ds_read_b128 v[100:103], v239 offset:32768
	v_cvt_pk_bf16_f32 v116, v178, v179
	v_cvt_pk_bf16_f32 v117, v180, v181
	v_cvt_pk_bf16_f32 v118, v182, v183
	v_cvt_pk_bf16_f32 v119, v184, v185
	v_mfma_f32_32x32x16_bf16 v[64:79], v[112:115], v[108:111], v[64:79]
	ds_read_b128 v[104:107], v239 offset:36864
	s_waitcnt lgkmcnt(0)
	v_mfma_f32_32x32x16_bf16 v[16:31], v[120:123], v[108:111], v[16:31]
	ds_read_b128 v[112:115], v239 offset:40960
	v_mfma_f32_32x32x16_bf16 v[0:15], v[124:127], v[108:111], v[0:15]
	ds_read_b128 v[120:123], v239 offset:45056
	v_mfma_f32_32x32x16_bf16 v[80:95], v[100:103], v[116:119], v[80:95]
	v_mfma_f32_32x32x16_bf16 v[64:79], v[104:107], v[116:119], v[64:79]
	s_waitcnt lgkmcnt(0)
	v_mfma_f32_32x32x16_bf16 v[16:31], v[112:115], v[116:119], v[16:31]
	v_mfma_f32_32x32x16_bf16 v[0:15], v[120:123], v[116:119], v[0:15]
	s_waitcnt vmcnt(4) lgkmcnt(0)
	v_add_f32_e32 v100, v128, v129
	v_add_f32_e32 v101, v130, v131
	v_add_f32_e32 v100, v100, v101
	v_add_f32_e32 v96, v96, v97
	v_add_f32_e32 v97, v98, v99
	s_barrier
	v_add_f32_e32 v100, v177, v100
	v_add_f32_e32 v96, v96, v97
	v_add_f32_e32 v177, v100, v96
	s_add_u32 s98, s98, 0x30000
	s_addc_u32 s99, s99, 0
	s_add_u32 s100, s100, 0x100
	s_addc_u32 s101, s101, 0
	s_add_i32 s46, s58, 0x8000
	s_mov_b32 m0, s46
	s_nop 0
	global_load_lds_dwordx4 v198, s[98:99]
	s_add_i32 m0, s46, 0x400
	s_nop 0
	global_load_lds_dwordx4 v194, s[98:99]
	s_add_i32 s48, s58, 0x8000
	s_add_i32 m0, s48, 0xc000
	s_nop 0
	global_load_lds_dwordx4 v196, s[100:101]
	s_add_i32 m0, s48, 0xc400
	s_nop 0
	global_load_lds_dwordx4 v192, s[100:101]
	ds_read_b128 v[96:99], v205
	ds_read_b128 v[100:103], v205 offset:8192
	s_waitcnt lgkmcnt(0)
	v_mfma_f32_32x32x16_bf16 v[112:127], v[96:99], v[160:163], 0
	ds_read_b128 v[128:131], v211
	ds_read_b128 v[132:135], v211 offset:8192
	ds_read_b128 v[136:139], v212
	v_exp_f32_e32 v140, v48
	v_exp_f32_e32 v141, v49
	v_exp_f32_e32 v142, v50
	v_exp_f32_e32 v143, v51
	ds_read_b128 v[48:51], v212 offset:8192
	v_mfma_f32_32x32x16_bf16 v[96:111], v[100:103], v[160:163], 0
	v_exp_f32_e32 v144, v52
	v_exp_f32_e32 v145, v53
	v_exp_f32_e32 v146, v54
	v_exp_f32_e32 v147, v55
	s_waitcnt lgkmcnt(0)
	v_mfma_f32_32x32x16_bf16 v[112:127], v[128:131], v[164:167], v[112:127]
	ds_read_b128 v[52:55], v213
	v_exp_f32_e32 v148, v56
	v_exp_f32_e32 v149, v57
	v_exp_f32_e32 v150, v58
	v_exp_f32_e32 v151, v59
	v_mfma_f32_32x32x16_bf16 v[96:111], v[132:135], v[164:167], v[96:111]
	ds_read_b128 v[56:59], v213 offset:8192
	v_exp_f32_e32 v128, v60
	v_exp_f32_e32 v129, v61
	v_exp_f32_e32 v130, v62
	v_exp_f32_e32 v131, v63
	v_mfma_f32_32x32x16_bf16 v[112:127], v[136:139], v[168:171], v[112:127]
	ds_read_b128 v[60:63], v206 offset:49152
	v_exp_f32_e32 v132, v32
	v_exp_f32_e32 v133, v33
	v_exp_f32_e32 v134, v34
	v_exp_f32_e32 v135, v35
	v_mfma_f32_32x32x16_bf16 v[96:111], v[48:51], v[168:171], v[96:111]
	ds_read_b128 v[32:35], v206 offset:53248
	v_exp_f32_e32 v136, v36
	v_exp_f32_e32 v137, v37
	v_exp_f32_e32 v138, v38
	v_exp_f32_e32 v139, v39
	s_waitcnt lgkmcnt(0)
	v_mfma_f32_32x32x16_bf16 v[112:127], v[52:55], v[172:175], v[112:127]
	ds_read_b128 v[36:39], v206 offset:57344
	v_exp_f32_e32 v152, v40
	v_exp_f32_e32 v153, v41
	v_exp_f32_e32 v154, v42
	v_exp_f32_e32 v155, v43
	v_mfma_f32_32x32x16_bf16 v[96:111], v[56:59], v[172:175], v[96:111]
	ds_read_b128 v[40:43], v206 offset:61440
	v_exp_f32_e32 v156, v44
	v_exp_f32_e32 v157, v45
	v_exp_f32_e32 v158, v46
	v_exp_f32_e32 v159, v47
	v_cvt_pk_bf16_f32 v44, v140, v141
	v_cvt_pk_bf16_f32 v45, v142, v143
	v_cvt_pk_bf16_f32 v46, v144, v145
	v_cvt_pk_bf16_f32 v47, v146, v147
	s_nop 1
	v_mfma_f32_32x32x16_bf16 v[80:95], v[60:63], v[44:47], v[80:95]
	ds_read_b128 v[48:51], v207 offset:49152
	v_cvt_pk_bf16_f32 v52, v148, v149
	v_cvt_pk_bf16_f32 v53, v150, v151
	v_cvt_pk_bf16_f32 v54, v128, v129
	v_cvt_pk_bf16_f32 v55, v130, v131
	v_mfma_f32_32x32x16_bf16 v[64:79], v[32:35], v[44:47], v[64:79]
	ds_read_b128 v[56:59], v207 offset:53248
	v_pk_add_f32 v[62:63], v[146:147], v[142:143]
	v_pk_add_f32 v[60:61], v[144:145], v[140:141]
	s_waitcnt lgkmcnt(0)
	v_mfma_f32_32x32x16_bf16 v[16:31], v[36:39], v[44:47], v[16:31]
	ds_read_b128 v[32:35], v207 offset:57344
	v_add_f32_e64 v62, v150, v62
	v_add_f32_e64 v63, v151, v63
	v_add_f32_e64 v60, v148, v60
	v_add_f32_e64 v61, v149, v61
	v_pk_add_f32 v[62:63], v[130:131], v[62:63]
	v_pk_add_f32 v[60:61], v[128:129], v[60:61]
	v_mfma_f32_32x32x16_bf16 v[0:15], v[40:43], v[44:47], v[0:15]
	ds_read_b128 v[36:39], v207 offset:61440
	v_mfma_f32_32x32x16_bf16 v[80:95], v[48:51], v[52:55], v[80:95]
	ds_read_b128 v[40:43], v208 offset:49152
	v_cvt_pk_bf16_f32 v44, v132, v133
	v_cvt_pk_bf16_f32 v45, v134, v135
	v_cvt_pk_bf16_f32 v46, v136, v137
	v_cvt_pk_bf16_f32 v47, v138, v139
	v_mfma_f32_32x32x16_bf16 v[64:79], v[56:59], v[52:55], v[64:79]
	ds_read_b128 v[48:51], v208 offset:53248
	v_add_f32_e64 v62, v134, v62
	v_add_f32_e64 v63, v135, v63
	v_add_f32_e64 v60, v132, v60
	v_add_f32_e64 v61, v133, v61
	v_pk_add_f32 v[62:63], v[138:139], v[62:63]
	v_pk_add_f32 v[60:61], v[136:137], v[60:61]
	s_waitcnt lgkmcnt(0)
	v_mfma_f32_32x32x16_bf16 v[16:31], v[32:35], v[52:55], v[16:31]
	ds_read_b128 v[56:59], v208 offset:57344
	v_add_f32_e64 v62, v154, v62
	v_add_f32_e64 v63, v155, v63
	v_add_f32_e64 v60, v152, v60
	v_add_f32_e64 v61, v153, v61
	v_pk_add_f32 v[130:131], v[158:159], v[62:63]
	v_pk_add_f32 v[128:129], v[156:157], v[60:61]
	v_mfma_f32_32x32x16_bf16 v[0:15], v[36:39], v[52:55], v[0:15]
	ds_read_b128 v[32:35], v208 offset:61440
	v_mfma_f32_32x32x16_bf16 v[80:95], v[40:43], v[44:47], v[80:95]
	ds_read_b128 v[36:39], v209 offset:49152
	v_cvt_pk_bf16_f32 v52, v152, v153
	v_cvt_pk_bf16_f32 v53, v154, v155
	v_cvt_pk_bf16_f32 v54, v156, v157
	v_cvt_pk_bf16_f32 v55, v158, v159
	v_mfma_f32_32x32x16_bf16 v[64:79], v[48:51], v[44:47], v[64:79]
	ds_read_b128 v[40:43], v209 offset:53248
	s_waitcnt lgkmcnt(0)
	v_mfma_f32_32x32x16_bf16 v[16:31], v[56:59], v[44:47], v[16:31]
	ds_read_b128 v[48:51], v209 offset:57344
	v_mfma_f32_32x32x16_bf16 v[0:15], v[32:35], v[44:47], v[0:15]
	ds_read_b128 v[56:59], v209 offset:61440
	v_mfma_f32_32x32x16_bf16 v[80:95], v[36:39], v[52:55], v[80:95]
	v_mfma_f32_32x32x16_bf16 v[64:79], v[40:43], v[52:55], v[64:79]
	s_waitcnt lgkmcnt(0)
	v_mfma_f32_32x32x16_bf16 v[16:31], v[48:51], v[52:55], v[16:31]
	v_mfma_f32_32x32x16_bf16 v[0:15], v[56:59], v[52:55], v[0:15]
	s_waitcnt vmcnt(4) lgkmcnt(0)
	s_barrier
	s_add_u32 s68, s98, 0x18000
	s_addc_u32 s69, s99, 0
	s_add_i32 s49, 0, s57
	s_mov_b32 m0, s49
	s_nop 0
	global_load_lds_dwordx4 v198, s[68:69]
	s_add_i32 m0, s49, 0x400
	s_nop 0
	global_load_lds_dwordx4 v194, s[68:69]
	s_add_u32 s44, s100, 0x80
	s_addc_u32 s45, s101, 0
	s_add_i32 s49, s58, 0xc000
	s_add_i32 m0, s49, 0xc000
	s_nop 0
	global_load_lds_dwordx4 v196, s[44:45]
	s_add_i32 m0, s49, 0xc400
	s_nop 0
	global_load_lds_dwordx4 v192, s[44:45]
	v_exp_f32_e32 v144, v112
	ds_read_b128 v[32:35], v205 offset:16384
	ds_read_b128 v[36:39], v205 offset:24576
	s_waitcnt lgkmcnt(0)
	v_mfma_f32_32x32x16_bf16 v[48:63], v[32:35], v[160:163], 0
	ds_read_b128 v[132:135], v211 offset:16384
	ds_read_b128 v[136:139], v211 offset:24576
	ds_read_b128 v[140:143], v212 offset:16384
	v_exp_f32_e32 v145, v113
	v_exp_f32_e32 v146, v114
	v_exp_f32_e32 v147, v115
	ds_read_b128 v[112:115], v212 offset:24576
	v_mfma_f32_32x32x16_bf16 v[32:47], v[36:39], v[160:163], 0
	v_exp_f32_e32 v148, v116
	v_exp_f32_e32 v149, v117
	v_exp_f32_e32 v150, v118
	v_exp_f32_e32 v151, v119
	s_waitcnt lgkmcnt(0)
	v_mfma_f32_32x32x16_bf16 v[48:63], v[132:135], v[164:167], v[48:63]
	ds_read_b128 v[116:119], v213 offset:16384
	v_exp_f32_e32 v152, v120
	v_exp_f32_e32 v153, v121
	v_exp_f32_e32 v154, v122
	v_exp_f32_e32 v155, v123
	v_mfma_f32_32x32x16_bf16 v[32:47], v[136:139], v[164:167], v[32:47]
	ds_read_b128 v[120:123], v213 offset:24576
	v_exp_f32_e32 v156, v124
	v_exp_f32_e32 v157, v125
	v_exp_f32_e32 v158, v126
	v_exp_f32_e32 v159, v127
	v_mfma_f32_32x32x16_bf16 v[48:63], v[140:143], v[168:171], v[48:63]
	ds_read_b128 v[124:127], v236
	v_exp_f32_e32 v136, v96
	v_exp_f32_e32 v137, v97
	v_exp_f32_e32 v138, v98
	v_exp_f32_e32 v139, v99
	v_mfma_f32_32x32x16_bf16 v[32:47], v[112:115], v[168:171], v[32:47]
	ds_read_b128 v[96:99], v236 offset:4096
	v_exp_f32_e32 v140, v100
	v_exp_f32_e32 v141, v101
	v_exp_f32_e32 v142, v102
	v_exp_f32_e32 v143, v103
	s_waitcnt lgkmcnt(0)
	v_mfma_f32_32x32x16_bf16 v[48:63], v[116:119], v[172:175], v[48:63]
	ds_read_b128 v[100:103], v236 offset:8192
	v_exp_f32_e32 v178, v104
	v_exp_f32_e32 v179, v105
	v_exp_f32_e32 v180, v106
	v_exp_f32_e32 v181, v107
	v_mfma_f32_32x32x16_bf16 v[32:47], v[120:123], v[172:175], v[32:47]
	ds_read_b128 v[104:107], v236 offset:12288
	v_exp_f32_e32 v182, v108
	v_exp_f32_e32 v183, v109
	v_exp_f32_e32 v184, v110
	v_exp_f32_e32 v185, v111
	v_cvt_pk_bf16_f32 v108, v144, v145
	v_cvt_pk_bf16_f32 v109, v146, v147
	v_cvt_pk_bf16_f32 v110, v148, v149
	v_cvt_pk_bf16_f32 v111, v150, v151
	s_nop 1
	v_mfma_f32_32x32x16_bf16 v[80:95], v[124:127], v[108:111], v[80:95]
	ds_read_b128 v[112:115], v237
	v_cvt_pk_bf16_f32 v116, v152, v153
	v_cvt_pk_bf16_f32 v117, v154, v155
	v_cvt_pk_bf16_f32 v118, v156, v157
	v_cvt_pk_bf16_f32 v119, v158, v159
	v_mfma_f32_32x32x16_bf16 v[64:79], v[96:99], v[108:111], v[64:79]
	ds_read_b128 v[120:123], v237 offset:4096
	v_pk_add_f32 v[126:127], v[150:151], v[146:147]
	v_pk_add_f32 v[124:125], v[148:149], v[144:145]
	s_waitcnt lgkmcnt(0)
	v_mfma_f32_32x32x16_bf16 v[16:31], v[100:103], v[108:111], v[16:31]
	ds_read_b128 v[132:135], v237 offset:8192
	v_add_f32_e64 v98, v154, v126
	v_add_f32_e64 v99, v155, v127
	v_add_f32_e64 v96, v152, v124
	v_add_f32_e64 v97, v153, v125
	v_pk_add_f32 v[98:99], v[158:159], v[98:99]
	v_pk_add_f32 v[96:97], v[156:157], v[96:97]
	v_mfma_f32_32x32x16_bf16 v[0:15], v[104:107], v[108:111], v[0:15]
	ds_read_b128 v[100:103], v237 offset:12288
	v_mfma_f32_32x32x16_bf16 v[80:95], v[112:115], v[116:119], v[80:95]
	ds_read_b128 v[104:107], v238
	v_cvt_pk_bf16_f32 v108, v136, v137
	v_cvt_pk_bf16_f32 v109, v138, v139
	v_cvt_pk_bf16_f32 v110, v140, v141
	v_cvt_pk_bf16_f32 v111, v142, v143
	v_mfma_f32_32x32x16_bf16 v[64:79], v[120:123], v[116:119], v[64:79]
	ds_read_b128 v[112:115], v238 offset:4096
	v_add_f32_e64 v98, v138, v98
	v_add_f32_e64 v99, v139, v99
	v_add_f32_e64 v96, v136, v96
	v_add_f32_e64 v97, v137, v97
	v_pk_add_f32 v[98:99], v[142:143], v[98:99]
	v_pk_add_f32 v[96:97], v[140:141], v[96:97]
	s_waitcnt lgkmcnt(0)
	v_mfma_f32_32x32x16_bf16 v[16:31], v[132:135], v[116:119], v[16:31]
	ds_read_b128 v[120:123], v238 offset:8192
	v_add_f32_e64 v98, v180, v98
	v_add_f32_e64 v99, v181, v99
	v_add_f32_e64 v96, v178, v96
	v_add_f32_e64 v97, v179, v97
	v_pk_add_f32 v[98:99], v[184:185], v[98:99]
	v_pk_add_f32 v[96:97], v[182:183], v[96:97]
	v_mfma_f32_32x32x16_bf16 v[0:15], v[100:103], v[116:119], v[0:15]
	ds_read_b128 v[124:127], v238 offset:12288
	v_mfma_f32_32x32x16_bf16 v[80:95], v[104:107], v[108:111], v[80:95]
	ds_read_b128 v[100:103], v239
	v_cvt_pk_bf16_f32 v116, v178, v179
	v_cvt_pk_bf16_f32 v117, v180, v181
	v_cvt_pk_bf16_f32 v118, v182, v183
	v_cvt_pk_bf16_f32 v119, v184, v185
	v_mfma_f32_32x32x16_bf16 v[64:79], v[112:115], v[108:111], v[64:79]
	ds_read_b128 v[104:107], v239 offset:4096
	s_waitcnt lgkmcnt(0)
	v_mfma_f32_32x32x16_bf16 v[16:31], v[120:123], v[108:111], v[16:31]
	ds_read_b128 v[112:115], v239 offset:8192
	v_mfma_f32_32x32x16_bf16 v[0:15], v[124:127], v[108:111], v[0:15]
	ds_read_b128 v[120:123], v239 offset:12288
	v_mfma_f32_32x32x16_bf16 v[80:95], v[100:103], v[116:119], v[80:95]
	v_mfma_f32_32x32x16_bf16 v[64:79], v[104:107], v[116:119], v[64:79]
	s_waitcnt lgkmcnt(0)
	v_mfma_f32_32x32x16_bf16 v[16:31], v[112:115], v[116:119], v[16:31]
	v_mfma_f32_32x32x16_bf16 v[0:15], v[120:123], v[116:119], v[0:15]
	s_waitcnt vmcnt(4) lgkmcnt(0)
	v_add_f32_e32 v100, v128, v129
	v_add_f32_e32 v101, v130, v131
	v_add_f32_e32 v100, v100, v101
	v_add_f32_e32 v96, v96, v97
	v_add_f32_e32 v97, v98, v99
	s_barrier
	v_add_f32_e32 v100, v177, v100
	v_add_f32_e32 v96, v96, v97
	v_add_f32_e32 v177, v100, v96
	s_add_u32 s98, s98, 0x30000
	s_addc_u32 s99, s99, 0
	s_add_u32 s100, s100, 0x100
	s_addc_u32 s101, s101, 0
	s_add_i32 s46, s58, 0x4000
	s_mov_b32 m0, s46
	s_nop 0
	global_load_lds_dwordx4 v198, s[98:99]
	s_add_i32 m0, s46, 0x400
	s_nop 0
	global_load_lds_dwordx4 v194, s[98:99]
	s_add_i32 s48, s58, 0
	s_add_i32 m0, s48, 0xc000
	s_nop 0
	global_load_lds_dwordx4 v196, s[100:101]
	s_add_i32 m0, s48, 0xc400
	s_nop 0
	global_load_lds_dwordx4 v192, s[100:101]
	ds_read_b128 v[96:99], v205 offset:32768
	ds_read_b128 v[100:103], v205 offset:40960
	s_waitcnt lgkmcnt(0)
	v_mfma_f32_32x32x16_bf16 v[112:127], v[96:99], v[160:163], 0
	ds_read_b128 v[128:131], v211 offset:32768
	ds_read_b128 v[132:135], v211 offset:40960
	ds_read_b128 v[136:139], v212 offset:32768
	v_exp_f32_e32 v140, v48
	v_exp_f32_e32 v141, v49
	v_exp_f32_e32 v142, v50
	v_exp_f32_e32 v143, v51
	ds_read_b128 v[48:51], v212 offset:40960
	v_mfma_f32_32x32x16_bf16 v[96:111], v[100:103], v[160:163], 0
	v_exp_f32_e32 v144, v52
	v_exp_f32_e32 v145, v53
	v_exp_f32_e32 v146, v54
	v_exp_f32_e32 v147, v55
	s_waitcnt lgkmcnt(0)
	v_mfma_f32_32x32x16_bf16 v[112:127], v[128:131], v[164:167], v[112:127]
	ds_read_b128 v[52:55], v213 offset:32768
	v_exp_f32_e32 v148, v56
	v_exp_f32_e32 v149, v57
	v_exp_f32_e32 v150, v58
	v_exp_f32_e32 v151, v59
	v_mfma_f32_32x32x16_bf16 v[96:111], v[132:135], v[164:167], v[96:111]
	ds_read_b128 v[56:59], v213 offset:40960
	v_exp_f32_e32 v128, v60
	v_exp_f32_e32 v129, v61
	v_exp_f32_e32 v130, v62
	v_exp_f32_e32 v131, v63
	v_mfma_f32_32x32x16_bf16 v[112:127], v[136:139], v[168:171], v[112:127]
	ds_read_b128 v[60:63], v236 offset:16384
	v_exp_f32_e32 v132, v32
	v_exp_f32_e32 v133, v33
	v_exp_f32_e32 v134, v34
	v_exp_f32_e32 v135, v35
	v_mfma_f32_32x32x16_bf16 v[96:111], v[48:51], v[168:171], v[96:111]
	ds_read_b128 v[32:35], v236 offset:20480
	v_exp_f32_e32 v136, v36
	v_exp_f32_e32 v137, v37
	v_exp_f32_e32 v138, v38
	v_exp_f32_e32 v139, v39
	s_waitcnt lgkmcnt(0)
	v_mfma_f32_32x32x16_bf16 v[112:127], v[52:55], v[172:175], v[112:127]
	ds_read_b128 v[36:39], v236 offset:24576
	v_exp_f32_e32 v152, v40
	v_exp_f32_e32 v153, v41
	v_exp_f32_e32 v154, v42
	v_exp_f32_e32 v155, v43
	v_mfma_f32_32x32x16_bf16 v[96:111], v[56:59], v[172:175], v[96:111]
	ds_read_b128 v[40:43], v236 offset:28672
	v_exp_f32_e32 v156, v44
	v_exp_f32_e32 v157, v45
	v_exp_f32_e32 v158, v46
	v_exp_f32_e32 v159, v47
	v_cvt_pk_bf16_f32 v44, v140, v141
	v_cvt_pk_bf16_f32 v45, v142, v143
	v_cvt_pk_bf16_f32 v46, v144, v145
	v_cvt_pk_bf16_f32 v47, v146, v147
	s_nop 1
	v_mfma_f32_32x32x16_bf16 v[80:95], v[60:63], v[44:47], v[80:95]
	ds_read_b128 v[48:51], v237 offset:16384
	v_cvt_pk_bf16_f32 v52, v148, v149
	v_cvt_pk_bf16_f32 v53, v150, v151
	v_cvt_pk_bf16_f32 v54, v128, v129
	v_cvt_pk_bf16_f32 v55, v130, v131
	v_mfma_f32_32x32x16_bf16 v[64:79], v[32:35], v[44:47], v[64:79]
	ds_read_b128 v[56:59], v237 offset:20480
	v_pk_add_f32 v[62:63], v[146:147], v[142:143]
	v_pk_add_f32 v[60:61], v[144:145], v[140:141]
	s_waitcnt lgkmcnt(0)
	v_mfma_f32_32x32x16_bf16 v[16:31], v[36:39], v[44:47], v[16:31]
	ds_read_b128 v[32:35], v237 offset:24576
	v_add_f32_e64 v62, v150, v62
	v_add_f32_e64 v63, v151, v63
	v_add_f32_e64 v60, v148, v60
	v_add_f32_e64 v61, v149, v61
	v_pk_add_f32 v[62:63], v[130:131], v[62:63]
	v_pk_add_f32 v[60:61], v[128:129], v[60:61]
	v_mfma_f32_32x32x16_bf16 v[0:15], v[40:43], v[44:47], v[0:15]
	ds_read_b128 v[36:39], v237 offset:28672
	v_mfma_f32_32x32x16_bf16 v[80:95], v[48:51], v[52:55], v[80:95]
	ds_read_b128 v[40:43], v238 offset:16384
	v_cvt_pk_bf16_f32 v44, v132, v133
	v_cvt_pk_bf16_f32 v45, v134, v135
	v_cvt_pk_bf16_f32 v46, v136, v137
	v_cvt_pk_bf16_f32 v47, v138, v139
	v_mfma_f32_32x32x16_bf16 v[64:79], v[56:59], v[52:55], v[64:79]
	ds_read_b128 v[48:51], v238 offset:20480
	v_add_f32_e64 v62, v134, v62
	v_add_f32_e64 v63, v135, v63
	v_add_f32_e64 v60, v132, v60
	v_add_f32_e64 v61, v133, v61
	v_pk_add_f32 v[62:63], v[138:139], v[62:63]
	v_pk_add_f32 v[60:61], v[136:137], v[60:61]
	s_waitcnt lgkmcnt(0)
	v_mfma_f32_32x32x16_bf16 v[16:31], v[32:35], v[52:55], v[16:31]
	ds_read_b128 v[56:59], v238 offset:24576
	v_add_f32_e64 v62, v154, v62
	v_add_f32_e64 v63, v155, v63
	v_add_f32_e64 v60, v152, v60
	v_add_f32_e64 v61, v153, v61
	v_pk_add_f32 v[130:131], v[158:159], v[62:63]
	v_pk_add_f32 v[128:129], v[156:157], v[60:61]
	v_mfma_f32_32x32x16_bf16 v[0:15], v[36:39], v[52:55], v[0:15]
	ds_read_b128 v[32:35], v238 offset:28672
	v_mfma_f32_32x32x16_bf16 v[80:95], v[40:43], v[44:47], v[80:95]
	ds_read_b128 v[36:39], v239 offset:16384
	v_cvt_pk_bf16_f32 v52, v152, v153
	v_cvt_pk_bf16_f32 v53, v154, v155
	v_cvt_pk_bf16_f32 v54, v156, v157
	v_cvt_pk_bf16_f32 v55, v158, v159
	v_mfma_f32_32x32x16_bf16 v[64:79], v[48:51], v[44:47], v[64:79]
	ds_read_b128 v[40:43], v239 offset:20480
	s_waitcnt lgkmcnt(0)
	v_mfma_f32_32x32x16_bf16 v[16:31], v[56:59], v[44:47], v[16:31]
	ds_read_b128 v[48:51], v239 offset:24576
	v_mfma_f32_32x32x16_bf16 v[0:15], v[32:35], v[44:47], v[0:15]
	ds_read_b128 v[56:59], v239 offset:28672
	v_mfma_f32_32x32x16_bf16 v[80:95], v[36:39], v[52:55], v[80:95]
	v_mfma_f32_32x32x16_bf16 v[64:79], v[40:43], v[52:55], v[64:79]
	s_waitcnt lgkmcnt(0)
	v_mfma_f32_32x32x16_bf16 v[16:31], v[48:51], v[52:55], v[16:31]
	v_mfma_f32_32x32x16_bf16 v[0:15], v[56:59], v[52:55], v[0:15]
	s_waitcnt vmcnt(4) lgkmcnt(0)
	s_barrier
	s_add_u32 s68, s98, 0x18000
	s_addc_u32 s69, s99, 0
	s_add_i32 s49, 0x8000, s57
	s_mov_b32 m0, s49
	s_nop 0
	global_load_lds_dwordx4 v198, s[68:69]
	s_add_i32 m0, s49, 0x400
	s_nop 0
	global_load_lds_dwordx4 v194, s[68:69]
	s_add_u32 s44, s100, 0x80
	s_addc_u32 s45, s101, 0
	s_add_i32 s49, s58, 0x4000
	s_add_i32 m0, s49, 0xc000
	s_nop 0
	global_load_lds_dwordx4 v196, s[44:45]
	s_add_i32 m0, s49, 0xc400
	s_nop 0
	global_load_lds_dwordx4 v192, s[44:45]
	v_exp_f32_e32 v144, v112
	ds_read_b128 v[32:35], v205
	ds_read_b128 v[36:39], v205 offset:8192
	s_waitcnt lgkmcnt(0)
	v_mfma_f32_32x32x16_bf16 v[48:63], v[32:35], v[160:163], 0
	ds_read_b128 v[132:135], v211
	ds_read_b128 v[136:139], v211 offset:8192
	ds_read_b128 v[140:143], v212
	v_exp_f32_e32 v145, v113
	v_exp_f32_e32 v146, v114
	v_exp_f32_e32 v147, v115
	ds_read_b128 v[112:115], v212 offset:8192
	v_mfma_f32_32x32x16_bf16 v[32:47], v[36:39], v[160:163], 0
	v_exp_f32_e32 v148, v116
	v_exp_f32_e32 v149, v117
	v_exp_f32_e32 v150, v118
	v_exp_f32_e32 v151, v119
	s_waitcnt lgkmcnt(0)
	v_mfma_f32_32x32x16_bf16 v[48:63], v[132:135], v[164:167], v[48:63]
	ds_read_b128 v[116:119], v213
	v_exp_f32_e32 v152, v120
	v_exp_f32_e32 v153, v121
	v_exp_f32_e32 v154, v122
	v_exp_f32_e32 v155, v123
	v_mfma_f32_32x32x16_bf16 v[32:47], v[136:139], v[164:167], v[32:47]
	ds_read_b128 v[120:123], v213 offset:8192
	v_exp_f32_e32 v156, v124
	v_exp_f32_e32 v157, v125
	v_exp_f32_e32 v158, v126
	v_exp_f32_e32 v159, v127
	v_mfma_f32_32x32x16_bf16 v[48:63], v[140:143], v[168:171], v[48:63]
	ds_read_b128 v[124:127], v236 offset:32768
	v_exp_f32_e32 v136, v96
	v_exp_f32_e32 v137, v97
	v_exp_f32_e32 v138, v98
	v_exp_f32_e32 v139, v99
	v_mfma_f32_32x32x16_bf16 v[32:47], v[112:115], v[168:171], v[32:47]
	ds_read_b128 v[96:99], v236 offset:36864
	v_exp_f32_e32 v140, v100
	v_exp_f32_e32 v141, v101
	v_exp_f32_e32 v142, v102
	v_exp_f32_e32 v143, v103
	s_waitcnt lgkmcnt(0)
	v_mfma_f32_32x32x16_bf16 v[48:63], v[116:119], v[172:175], v[48:63]
	ds_read_b128 v[100:103], v236 offset:40960
	v_exp_f32_e32 v178, v104
	v_exp_f32_e32 v179, v105
	v_exp_f32_e32 v180, v106
	v_exp_f32_e32 v181, v107
	v_mfma_f32_32x32x16_bf16 v[32:47], v[120:123], v[172:175], v[32:47]
	ds_read_b128 v[104:107], v236 offset:45056
	v_exp_f32_e32 v182, v108
	v_exp_f32_e32 v183, v109
	v_exp_f32_e32 v184, v110
	v_exp_f32_e32 v185, v111
	v_cvt_pk_bf16_f32 v108, v144, v145
	v_cvt_pk_bf16_f32 v109, v146, v147
	v_cvt_pk_bf16_f32 v110, v148, v149
	v_cvt_pk_bf16_f32 v111, v150, v151
	s_nop 1
	v_mfma_f32_32x32x16_bf16 v[80:95], v[124:127], v[108:111], v[80:95]
	ds_read_b128 v[112:115], v237 offset:32768
	v_cvt_pk_bf16_f32 v116, v152, v153
	v_cvt_pk_bf16_f32 v117, v154, v155
	v_cvt_pk_bf16_f32 v118, v156, v157
	v_cvt_pk_bf16_f32 v119, v158, v159
	v_mfma_f32_32x32x16_bf16 v[64:79], v[96:99], v[108:111], v[64:79]
	ds_read_b128 v[120:123], v237 offset:36864
	v_pk_add_f32 v[126:127], v[150:151], v[146:147]
	v_pk_add_f32 v[124:125], v[148:149], v[144:145]
	s_waitcnt lgkmcnt(0)
	v_mfma_f32_32x32x16_bf16 v[16:31], v[100:103], v[108:111], v[16:31]
	ds_read_b128 v[132:135], v237 offset:40960
	v_add_f32_e64 v98, v154, v126
	v_add_f32_e64 v99, v155, v127
	v_add_f32_e64 v96, v152, v124
	v_add_f32_e64 v97, v153, v125
	v_pk_add_f32 v[98:99], v[158:159], v[98:99]
	v_pk_add_f32 v[96:97], v[156:157], v[96:97]
	v_mfma_f32_32x32x16_bf16 v[0:15], v[104:107], v[108:111], v[0:15]
	ds_read_b128 v[100:103], v237 offset:45056
	v_mfma_f32_32x32x16_bf16 v[80:95], v[112:115], v[116:119], v[80:95]
	ds_read_b128 v[104:107], v238 offset:32768
	v_cvt_pk_bf16_f32 v108, v136, v137
	v_cvt_pk_bf16_f32 v109, v138, v139
	v_cvt_pk_bf16_f32 v110, v140, v141
	v_cvt_pk_bf16_f32 v111, v142, v143
	v_mfma_f32_32x32x16_bf16 v[64:79], v[120:123], v[116:119], v[64:79]
	ds_read_b128 v[112:115], v238 offset:36864
	v_add_f32_e64 v98, v138, v98
	v_add_f32_e64 v99, v139, v99
	v_add_f32_e64 v96, v136, v96
	v_add_f32_e64 v97, v137, v97
	v_pk_add_f32 v[98:99], v[142:143], v[98:99]
	v_pk_add_f32 v[96:97], v[140:141], v[96:97]
	s_waitcnt lgkmcnt(0)
	v_mfma_f32_32x32x16_bf16 v[16:31], v[132:135], v[116:119], v[16:31]
	ds_read_b128 v[120:123], v238 offset:40960
	v_add_f32_e64 v98, v180, v98
	v_add_f32_e64 v99, v181, v99
	v_add_f32_e64 v96, v178, v96
	v_add_f32_e64 v97, v179, v97
	v_pk_add_f32 v[98:99], v[184:185], v[98:99]
	v_pk_add_f32 v[96:97], v[182:183], v[96:97]
	v_mfma_f32_32x32x16_bf16 v[0:15], v[100:103], v[116:119], v[0:15]
	ds_read_b128 v[124:127], v238 offset:45056
	v_mfma_f32_32x32x16_bf16 v[80:95], v[104:107], v[108:111], v[80:95]
	ds_read_b128 v[100:103], v239 offset:32768
	v_cvt_pk_bf16_f32 v116, v178, v179
	v_cvt_pk_bf16_f32 v117, v180, v181
	v_cvt_pk_bf16_f32 v118, v182, v183
	v_cvt_pk_bf16_f32 v119, v184, v185
	v_mfma_f32_32x32x16_bf16 v[64:79], v[112:115], v[108:111], v[64:79]
	ds_read_b128 v[104:107], v239 offset:36864
	s_waitcnt lgkmcnt(0)
	v_mfma_f32_32x32x16_bf16 v[16:31], v[120:123], v[108:111], v[16:31]
	ds_read_b128 v[112:115], v239 offset:40960
	v_mfma_f32_32x32x16_bf16 v[0:15], v[124:127], v[108:111], v[0:15]
	ds_read_b128 v[120:123], v239 offset:45056
	v_mfma_f32_32x32x16_bf16 v[80:95], v[100:103], v[116:119], v[80:95]
	v_mfma_f32_32x32x16_bf16 v[64:79], v[104:107], v[116:119], v[64:79]
	s_waitcnt lgkmcnt(0)
	v_mfma_f32_32x32x16_bf16 v[16:31], v[112:115], v[116:119], v[16:31]
	v_mfma_f32_32x32x16_bf16 v[0:15], v[120:123], v[116:119], v[0:15]
	s_waitcnt vmcnt(4) lgkmcnt(0)
	v_add_f32_e32 v100, v128, v129
	v_add_f32_e32 v101, v130, v131
	v_add_f32_e32 v100, v100, v101
	v_add_f32_e32 v96, v96, v97
	v_add_f32_e32 v97, v98, v99
	s_barrier
	v_add_f32_e32 v100, v177, v100
	v_add_f32_e32 v96, v96, v97
	v_add_f32_e32 v177, v100, v96
	s_add_u32 s98, s98, 0x30000
	s_addc_u32 s99, s99, 0
	s_add_u32 s100, s100, 0x100
	s_addc_u32 s101, s101, 0
	s_add_i32 s21, s21, 12
	s_addk_i32 s15, 0x300
	s_add_i32 s20, s20, 0x30000
	s_cmp_lt_u32 s21, 50
	s_cbranch_scc1 .Lst0_u6_loop
	s_cmp_lt_u32 s21, 60
	s_cbranch_scc1 .Lst0_single

.Lst1_u6_loop:
	s_add_i32 s49, s58, 0x4000
	s_mov_b32 m0, s49
	s_nop 0
	global_load_lds_dwordx4 v198, s[98:99]
	s_add_i32 m0, s49, 0x400
	s_nop 0
	global_load_lds_dwordx4 v194, s[98:99]
	s_add_i32 s49, s58, 0xc000
	s_add_i32 m0, s49, 0xc000
	s_nop 0
	global_load_lds_dwordx4 v196, s[100:101]
	s_add_i32 m0, s49, 0xc400
	s_nop 0
	global_load_lds_dwordx4 v192, s[100:101]
	ds_read_b128 v[140:143], v206 offset:49152
	ds_read_b128 v[148:151], v206 offset:53248
	ds_read_b128 v[152:155], v206 offset:57344
	ds_read_b128 v[156:159], v206 offset:61440
	s_waitcnt lgkmcnt(0)
	v_mfma_f32_32x32x16_bf16 v[80:95], v[140:143], v[144:147], v[80:95]
	ds_read_b128 v[140:143], v207 offset:49152
	v_mfma_f32_32x32x16_bf16 v[64:79], v[148:151], v[144:147], v[64:79]
	ds_read_b128 v[148:151], v207 offset:53248
	v_mfma_f32_32x32x16_bf16 v[16:31], v[152:155], v[144:147], v[16:31]
	ds_read_b128 v[152:155], v207 offset:57344
	v_mfma_f32_32x32x16_bf16 v[0:15], v[156:159], v[144:147], v[0:15]
	ds_read_b128 v[144:147], v207 offset:61440
	s_waitcnt lgkmcnt(0)
	v_mfma_f32_32x32x16_bf16 v[80:95], v[140:143], v[128:131], v[80:95]
	ds_read_b128 v[140:143], v208 offset:49152
	v_mfma_f32_32x32x16_bf16 v[64:79], v[148:151], v[128:131], v[64:79]
	ds_read_b128 v[148:151], v208 offset:53248
	v_mfma_f32_32x32x16_bf16 v[16:31], v[152:155], v[128:131], v[16:31]
	ds_read_b128 v[152:155], v208 offset:57344
	v_mfma_f32_32x32x16_bf16 v[0:15], v[144:147], v[128:131], v[0:15]
	ds_read_b128 v[128:131], v208 offset:61440
	s_waitcnt lgkmcnt(0)
	v_mfma_f32_32x32x16_bf16 v[80:95], v[140:143], v[132:135], v[80:95]
	ds_read_b128 v[140:143], v209 offset:49152
	v_mfma_f32_32x32x16_bf16 v[64:79], v[148:151], v[132:135], v[64:79]
	ds_read_b128 v[144:147], v209 offset:53248
	v_mfma_f32_32x32x16_bf16 v[16:31], v[152:155], v[132:135], v[16:31]
	ds_read_b128 v[148:151], v209 offset:57344
	v_mfma_f32_32x32x16_bf16 v[0:15], v[128:131], v[132:135], v[0:15]
	ds_read_b128 v[128:131], v209 offset:61440
	s_waitcnt lgkmcnt(0)
	v_mfma_f32_32x32x16_bf16 v[80:95], v[140:143], v[136:139], v[80:95]
	ds_read_b128 v[132:135], v205 offset:32768
	v_mfma_f32_32x32x16_bf16 v[64:79], v[144:147], v[136:139], v[64:79]
	ds_read_b128 v[140:143], v205 offset:40960
	v_mfma_f32_32x32x16_bf16 v[16:31], v[148:151], v[136:139], v[16:31]
	ds_read_b128 v[176:179], v211 offset:32768
	v_mfma_f32_32x32x16_bf16 v[0:15], v[128:131], v[136:139], v[0:15]
	ds_read_b128 v[182:185], v211 offset:40960
	s_waitcnt lgkmcnt(0)
	v_mfma_f32_32x32x16_bf16 v[144:159], v[132:135], v[160:163], 0
	ds_read_b128 v[186:189], v212 offset:32768
	v_exp_f32_e32 v220, v112
	v_exp_f32_e32 v221, v113
	v_exp_f32_e32 v222, v114
	v_exp_f32_e32 v223, v115
	v_mfma_f32_32x32x16_bf16 v[128:143], v[140:143], v[160:163], 0
	ds_read_b128 v[216:219], v212 offset:40960
	v_exp_f32_e32 v224, v116
	v_exp_f32_e32 v225, v117
	v_exp_f32_e32 v226, v118
	v_exp_f32_e32 v227, v119
	v_mfma_f32_32x32x16_bf16 v[144:159], v[176:179], v[164:167], v[144:159]
	ds_read_b128 v[116:119], v213 offset:32768
	v_exp_f32_e32 v228, v120
	v_exp_f32_e32 v229, v121
	v_exp_f32_e32 v230, v122
	v_exp_f32_e32 v231, v123
	v_cvt_pk_bf16_f32 v112, v220, v221
	v_cvt_pk_bf16_f32 v113, v222, v223
	v_cvt_pk_bf16_f32 v114, v224, v225
	v_cvt_pk_bf16_f32 v115, v226, v227
	v_pk_add_f32 v[122:123], v[226:227], v[222:223]
	v_pk_add_f32 v[120:121], v[224:225], v[220:221]
	v_mfma_f32_32x32x16_bf16 v[128:143], v[182:185], v[164:167], v[128:143]
	ds_read_b128 v[176:179], v213 offset:40960
	v_exp_f32_e32 v124, v124
	v_exp_f32_e32 v125, v125
	v_exp_f32_e32 v126, v126
	v_exp_f32_e32 v127, v127
	s_waitcnt lgkmcnt(0)
	v_mfma_f32_32x32x16_bf16 v[144:159], v[186:189], v[168:171], v[144:159]
	v_add_f32_e64 v122, v230, v122
	v_add_f32_e64 v123, v231, v123
	v_add_f32_e64 v120, v228, v120
	v_add_f32_e64 v121, v229, v121
	v_exp_f32_e32 v182, v96
	v_exp_f32_e32 v183, v97
	v_exp_f32_e32 v184, v98
	v_exp_f32_e32 v185, v99
	v_cvt_pk_bf16_f32 v96, v228, v229
	v_cvt_pk_bf16_f32 v97, v230, v231
	v_cvt_pk_bf16_f32 v98, v124, v125
	v_cvt_pk_bf16_f32 v99, v126, v127
	v_pk_add_f32 v[122:123], v[126:127], v[122:123]
	v_pk_add_f32 v[120:121], v[124:125], v[120:121]
	v_mfma_f32_32x32x16_bf16 v[128:143], v[216:219], v[168:171], v[128:143]
	v_exp_f32_e32 v124, v100
	v_exp_f32_e32 v125, v101
	v_exp_f32_e32 v126, v102
	v_exp_f32_e32 v127, v103
	v_mfma_f32_32x32x16_bf16 v[144:159], v[116:119], v[172:175], v[144:159]
	v_exp_f32_e32 v186, v104
	v_exp_f32_e32 v187, v105
	v_exp_f32_e32 v188, v106
	v_exp_f32_e32 v189, v107
	v_pk_add_f32 v[106:107], v[184:185], v[122:123]
	v_pk_add_f32 v[104:105], v[182:183], v[120:121]
	v_cvt_pk_bf16_f32 v100, v182, v183
	v_cvt_pk_bf16_f32 v101, v184, v185
	v_cvt_pk_bf16_f32 v102, v124, v125
	v_cvt_pk_bf16_f32 v103, v126, v127
	v_pk_add_f32 v[118:119], v[126:127], v[106:107]
	v_pk_add_f32 v[116:117], v[124:125], v[104:105]
	v_mfma_f32_32x32x16_bf16 v[128:143], v[176:179], v[172:175], v[128:143]
	v_exp_f32_e32 v120, v108
	v_exp_f32_e32 v121, v109
	v_exp_f32_e32 v122, v110
	v_exp_f32_e32 v123, v111
	v_pk_add_f32 v[110:111], v[188:189], v[118:119]
	v_pk_add_f32 v[108:109], v[186:187], v[116:117]
	v_cvt_pk_bf16_f32 v104, v186, v187
	v_cvt_pk_bf16_f32 v105, v188, v189
	v_cvt_pk_bf16_f32 v106, v120, v121
	v_cvt_pk_bf16_f32 v107, v122, v123
	v_pk_add_f32 v[178:179], v[122:123], v[110:111]
	v_pk_add_f32 v[176:177], v[120:121], v[108:109]
	s_waitcnt vmcnt(4) lgkmcnt(0)
	s_barrier
	s_add_u32 s70, s98, 0x18000
	s_addc_u32 s71, s99, 0
	s_add_i32 s68, 0x8000, s57
	s_mov_b32 m0, s68
	s_nop 0
	global_load_lds_dwordx4 v198, s[70:71]
	s_add_i32 m0, s68, 0x400
	s_nop 0
	global_load_lds_dwordx4 v194, s[70:71]
	s_add_u32 s2, s100, 0x80
	s_addc_u32 s3, s101, 0
	s_add_i32 s49, s58, 0
	s_add_i32 m0, s49, 0xc000
	s_nop 0
	global_load_lds_dwordx4 v196, s[2:3]
	s_add_i32 m0, s49, 0xc400
	s_nop 0
	global_load_lds_dwordx4 v192, s[2:3]
	ds_read_b128 v[108:111], v236
	ds_read_b128 v[116:119], v236 offset:4096
	ds_read_b128 v[120:123], v236 offset:8192
	ds_read_b128 v[124:127], v236 offset:12288
	s_waitcnt lgkmcnt(0)
	v_mfma_f32_32x32x16_bf16 v[80:95], v[108:111], v[112:115], v[80:95]
	ds_read_b128 v[108:111], v237
	v_mfma_f32_32x32x16_bf16 v[64:79], v[116:119], v[112:115], v[64:79]
	ds_read_b128 v[116:119], v237 offset:4096
	v_mfma_f32_32x32x16_bf16 v[16:31], v[120:123], v[112:115], v[16:31]
	ds_read_b128 v[120:123], v237 offset:8192
	v_mfma_f32_32x32x16_bf16 v[0:15], v[124:127], v[112:115], v[0:15]
	ds_read_b128 v[112:115], v237 offset:12288
	s_waitcnt lgkmcnt(0)
	v_mfma_f32_32x32x16_bf16 v[80:95], v[108:111], v[96:99], v[80:95]
	ds_read_b128 v[108:111], v238
	v_mfma_f32_32x32x16_bf16 v[64:79], v[116:119], v[96:99], v[64:79]
	ds_read_b128 v[116:119], v238 offset:4096
	v_mfma_f32_32x32x16_bf16 v[16:31], v[120:123], v[96:99], v[16:31]
	ds_read_b128 v[120:123], v238 offset:8192
	v_mfma_f32_32x32x16_bf16 v[0:15], v[112:115], v[96:99], v[0:15]
	ds_read_b128 v[96:99], v238 offset:12288
	s_waitcnt lgkmcnt(0)
	v_mfma_f32_32x32x16_bf16 v[80:95], v[108:111], v[100:103], v[80:95]
	ds_read_b128 v[108:111], v239
	v_mfma_f32_32x32x16_bf16 v[64:79], v[116:119], v[100:103], v[64:79]
	ds_read_b128 v[112:115], v239 offset:4096
	v_mfma_f32_32x32x16_bf16 v[16:31], v[120:123], v[100:103], v[16:31]
	ds_read_b128 v[116:119], v239 offset:8192
	v_mfma_f32_32x32x16_bf16 v[0:15], v[96:99], v[100:103], v[0:15]
	ds_read_b128 v[120:123], v239 offset:12288
	s_waitcnt lgkmcnt(0)
	v_mfma_f32_32x32x16_bf16 v[80:95], v[108:111], v[104:107], v[80:95]
	ds_read_b128 v[96:99], v205
	v_mfma_f32_32x32x16_bf16 v[64:79], v[112:115], v[104:107], v[64:79]
	ds_read_b128 v[100:103], v205 offset:8192
	v_mfma_f32_32x32x16_bf16 v[16:31], v[116:119], v[104:107], v[16:31]
	ds_read_b128 v[182:185], v211
	v_mfma_f32_32x32x16_bf16 v[0:15], v[120:123], v[104:107], v[0:15]
	ds_read_b128 v[186:189], v211 offset:8192
	s_waitcnt lgkmcnt(0)
	v_mfma_f32_32x32x16_bf16 v[112:127], v[96:99], v[160:163], 0
	ds_read_b128 v[216:219], v212
	v_exp_f32_e32 v224, v144
	v_exp_f32_e32 v225, v145
	v_exp_f32_e32 v226, v146
	v_exp_f32_e32 v227, v147
	ds_read_b128 v[220:223], v212 offset:8192
	v_mfma_f32_32x32x16_bf16 v[96:111], v[100:103], v[160:163], 0
	v_exp_f32_e32 v228, v148
	v_exp_f32_e32 v229, v149
	v_exp_f32_e32 v230, v150
	v_exp_f32_e32 v231, v151
	v_mfma_f32_32x32x16_bf16 v[112:127], v[182:185], v[164:167], v[112:127]
	ds_read_b128 v[148:151], v213
	v_exp_f32_e32 v232, v152
	v_exp_f32_e32 v233, v153
	v_exp_f32_e32 v234, v154
	v_exp_f32_e32 v235, v155
	v_cvt_pk_bf16_f32 v144, v224, v225
	v_cvt_pk_bf16_f32 v145, v226, v227
	v_cvt_pk_bf16_f32 v146, v228, v229
	v_cvt_pk_bf16_f32 v147, v230, v231
	v_pk_add_f32 v[154:155], v[230:231], v[226:227]
	v_pk_add_f32 v[152:153], v[228:229], v[224:225]
	v_mfma_f32_32x32x16_bf16 v[96:111], v[186:189], v[164:167], v[96:111]
	ds_read_b128 v[182:185], v213 offset:8192
	v_exp_f32_e32 v156, v156
	v_exp_f32_e32 v157, v157
	v_exp_f32_e32 v158, v158
	v_exp_f32_e32 v159, v159
	s_waitcnt lgkmcnt(0)
	v_mfma_f32_32x32x16_bf16 v[112:127], v[216:219], v[168:171], v[112:127]
	v_add_f32_e64 v154, v234, v154
	v_add_f32_e64 v155, v235, v155
	v_add_f32_e64 v152, v232, v152
	v_add_f32_e64 v153, v233, v153
	v_exp_f32_e32 v186, v128
	v_exp_f32_e32 v187, v129
	v_exp_f32_e32 v188, v130
	v_exp_f32_e32 v189, v131
	v_cvt_pk_bf16_f32 v128, v232, v233
	v_cvt_pk_bf16_f32 v129, v234, v235
	v_cvt_pk_bf16_f32 v130, v156, v157
	v_cvt_pk_bf16_f32 v131, v158, v159
	v_pk_add_f32 v[154:155], v[158:159], v[154:155]
	v_pk_add_f32 v[152:153], v[156:157], v[152:153]
	v_mfma_f32_32x32x16_bf16 v[96:111], v[220:223], v[168:171], v[96:111]
	v_exp_f32_e32 v156, v132
	v_exp_f32_e32 v157, v133
	v_exp_f32_e32 v158, v134
	v_exp_f32_e32 v159, v135
	v_mfma_f32_32x32x16_bf16 v[112:127], v[148:151], v[172:175], v[112:127]
	v_exp_f32_e32 v216, v136
	v_exp_f32_e32 v217, v137
	v_exp_f32_e32 v218, v138
	v_exp_f32_e32 v219, v139
	v_pk_add_f32 v[138:139], v[188:189], v[154:155]
	v_pk_add_f32 v[136:137], v[186:187], v[152:153]
	v_cvt_pk_bf16_f32 v132, v186, v187
	v_cvt_pk_bf16_f32 v133, v188, v189
	v_cvt_pk_bf16_f32 v134, v156, v157
	v_cvt_pk_bf16_f32 v135, v158, v159
	v_pk_add_f32 v[150:151], v[158:159], v[138:139]
	v_pk_add_f32 v[148:149], v[156:157], v[136:137]
	v_mfma_f32_32x32x16_bf16 v[96:111], v[182:185], v[172:175], v[96:111]
	v_exp_f32_e32 v152, v140
	v_exp_f32_e32 v153, v141
	v_exp_f32_e32 v154, v142
	v_exp_f32_e32 v155, v143
	v_pk_add_f32 v[142:143], v[218:219], v[150:151]
	v_pk_add_f32 v[140:141], v[216:217], v[148:149]
	v_cvt_pk_bf16_f32 v136, v216, v217
	v_cvt_pk_bf16_f32 v137, v218, v219
	v_cvt_pk_bf16_f32 v138, v152, v153
	v_cvt_pk_bf16_f32 v139, v154, v155
	v_pk_add_f32 v[142:143], v[154:155], v[142:143]
	v_pk_add_f32 v[140:141], v[152:153], v[140:141]
	s_waitcnt vmcnt(4) lgkmcnt(0)
	v_add_f32_e32 v148, v176, v177
	v_add_f32_e32 v149, v178, v179
	v_add_f32_e32 v148, v148, v149
	v_add_f32_e32 v140, v140, v141
	v_add_f32_e32 v141, v142, v143
	s_barrier
	v_add_f32_e32 v148, v180, v148
	v_add_f32_e32 v140, v140, v141
	v_add_f32_e32 v180, v148, v140
	s_add_u32 s98, s98, 0x30000
	s_addc_u32 s99, s99, 0
	s_add_u32 s100, s100, 0x100
	s_addc_u32 s101, s101, 0
	s_add_i32 s49, s58, 0
	s_mov_b32 m0, s49
	s_nop 0
	global_load_lds_dwordx4 v198, s[98:99]
	s_add_i32 m0, s49, 0x400
	s_nop 0
	global_load_lds_dwordx4 v194, s[98:99]
	s_add_i32 s49, s58, 0x4000
	s_add_i32 m0, s49, 0xc000
	s_nop 0
	global_load_lds_dwordx4 v196, s[100:101]
	s_add_i32 m0, s49, 0xc400
	s_nop 0
	global_load_lds_dwordx4 v192, s[100:101]
	ds_read_b128 v[140:143], v236 offset:16384
	ds_read_b128 v[148:151], v236 offset:20480
	ds_read_b128 v[152:155], v236 offset:24576
	ds_read_b128 v[156:159], v236 offset:28672
	s_waitcnt lgkmcnt(0)
	v_mfma_f32_32x32x16_bf16 v[80:95], v[140:143], v[144:147], v[80:95]
	ds_read_b128 v[140:143], v237 offset:16384
	v_mfma_f32_32x32x16_bf16 v[64:79], v[148:151], v[144:147], v[64:79]
	ds_read_b128 v[148:151], v237 offset:20480
	v_mfma_f32_32x32x16_bf16 v[16:31], v[152:155], v[144:147], v[16:31]
	ds_read_b128 v[152:155], v237 offset:24576
	v_mfma_f32_32x32x16_bf16 v[0:15], v[156:159], v[144:147], v[0:15]
	ds_read_b128 v[144:147], v237 offset:28672
	s_waitcnt lgkmcnt(0)
	v_mfma_f32_32x32x16_bf16 v[80:95], v[140:143], v[128:131], v[80:95]
	ds_read_b128 v[140:143], v238 offset:16384
	v_mfma_f32_32x32x16_bf16 v[64:79], v[148:151], v[128:131], v[64:79]
	ds_read_b128 v[148:151], v238 offset:20480
	v_mfma_f32_32x32x16_bf16 v[16:31], v[152:155], v[128:131], v[16:31]
	ds_read_b128 v[152:155], v238 offset:24576
	v_mfma_f32_32x32x16_bf16 v[0:15], v[144:147], v[128:131], v[0:15]
	ds_read_b128 v[128:131], v238 offset:28672
	s_waitcnt lgkmcnt(0)
	v_mfma_f32_32x32x16_bf16 v[80:95], v[140:143], v[132:135], v[80:95]
	ds_read_b128 v[140:143], v239 offset:16384
	v_mfma_f32_32x32x16_bf16 v[64:79], v[148:151], v[132:135], v[64:79]
	ds_read_b128 v[144:147], v239 offset:20480
	v_mfma_f32_32x32x16_bf16 v[16:31], v[152:155], v[132:135], v[16:31]
	ds_read_b128 v[148:151], v239 offset:24576
	v_mfma_f32_32x32x16_bf16 v[0:15], v[128:131], v[132:135], v[0:15]
	ds_read_b128 v[128:131], v239 offset:28672
	s_waitcnt lgkmcnt(0)
	v_mfma_f32_32x32x16_bf16 v[80:95], v[140:143], v[136:139], v[80:95]
	ds_read_b128 v[132:135], v205 offset:16384
	v_mfma_f32_32x32x16_bf16 v[64:79], v[144:147], v[136:139], v[64:79]
	ds_read_b128 v[140:143], v205 offset:24576
	v_mfma_f32_32x32x16_bf16 v[16:31], v[148:151], v[136:139], v[16:31]
	ds_read_b128 v[176:179], v211 offset:16384
	v_mfma_f32_32x32x16_bf16 v[0:15], v[128:131], v[136:139], v[0:15]
	ds_read_b128 v[182:185], v211 offset:24576
	s_waitcnt lgkmcnt(0)
	v_mfma_f32_32x32x16_bf16 v[144:159], v[132:135], v[160:163], 0
	ds_read_b128 v[186:189], v212 offset:16384
	v_exp_f32_e32 v220, v112
	v_exp_f32_e32 v221, v113
	v_exp_f32_e32 v222, v114
	v_exp_f32_e32 v223, v115
	v_mfma_f32_32x32x16_bf16 v[128:143], v[140:143], v[160:163], 0
	ds_read_b128 v[216:219], v212 offset:24576
	v_exp_f32_e32 v224, v116
	v_exp_f32_e32 v225, v117
	v_exp_f32_e32 v226, v118
	v_exp_f32_e32 v227, v119
	v_mfma_f32_32x32x16_bf16 v[144:159], v[176:179], v[164:167], v[144:159]
	ds_read_b128 v[116:119], v213 offset:16384
	v_exp_f32_e32 v228, v120
	v_exp_f32_e32 v229, v121
	v_exp_f32_e32 v230, v122
	v_exp_f32_e32 v231, v123
	v_cvt_pk_bf16_f32 v112, v220, v221
	v_cvt_pk_bf16_f32 v113, v222, v223
	v_cvt_pk_bf16_f32 v114, v224, v225
	v_cvt_pk_bf16_f32 v115, v226, v227
	v_pk_add_f32 v[122:123], v[226:227], v[222:223]
	v_pk_add_f32 v[120:121], v[224:225], v[220:221]
	v_mfma_f32_32x32x16_bf16 v[128:143], v[182:185], v[164:167], v[128:143]
	ds_read_b128 v[176:179], v213 offset:24576
	v_exp_f32_e32 v124, v124
	v_exp_f32_e32 v125, v125
	v_exp_f32_e32 v126, v126
	v_exp_f32_e32 v127, v127
	s_waitcnt lgkmcnt(0)
	v_mfma_f32_32x32x16_bf16 v[144:159], v[186:189], v[168:171], v[144:159]
	v_add_f32_e64 v122, v230, v122
	v_add_f32_e64 v123, v231, v123
	v_add_f32_e64 v120, v228, v120
	v_add_f32_e64 v121, v229, v121
	v_exp_f32_e32 v182, v96
	v_exp_f32_e32 v183, v97
	v_exp_f32_e32 v184, v98
	v_exp_f32_e32 v185, v99
	v_cvt_pk_bf16_f32 v96, v228, v229
	v_cvt_pk_bf16_f32 v97, v230, v231
	v_cvt_pk_bf16_f32 v98, v124, v125
	v_cvt_pk_bf16_f32 v99, v126, v127
	v_pk_add_f32 v[122:123], v[126:127], v[122:123]
	v_pk_add_f32 v[120:121], v[124:125], v[120:121]
	v_mfma_f32_32x32x16_bf16 v[128:143], v[216:219], v[168:171], v[128:143]
	v_exp_f32_e32 v124, v100
	v_exp_f32_e32 v125, v101
	v_exp_f32_e32 v126, v102
	v_exp_f32_e32 v127, v103
	v_mfma_f32_32x32x16_bf16 v[144:159], v[116:119], v[172:175], v[144:159]
	v_exp_f32_e32 v186, v104
	v_exp_f32_e32 v187, v105
	v_exp_f32_e32 v188, v106
	v_exp_f32_e32 v189, v107
	v_pk_add_f32 v[106:107], v[184:185], v[122:123]
	v_pk_add_f32 v[104:105], v[182:183], v[120:121]
	v_cvt_pk_bf16_f32 v100, v182, v183
	v_cvt_pk_bf16_f32 v101, v184, v185
	v_cvt_pk_bf16_f32 v102, v124, v125
	v_cvt_pk_bf16_f32 v103, v126, v127
	v_pk_add_f32 v[118:119], v[126:127], v[106:107]
	v_pk_add_f32 v[116:117], v[124:125], v[104:105]
	v_mfma_f32_32x32x16_bf16 v[128:143], v[176:179], v[172:175], v[128:143]
	v_exp_f32_e32 v120, v108
	v_exp_f32_e32 v121, v109
	v_exp_f32_e32 v122, v110
	v_exp_f32_e32 v123, v111
	v_pk_add_f32 v[110:111], v[188:189], v[118:119]
	v_pk_add_f32 v[108:109], v[186:187], v[116:117]
	v_cvt_pk_bf16_f32 v104, v186, v187
	v_cvt_pk_bf16_f32 v105, v188, v189
	v_cvt_pk_bf16_f32 v106, v120, v121
	v_cvt_pk_bf16_f32 v107, v122, v123
	v_pk_add_f32 v[178:179], v[122:123], v[110:111]
	v_pk_add_f32 v[176:177], v[120:121], v[108:109]
	s_waitcnt vmcnt(4) lgkmcnt(0)
	s_barrier
	s_add_u32 s70, s98, 0x18000
	s_addc_u32 s71, s99, 0
	s_add_i32 s68, 0x4000, s57
	s_mov_b32 m0, s68
	s_nop 0
	global_load_lds_dwordx4 v198, s[70:71]
	s_add_i32 m0, s68, 0x400
	s_nop 0
	global_load_lds_dwordx4 v194, s[70:71]
	s_add_u32 s2, s100, 0x80
	s_addc_u32 s3, s101, 0
	s_add_i32 s49, s58, 0x8000
	s_add_i32 m0, s49, 0xc000
	s_nop 0
	global_load_lds_dwordx4 v196, s[2:3]
	s_add_i32 m0, s49, 0xc400
	s_nop 0
	global_load_lds_dwordx4 v192, s[2:3]
	ds_read_b128 v[108:111], v236 offset:32768
	ds_read_b128 v[116:119], v236 offset:36864
	ds_read_b128 v[120:123], v236 offset:40960
	ds_read_b128 v[124:127], v236 offset:45056
	s_waitcnt lgkmcnt(0)
	v_mfma_f32_32x32x16_bf16 v[80:95], v[108:111], v[112:115], v[80:95]
	ds_read_b128 v[108:111], v237 offset:32768
	v_mfma_f32_32x32x16_bf16 v[64:79], v[116:119], v[112:115], v[64:79]
	ds_read_b128 v[116:119], v237 offset:36864
	v_mfma_f32_32x32x16_bf16 v[16:31], v[120:123], v[112:115], v[16:31]
	ds_read_b128 v[120:123], v237 offset:40960
	v_mfma_f32_32x32x16_bf16 v[0:15], v[124:127], v[112:115], v[0:15]
	ds_read_b128 v[112:115], v237 offset:45056
	s_waitcnt lgkmcnt(0)
	v_mfma_f32_32x32x16_bf16 v[80:95], v[108:111], v[96:99], v[80:95]
	ds_read_b128 v[108:111], v238 offset:32768
	v_mfma_f32_32x32x16_bf16 v[64:79], v[116:119], v[96:99], v[64:79]
	ds_read_b128 v[116:119], v238 offset:36864
	v_mfma_f32_32x32x16_bf16 v[16:31], v[120:123], v[96:99], v[16:31]
	ds_read_b128 v[120:123], v238 offset:40960
	v_mfma_f32_32x32x16_bf16 v[0:15], v[112:115], v[96:99], v[0:15]
	ds_read_b128 v[96:99], v238 offset:45056
	s_waitcnt lgkmcnt(0)
	v_mfma_f32_32x32x16_bf16 v[80:95], v[108:111], v[100:103], v[80:95]
	ds_read_b128 v[108:111], v239 offset:32768
	v_mfma_f32_32x32x16_bf16 v[64:79], v[116:119], v[100:103], v[64:79]
	ds_read_b128 v[112:115], v239 offset:36864
	v_mfma_f32_32x32x16_bf16 v[16:31], v[120:123], v[100:103], v[16:31]
	ds_read_b128 v[116:119], v239 offset:40960
	v_mfma_f32_32x32x16_bf16 v[0:15], v[96:99], v[100:103], v[0:15]
	ds_read_b128 v[120:123], v239 offset:45056
	s_waitcnt lgkmcnt(0)
	v_mfma_f32_32x32x16_bf16 v[80:95], v[108:111], v[104:107], v[80:95]
	ds_read_b128 v[96:99], v205 offset:32768
	v_mfma_f32_32x32x16_bf16 v[64:79], v[112:115], v[104:107], v[64:79]
	ds_read_b128 v[100:103], v205 offset:40960
	v_mfma_f32_32x32x16_bf16 v[16:31], v[116:119], v[104:107], v[16:31]
	ds_read_b128 v[182:185], v211 offset:32768
	v_mfma_f32_32x32x16_bf16 v[0:15], v[120:123], v[104:107], v[0:15]
	ds_read_b128 v[186:189], v211 offset:40960
	s_waitcnt lgkmcnt(0)
	v_mfma_f32_32x32x16_bf16 v[112:127], v[96:99], v[160:163], 0
	ds_read_b128 v[216:219], v212 offset:32768
	v_exp_f32_e32 v224, v144
	v_exp_f32_e32 v225, v145
	v_exp_f32_e32 v226, v146
	v_exp_f32_e32 v227, v147
	ds_read_b128 v[220:223], v212 offset:40960
	v_mfma_f32_32x32x16_bf16 v[96:111], v[100:103], v[160:163], 0
	v_exp_f32_e32 v228, v148
	v_exp_f32_e32 v229, v149
	v_exp_f32_e32 v230, v150
	v_exp_f32_e32 v231, v151
	v_mfma_f32_32x32x16_bf16 v[112:127], v[182:185], v[164:167], v[112:127]
	ds_read_b128 v[148:151], v213 offset:32768
	v_exp_f32_e32 v232, v152
	v_exp_f32_e32 v233, v153
	v_exp_f32_e32 v234, v154
	v_exp_f32_e32 v235, v155
	v_cvt_pk_bf16_f32 v144, v224, v225
	v_cvt_pk_bf16_f32 v145, v226, v227
	v_cvt_pk_bf16_f32 v146, v228, v229
	v_cvt_pk_bf16_f32 v147, v230, v231
	v_pk_add_f32 v[154:155], v[230:231], v[226:227]
	v_pk_add_f32 v[152:153], v[228:229], v[224:225]
	v_mfma_f32_32x32x16_bf16 v[96:111], v[186:189], v[164:167], v[96:111]
	ds_read_b128 v[182:185], v213 offset:40960
	v_exp_f32_e32 v156, v156
	v_exp_f32_e32 v157, v157
	v_exp_f32_e32 v158, v158
	v_exp_f32_e32 v159, v159
	s_waitcnt lgkmcnt(0)
	v_mfma_f32_32x32x16_bf16 v[112:127], v[216:219], v[168:171], v[112:127]
	v_add_f32_e64 v154, v234, v154
	v_add_f32_e64 v155, v235, v155
	v_add_f32_e64 v152, v232, v152
	v_add_f32_e64 v153, v233, v153
	v_exp_f32_e32 v186, v128
	v_exp_f32_e32 v187, v129
	v_exp_f32_e32 v188, v130
	v_exp_f32_e32 v189, v131
	v_cvt_pk_bf16_f32 v128, v232, v233
	v_cvt_pk_bf16_f32 v129, v234, v235
	v_cvt_pk_bf16_f32 v130, v156, v157
	v_cvt_pk_bf16_f32 v131, v158, v159
	v_pk_add_f32 v[154:155], v[158:159], v[154:155]
	v_pk_add_f32 v[152:153], v[156:157], v[152:153]
	v_mfma_f32_32x32x16_bf16 v[96:111], v[220:223], v[168:171], v[96:111]
	v_exp_f32_e32 v156, v132
	v_exp_f32_e32 v157, v133
	v_exp_f32_e32 v158, v134
	v_exp_f32_e32 v159, v135
	v_mfma_f32_32x32x16_bf16 v[112:127], v[148:151], v[172:175], v[112:127]
	v_exp_f32_e32 v216, v136
	v_exp_f32_e32 v217, v137
	v_exp_f32_e32 v218, v138
	v_exp_f32_e32 v219, v139
	v_pk_add_f32 v[138:139], v[188:189], v[154:155]
	v_pk_add_f32 v[136:137], v[186:187], v[152:153]
	v_cvt_pk_bf16_f32 v132, v186, v187
	v_cvt_pk_bf16_f32 v133, v188, v189
	v_cvt_pk_bf16_f32 v134, v156, v157
	v_cvt_pk_bf16_f32 v135, v158, v159
	v_pk_add_f32 v[150:151], v[158:159], v[138:139]
	v_pk_add_f32 v[148:149], v[156:157], v[136:137]
	v_mfma_f32_32x32x16_bf16 v[96:111], v[182:185], v[172:175], v[96:111]
	v_exp_f32_e32 v152, v140
	v_exp_f32_e32 v153, v141
	v_exp_f32_e32 v154, v142
	v_exp_f32_e32 v155, v143
	v_pk_add_f32 v[142:143], v[218:219], v[150:151]
	v_pk_add_f32 v[140:141], v[216:217], v[148:149]
	v_cvt_pk_bf16_f32 v136, v216, v217
	v_cvt_pk_bf16_f32 v137, v218, v219
	v_cvt_pk_bf16_f32 v138, v152, v153
	v_cvt_pk_bf16_f32 v139, v154, v155
	v_pk_add_f32 v[142:143], v[154:155], v[142:143]
	v_pk_add_f32 v[140:141], v[152:153], v[140:141]
	s_waitcnt vmcnt(4) lgkmcnt(0)
	v_add_f32_e32 v148, v176, v177
	v_add_f32_e32 v149, v178, v179
	v_add_f32_e32 v148, v148, v149
	v_add_f32_e32 v140, v140, v141
	v_add_f32_e32 v141, v142, v143
	s_barrier
	v_add_f32_e32 v148, v180, v148
	v_add_f32_e32 v140, v140, v141
	v_add_f32_e32 v180, v148, v140
	s_add_u32 s98, s98, 0x30000
	s_addc_u32 s99, s99, 0
	s_add_u32 s100, s100, 0x100
	s_addc_u32 s101, s101, 0
	s_add_i32 s49, s58, 0x8000
	s_mov_b32 m0, s49
	s_nop 0
	global_load_lds_dwordx4 v198, s[98:99]
	s_add_i32 m0, s49, 0x400
	s_nop 0
	global_load_lds_dwordx4 v194, s[98:99]
	s_add_i32 s49, s58, 0xc000
	s_add_i32 m0, s49, 0xc000
	s_nop 0
	global_load_lds_dwordx4 v196, s[100:101]
	s_add_i32 m0, s49, 0xc400
	s_nop 0
	global_load_lds_dwordx4 v192, s[100:101]
	ds_read_b128 v[140:143], v206 offset:49152
	ds_read_b128 v[148:151], v206 offset:53248
	ds_read_b128 v[152:155], v206 offset:57344
	ds_read_b128 v[156:159], v206 offset:61440
	s_waitcnt lgkmcnt(0)
	v_mfma_f32_32x32x16_bf16 v[80:95], v[140:143], v[144:147], v[80:95]
	ds_read_b128 v[140:143], v207 offset:49152
	v_mfma_f32_32x32x16_bf16 v[64:79], v[148:151], v[144:147], v[64:79]
	ds_read_b128 v[148:151], v207 offset:53248
	v_mfma_f32_32x32x16_bf16 v[16:31], v[152:155], v[144:147], v[16:31]
	ds_read_b128 v[152:155], v207 offset:57344
	v_mfma_f32_32x32x16_bf16 v[0:15], v[156:159], v[144:147], v[0:15]
	ds_read_b128 v[144:147], v207 offset:61440
	s_waitcnt lgkmcnt(0)
	v_mfma_f32_32x32x16_bf16 v[80:95], v[140:143], v[128:131], v[80:95]
	ds_read_b128 v[140:143], v208 offset:49152
	v_mfma_f32_32x32x16_bf16 v[64:79], v[148:151], v[128:131], v[64:79]
	ds_read_b128 v[148:151], v208 offset:53248
	v_mfma_f32_32x32x16_bf16 v[16:31], v[152:155], v[128:131], v[16:31]
	ds_read_b128 v[152:155], v208 offset:57344
	v_mfma_f32_32x32x16_bf16 v[0:15], v[144:147], v[128:131], v[0:15]
	ds_read_b128 v[128:131], v208 offset:61440
	s_waitcnt lgkmcnt(0)
	v_mfma_f32_32x32x16_bf16 v[80:95], v[140:143], v[132:135], v[80:95]
	ds_read_b128 v[140:143], v209 offset:49152
	v_mfma_f32_32x32x16_bf16 v[64:79], v[148:151], v[132:135], v[64:79]
	ds_read_b128 v[144:147], v209 offset:53248
	v_mfma_f32_32x32x16_bf16 v[16:31], v[152:155], v[132:135], v[16:31]
	ds_read_b128 v[148:151], v209 offset:57344
	v_mfma_f32_32x32x16_bf16 v[0:15], v[128:131], v[132:135], v[0:15]
	ds_read_b128 v[128:131], v209 offset:61440
	s_waitcnt lgkmcnt(0)
	v_mfma_f32_32x32x16_bf16 v[80:95], v[140:143], v[136:139], v[80:95]
	ds_read_b128 v[132:135], v205
	v_mfma_f32_32x32x16_bf16 v[64:79], v[144:147], v[136:139], v[64:79]
	ds_read_b128 v[140:143], v205 offset:8192
	v_mfma_f32_32x32x16_bf16 v[16:31], v[148:151], v[136:139], v[16:31]
	ds_read_b128 v[176:179], v211
	v_mfma_f32_32x32x16_bf16 v[0:15], v[128:131], v[136:139], v[0:15]
	ds_read_b128 v[182:185], v211 offset:8192
	s_waitcnt lgkmcnt(0)
	v_mfma_f32_32x32x16_bf16 v[144:159], v[132:135], v[160:163], 0
	ds_read_b128 v[186:189], v212
	v_exp_f32_e32 v220, v112
	v_exp_f32_e32 v221, v113
	v_exp_f32_e32 v222, v114
	v_exp_f32_e32 v223, v115
	v_mfma_f32_32x32x16_bf16 v[128:143], v[140:143], v[160:163], 0
	ds_read_b128 v[216:219], v212 offset:8192
	v_exp_f32_e32 v224, v116
	v_exp_f32_e32 v225, v117
	v_exp_f32_e32 v226, v118
	v_exp_f32_e32 v227, v119
	v_mfma_f32_32x32x16_bf16 v[144:159], v[176:179], v[164:167], v[144:159]
	ds_read_b128 v[116:119], v213
	v_exp_f32_e32 v228, v120
	v_exp_f32_e32 v229, v121
	v_exp_f32_e32 v230, v122
	v_exp_f32_e32 v231, v123
	v_cvt_pk_bf16_f32 v112, v220, v221
	v_cvt_pk_bf16_f32 v113, v222, v223
	v_cvt_pk_bf16_f32 v114, v224, v225
	v_cvt_pk_bf16_f32 v115, v226, v227
	v_pk_add_f32 v[122:123], v[226:227], v[222:223]
	v_pk_add_f32 v[120:121], v[224:225], v[220:221]
	v_mfma_f32_32x32x16_bf16 v[128:143], v[182:185], v[164:167], v[128:143]
	ds_read_b128 v[176:179], v213 offset:8192
	v_exp_f32_e32 v124, v124
	v_exp_f32_e32 v125, v125
	v_exp_f32_e32 v126, v126
	v_exp_f32_e32 v127, v127
	s_waitcnt lgkmcnt(0)
	v_mfma_f32_32x32x16_bf16 v[144:159], v[186:189], v[168:171], v[144:159]
	v_add_f32_e64 v122, v230, v122
	v_add_f32_e64 v123, v231, v123
	v_add_f32_e64 v120, v228, v120
	v_add_f32_e64 v121, v229, v121
	v_exp_f32_e32 v182, v96
	v_exp_f32_e32 v183, v97
	v_exp_f32_e32 v184, v98
	v_exp_f32_e32 v185, v99
	v_cvt_pk_bf16_f32 v96, v228, v229
	v_cvt_pk_bf16_f32 v97, v230, v231
	v_cvt_pk_bf16_f32 v98, v124, v125
	v_cvt_pk_bf16_f32 v99, v126, v127
	v_pk_add_f32 v[122:123], v[126:127], v[122:123]
	v_pk_add_f32 v[120:121], v[124:125], v[120:121]
	v_mfma_f32_32x32x16_bf16 v[128:143], v[216:219], v[168:171], v[128:143]
	v_exp_f32_e32 v124, v100
	v_exp_f32_e32 v125, v101
	v_exp_f32_e32 v126, v102
	v_exp_f32_e32 v127, v103
	v_mfma_f32_32x32x16_bf16 v[144:159], v[116:119], v[172:175], v[144:159]
	v_exp_f32_e32 v186, v104
	v_exp_f32_e32 v187, v105
	v_exp_f32_e32 v188, v106
	v_exp_f32_e32 v189, v107
	v_pk_add_f32 v[106:107], v[184:185], v[122:123]
	v_pk_add_f32 v[104:105], v[182:183], v[120:121]
	v_cvt_pk_bf16_f32 v100, v182, v183
	v_cvt_pk_bf16_f32 v101, v184, v185
	v_cvt_pk_bf16_f32 v102, v124, v125
	v_cvt_pk_bf16_f32 v103, v126, v127
	v_pk_add_f32 v[118:119], v[126:127], v[106:107]
	v_pk_add_f32 v[116:117], v[124:125], v[104:105]
	v_mfma_f32_32x32x16_bf16 v[128:143], v[176:179], v[172:175], v[128:143]
	v_exp_f32_e32 v120, v108
	v_exp_f32_e32 v121, v109
	v_exp_f32_e32 v122, v110
	v_exp_f32_e32 v123, v111
	v_pk_add_f32 v[110:111], v[188:189], v[118:119]
	v_pk_add_f32 v[108:109], v[186:187], v[116:117]
	v_cvt_pk_bf16_f32 v104, v186, v187
	v_cvt_pk_bf16_f32 v105, v188, v189
	v_cvt_pk_bf16_f32 v106, v120, v121
	v_cvt_pk_bf16_f32 v107, v122, v123
	v_pk_add_f32 v[178:179], v[122:123], v[110:111]
	v_pk_add_f32 v[176:177], v[120:121], v[108:109]
	s_waitcnt vmcnt(4) lgkmcnt(0)
	s_barrier
	s_add_u32 s70, s98, 0x18000
	s_addc_u32 s71, s99, 0
	s_add_i32 s68, 0, s57
	s_mov_b32 m0, s68
	s_nop 0
	global_load_lds_dwordx4 v198, s[70:71]
	s_add_i32 m0, s68, 0x400
	s_nop 0
	global_load_lds_dwordx4 v194, s[70:71]
	s_add_u32 s2, s100, 0x80
	s_addc_u32 s3, s101, 0
	s_add_i32 s49, s58, 0
	s_add_i32 m0, s49, 0xc000
	s_nop 0
	global_load_lds_dwordx4 v196, s[2:3]
	s_add_i32 m0, s49, 0xc400
	s_nop 0
	global_load_lds_dwordx4 v192, s[2:3]
	ds_read_b128 v[108:111], v236
	ds_read_b128 v[116:119], v236 offset:4096
	ds_read_b128 v[120:123], v236 offset:8192
	ds_read_b128 v[124:127], v236 offset:12288
	s_waitcnt lgkmcnt(0)
	v_mfma_f32_32x32x16_bf16 v[80:95], v[108:111], v[112:115], v[80:95]
	ds_read_b128 v[108:111], v237
	v_mfma_f32_32x32x16_bf16 v[64:79], v[116:119], v[112:115], v[64:79]
	ds_read_b128 v[116:119], v237 offset:4096
	v_mfma_f32_32x32x16_bf16 v[16:31], v[120:123], v[112:115], v[16:31]
	ds_read_b128 v[120:123], v237 offset:8192
	v_mfma_f32_32x32x16_bf16 v[0:15], v[124:127], v[112:115], v[0:15]
	ds_read_b128 v[112:115], v237 offset:12288
	s_waitcnt lgkmcnt(0)
	v_mfma_f32_32x32x16_bf16 v[80:95], v[108:111], v[96:99], v[80:95]
	ds_read_b128 v[108:111], v238
	v_mfma_f32_32x32x16_bf16 v[64:79], v[116:119], v[96:99], v[64:79]
	ds_read_b128 v[116:119], v238 offset:4096
	v_mfma_f32_32x32x16_bf16 v[16:31], v[120:123], v[96:99], v[16:31]
	ds_read_b128 v[120:123], v238 offset:8192
	v_mfma_f32_32x32x16_bf16 v[0:15], v[112:115], v[96:99], v[0:15]
	ds_read_b128 v[96:99], v238 offset:12288
	s_waitcnt lgkmcnt(0)
	v_mfma_f32_32x32x16_bf16 v[80:95], v[108:111], v[100:103], v[80:95]
	ds_read_b128 v[108:111], v239
	v_mfma_f32_32x32x16_bf16 v[64:79], v[116:119], v[100:103], v[64:79]
	ds_read_b128 v[112:115], v239 offset:4096
	v_mfma_f32_32x32x16_bf16 v[16:31], v[120:123], v[100:103], v[16:31]
	ds_read_b128 v[116:119], v239 offset:8192
	v_mfma_f32_32x32x16_bf16 v[0:15], v[96:99], v[100:103], v[0:15]
	ds_read_b128 v[120:123], v239 offset:12288
	s_waitcnt lgkmcnt(0)
	v_mfma_f32_32x32x16_bf16 v[80:95], v[108:111], v[104:107], v[80:95]
	ds_read_b128 v[96:99], v205 offset:16384
	v_mfma_f32_32x32x16_bf16 v[64:79], v[112:115], v[104:107], v[64:79]
	ds_read_b128 v[100:103], v205 offset:24576
	v_mfma_f32_32x32x16_bf16 v[16:31], v[116:119], v[104:107], v[16:31]
	ds_read_b128 v[182:185], v211 offset:16384
	v_mfma_f32_32x32x16_bf16 v[0:15], v[120:123], v[104:107], v[0:15]
	ds_read_b128 v[186:189], v211 offset:24576
	s_waitcnt lgkmcnt(0)
	v_mfma_f32_32x32x16_bf16 v[112:127], v[96:99], v[160:163], 0
	ds_read_b128 v[216:219], v212 offset:16384
	v_exp_f32_e32 v224, v144
	v_exp_f32_e32 v225, v145
	v_exp_f32_e32 v226, v146
	v_exp_f32_e32 v227, v147
	ds_read_b128 v[220:223], v212 offset:24576
	v_mfma_f32_32x32x16_bf16 v[96:111], v[100:103], v[160:163], 0
	v_exp_f32_e32 v228, v148
	v_exp_f32_e32 v229, v149
	v_exp_f32_e32 v230, v150
	v_exp_f32_e32 v231, v151
	v_mfma_f32_32x32x16_bf16 v[112:127], v[182:185], v[164:167], v[112:127]
	ds_read_b128 v[148:151], v213 offset:16384
	v_exp_f32_e32 v232, v152
	v_exp_f32_e32 v233, v153
	v_exp_f32_e32 v234, v154
	v_exp_f32_e32 v235, v155
	v_cvt_pk_bf16_f32 v144, v224, v225
	v_cvt_pk_bf16_f32 v145, v226, v227
	v_cvt_pk_bf16_f32 v146, v228, v229
	v_cvt_pk_bf16_f32 v147, v230, v231
	v_pk_add_f32 v[154:155], v[230:231], v[226:227]
	v_pk_add_f32 v[152:153], v[228:229], v[224:225]
	v_mfma_f32_32x32x16_bf16 v[96:111], v[186:189], v[164:167], v[96:111]
	ds_read_b128 v[182:185], v213 offset:24576
	v_exp_f32_e32 v156, v156
	v_exp_f32_e32 v157, v157
	v_exp_f32_e32 v158, v158
	v_exp_f32_e32 v159, v159
	s_waitcnt lgkmcnt(0)
	v_mfma_f32_32x32x16_bf16 v[112:127], v[216:219], v[168:171], v[112:127]
	v_add_f32_e64 v154, v234, v154
	v_add_f32_e64 v155, v235, v155
	v_add_f32_e64 v152, v232, v152
	v_add_f32_e64 v153, v233, v153
	v_exp_f32_e32 v186, v128
	v_exp_f32_e32 v187, v129
	v_exp_f32_e32 v188, v130
	v_exp_f32_e32 v189, v131
	v_cvt_pk_bf16_f32 v128, v232, v233
	v_cvt_pk_bf16_f32 v129, v234, v235
	v_cvt_pk_bf16_f32 v130, v156, v157
	v_cvt_pk_bf16_f32 v131, v158, v159
	v_pk_add_f32 v[154:155], v[158:159], v[154:155]
	v_pk_add_f32 v[152:153], v[156:157], v[152:153]
	v_mfma_f32_32x32x16_bf16 v[96:111], v[220:223], v[168:171], v[96:111]
	v_exp_f32_e32 v156, v132
	v_exp_f32_e32 v157, v133
	v_exp_f32_e32 v158, v134
	v_exp_f32_e32 v159, v135
	v_mfma_f32_32x32x16_bf16 v[112:127], v[148:151], v[172:175], v[112:127]
	v_exp_f32_e32 v216, v136
	v_exp_f32_e32 v217, v137
	v_exp_f32_e32 v218, v138
	v_exp_f32_e32 v219, v139
	v_pk_add_f32 v[138:139], v[188:189], v[154:155]
	v_pk_add_f32 v[136:137], v[186:187], v[152:153]
	v_cvt_pk_bf16_f32 v132, v186, v187
	v_cvt_pk_bf16_f32 v133, v188, v189
	v_cvt_pk_bf16_f32 v134, v156, v157
	v_cvt_pk_bf16_f32 v135, v158, v159
	v_pk_add_f32 v[150:151], v[158:159], v[138:139]
	v_pk_add_f32 v[148:149], v[156:157], v[136:137]
	v_mfma_f32_32x32x16_bf16 v[96:111], v[182:185], v[172:175], v[96:111]
	v_exp_f32_e32 v152, v140
	v_exp_f32_e32 v153, v141
	v_exp_f32_e32 v154, v142
	v_exp_f32_e32 v155, v143
	v_pk_add_f32 v[142:143], v[218:219], v[150:151]
	v_pk_add_f32 v[140:141], v[216:217], v[148:149]
	v_cvt_pk_bf16_f32 v136, v216, v217
	v_cvt_pk_bf16_f32 v137, v218, v219
	v_cvt_pk_bf16_f32 v138, v152, v153
	v_cvt_pk_bf16_f32 v139, v154, v155
	v_pk_add_f32 v[142:143], v[154:155], v[142:143]
	v_pk_add_f32 v[140:141], v[152:153], v[140:141]
	s_waitcnt vmcnt(4) lgkmcnt(0)
	v_add_f32_e32 v148, v176, v177
	v_add_f32_e32 v149, v178, v179
	v_add_f32_e32 v148, v148, v149
	v_add_f32_e32 v140, v140, v141
	v_add_f32_e32 v141, v142, v143
	s_barrier
	v_add_f32_e32 v148, v180, v148
	v_add_f32_e32 v140, v140, v141
	v_add_f32_e32 v180, v148, v140
	s_add_u32 s98, s98, 0x30000
	s_addc_u32 s99, s99, 0
	s_add_u32 s100, s100, 0x100
	s_addc_u32 s101, s101, 0
	s_add_i32 s49, s58, 0x4000
	s_mov_b32 m0, s49
	s_nop 0
	global_load_lds_dwordx4 v198, s[98:99]
	s_add_i32 m0, s49, 0x400
	s_nop 0
	global_load_lds_dwordx4 v194, s[98:99]
	s_add_i32 s49, s58, 0x4000
	s_add_i32 m0, s49, 0xc000
	s_nop 0
	global_load_lds_dwordx4 v196, s[100:101]
	s_add_i32 m0, s49, 0xc400
	s_nop 0
	global_load_lds_dwordx4 v192, s[100:101]
	ds_read_b128 v[140:143], v236 offset:16384
	ds_read_b128 v[148:151], v236 offset:20480
	ds_read_b128 v[152:155], v236 offset:24576
	ds_read_b128 v[156:159], v236 offset:28672
	s_waitcnt lgkmcnt(0)
	v_mfma_f32_32x32x16_bf16 v[80:95], v[140:143], v[144:147], v[80:95]
	ds_read_b128 v[140:143], v237 offset:16384
	v_mfma_f32_32x32x16_bf16 v[64:79], v[148:151], v[144:147], v[64:79]
	ds_read_b128 v[148:151], v237 offset:20480
	v_mfma_f32_32x32x16_bf16 v[16:31], v[152:155], v[144:147], v[16:31]
	ds_read_b128 v[152:155], v237 offset:24576
	v_mfma_f32_32x32x16_bf16 v[0:15], v[156:159], v[144:147], v[0:15]
	ds_read_b128 v[144:147], v237 offset:28672
	s_waitcnt lgkmcnt(0)
	v_mfma_f32_32x32x16_bf16 v[80:95], v[140:143], v[128:131], v[80:95]
	ds_read_b128 v[140:143], v238 offset:16384
	v_mfma_f32_32x32x16_bf16 v[64:79], v[148:151], v[128:131], v[64:79]
	ds_read_b128 v[148:151], v238 offset:20480
	v_mfma_f32_32x32x16_bf16 v[16:31], v[152:155], v[128:131], v[16:31]
	ds_read_b128 v[152:155], v238 offset:24576
	v_mfma_f32_32x32x16_bf16 v[0:15], v[144:147], v[128:131], v[0:15]
	ds_read_b128 v[128:131], v238 offset:28672
	s_waitcnt lgkmcnt(0)
	v_mfma_f32_32x32x16_bf16 v[80:95], v[140:143], v[132:135], v[80:95]
	ds_read_b128 v[140:143], v239 offset:16384
	v_mfma_f32_32x32x16_bf16 v[64:79], v[148:151], v[132:135], v[64:79]
	ds_read_b128 v[144:147], v239 offset:20480
	v_mfma_f32_32x32x16_bf16 v[16:31], v[152:155], v[132:135], v[16:31]
	ds_read_b128 v[148:151], v239 offset:24576
	v_mfma_f32_32x32x16_bf16 v[0:15], v[128:131], v[132:135], v[0:15]
	ds_read_b128 v[128:131], v239 offset:28672
	s_waitcnt lgkmcnt(0)
	v_mfma_f32_32x32x16_bf16 v[80:95], v[140:143], v[136:139], v[80:95]
	ds_read_b128 v[132:135], v205 offset:32768
	v_mfma_f32_32x32x16_bf16 v[64:79], v[144:147], v[136:139], v[64:79]
	ds_read_b128 v[140:143], v205 offset:40960
	v_mfma_f32_32x32x16_bf16 v[16:31], v[148:151], v[136:139], v[16:31]
	ds_read_b128 v[176:179], v211 offset:32768
	v_mfma_f32_32x32x16_bf16 v[0:15], v[128:131], v[136:139], v[0:15]
	ds_read_b128 v[182:185], v211 offset:40960
	s_waitcnt lgkmcnt(0)
	v_mfma_f32_32x32x16_bf16 v[144:159], v[132:135], v[160:163], 0
	ds_read_b128 v[186:189], v212 offset:32768
	v_exp_f32_e32 v220, v112
	v_exp_f32_e32 v221, v113
	v_exp_f32_e32 v222, v114
	v_exp_f32_e32 v223, v115
	v_mfma_f32_32x32x16_bf16 v[128:143], v[140:143], v[160:163], 0
	ds_read_b128 v[216:219], v212 offset:40960
	v_exp_f32_e32 v224, v116
	v_exp_f32_e32 v225, v117
	v_exp_f32_e32 v226, v118
	v_exp_f32_e32 v227, v119
	v_mfma_f32_32x32x16_bf16 v[144:159], v[176:179], v[164:167], v[144:159]
	ds_read_b128 v[116:119], v213 offset:32768
	v_exp_f32_e32 v228, v120
	v_exp_f32_e32 v229, v121
	v_exp_f32_e32 v230, v122
	v_exp_f32_e32 v231, v123
	v_cvt_pk_bf16_f32 v112, v220, v221
	v_cvt_pk_bf16_f32 v113, v222, v223
	v_cvt_pk_bf16_f32 v114, v224, v225
	v_cvt_pk_bf16_f32 v115, v226, v227
	v_pk_add_f32 v[122:123], v[226:227], v[222:223]
	v_pk_add_f32 v[120:121], v[224:225], v[220:221]
	v_mfma_f32_32x32x16_bf16 v[128:143], v[182:185], v[164:167], v[128:143]
	ds_read_b128 v[176:179], v213 offset:40960
	v_exp_f32_e32 v124, v124
	v_exp_f32_e32 v125, v125
	v_exp_f32_e32 v126, v126
	v_exp_f32_e32 v127, v127
	s_waitcnt lgkmcnt(0)
	v_mfma_f32_32x32x16_bf16 v[144:159], v[186:189], v[168:171], v[144:159]
	v_add_f32_e64 v122, v230, v122
	v_add_f32_e64 v123, v231, v123
	v_add_f32_e64 v120, v228, v120
	v_add_f32_e64 v121, v229, v121
	v_exp_f32_e32 v182, v96
	v_exp_f32_e32 v183, v97
	v_exp_f32_e32 v184, v98
	v_exp_f32_e32 v185, v99
	v_cvt_pk_bf16_f32 v96, v228, v229
	v_cvt_pk_bf16_f32 v97, v230, v231
	v_cvt_pk_bf16_f32 v98, v124, v125
	v_cvt_pk_bf16_f32 v99, v126, v127
	v_pk_add_f32 v[122:123], v[126:127], v[122:123]
	v_pk_add_f32 v[120:121], v[124:125], v[120:121]
	v_mfma_f32_32x32x16_bf16 v[128:143], v[216:219], v[168:171], v[128:143]
	v_exp_f32_e32 v124, v100
	v_exp_f32_e32 v125, v101
	v_exp_f32_e32 v126, v102
	v_exp_f32_e32 v127, v103
	v_mfma_f32_32x32x16_bf16 v[144:159], v[116:119], v[172:175], v[144:159]
	v_exp_f32_e32 v186, v104
	v_exp_f32_e32 v187, v105
	v_exp_f32_e32 v188, v106
	v_exp_f32_e32 v189, v107
	v_pk_add_f32 v[106:107], v[184:185], v[122:123]
	v_pk_add_f32 v[104:105], v[182:183], v[120:121]
	v_cvt_pk_bf16_f32 v100, v182, v183
	v_cvt_pk_bf16_f32 v101, v184, v185
	v_cvt_pk_bf16_f32 v102, v124, v125
	v_cvt_pk_bf16_f32 v103, v126, v127
	v_pk_add_f32 v[118:119], v[126:127], v[106:107]
	v_pk_add_f32 v[116:117], v[124:125], v[104:105]
	v_mfma_f32_32x32x16_bf16 v[128:143], v[176:179], v[172:175], v[128:143]
	v_exp_f32_e32 v120, v108
	v_exp_f32_e32 v121, v109
	v_exp_f32_e32 v122, v110
	v_exp_f32_e32 v123, v111
	v_pk_add_f32 v[110:111], v[188:189], v[118:119]
	v_pk_add_f32 v[108:109], v[186:187], v[116:117]
	v_cvt_pk_bf16_f32 v104, v186, v187
	v_cvt_pk_bf16_f32 v105, v188, v189
	v_cvt_pk_bf16_f32 v106, v120, v121
	v_cvt_pk_bf16_f32 v107, v122, v123
	v_pk_add_f32 v[178:179], v[122:123], v[110:111]
	v_pk_add_f32 v[176:177], v[120:121], v[108:109]
	s_waitcnt vmcnt(4) lgkmcnt(0)
	s_barrier
	s_add_u32 s70, s98, 0x18000
	s_addc_u32 s71, s99, 0
	s_add_i32 s68, 0x8000, s57
	s_mov_b32 m0, s68
	s_nop 0
	global_load_lds_dwordx4 v198, s[70:71]
	s_add_i32 m0, s68, 0x400
	s_nop 0
	global_load_lds_dwordx4 v194, s[70:71]
	s_add_u32 s2, s100, 0x80
	s_addc_u32 s3, s101, 0
	s_add_i32 s49, s58, 0x8000
	s_add_i32 m0, s49, 0xc000
	s_nop 0
	global_load_lds_dwordx4 v196, s[2:3]
	s_add_i32 m0, s49, 0xc400
	s_nop 0
	global_load_lds_dwordx4 v192, s[2:3]
	ds_read_b128 v[108:111], v236 offset:32768
	ds_read_b128 v[116:119], v236 offset:36864
	ds_read_b128 v[120:123], v236 offset:40960
	ds_read_b128 v[124:127], v236 offset:45056
	s_waitcnt lgkmcnt(0)
	v_mfma_f32_32x32x16_bf16 v[80:95], v[108:111], v[112:115], v[80:95]
	ds_read_b128 v[108:111], v237 offset:32768
	v_mfma_f32_32x32x16_bf16 v[64:79], v[116:119], v[112:115], v[64:79]
	ds_read_b128 v[116:119], v237 offset:36864
	v_mfma_f32_32x32x16_bf16 v[16:31], v[120:123], v[112:115], v[16:31]
	ds_read_b128 v[120:123], v237 offset:40960
	v_mfma_f32_32x32x16_bf16 v[0:15], v[124:127], v[112:115], v[0:15]
	ds_read_b128 v[112:115], v237 offset:45056
	s_waitcnt lgkmcnt(0)
	v_mfma_f32_32x32x16_bf16 v[80:95], v[108:111], v[96:99], v[80:95]
	ds_read_b128 v[108:111], v238 offset:32768
	v_mfma_f32_32x32x16_bf16 v[64:79], v[116:119], v[96:99], v[64:79]
	ds_read_b128 v[116:119], v238 offset:36864
	v_mfma_f32_32x32x16_bf16 v[16:31], v[120:123], v[96:99], v[16:31]
	ds_read_b128 v[120:123], v238 offset:40960
	v_mfma_f32_32x32x16_bf16 v[0:15], v[112:115], v[96:99], v[0:15]
	ds_read_b128 v[96:99], v238 offset:45056
	s_waitcnt lgkmcnt(0)
	v_mfma_f32_32x32x16_bf16 v[80:95], v[108:111], v[100:103], v[80:95]
	ds_read_b128 v[108:111], v239 offset:32768
	v_mfma_f32_32x32x16_bf16 v[64:79], v[116:119], v[100:103], v[64:79]
	ds_read_b128 v[112:115], v239 offset:36864
	v_mfma_f32_32x32x16_bf16 v[16:31], v[120:123], v[100:103], v[16:31]
	ds_read_b128 v[116:119], v239 offset:40960
	v_mfma_f32_32x32x16_bf16 v[0:15], v[96:99], v[100:103], v[0:15]
	ds_read_b128 v[120:123], v239 offset:45056
	s_waitcnt lgkmcnt(0)
	v_mfma_f32_32x32x16_bf16 v[80:95], v[108:111], v[104:107], v[80:95]
	ds_read_b128 v[96:99], v205
	v_mfma_f32_32x32x16_bf16 v[64:79], v[112:115], v[104:107], v[64:79]
	ds_read_b128 v[100:103], v205 offset:8192
	v_mfma_f32_32x32x16_bf16 v[16:31], v[116:119], v[104:107], v[16:31]
	ds_read_b128 v[182:185], v211
	v_mfma_f32_32x32x16_bf16 v[0:15], v[120:123], v[104:107], v[0:15]
	ds_read_b128 v[186:189], v211 offset:8192
	s_waitcnt lgkmcnt(0)
	v_mfma_f32_32x32x16_bf16 v[112:127], v[96:99], v[160:163], 0
	ds_read_b128 v[216:219], v212
	v_exp_f32_e32 v224, v144
	v_exp_f32_e32 v225, v145
	v_exp_f32_e32 v226, v146
	v_exp_f32_e32 v227, v147
	ds_read_b128 v[220:223], v212 offset:8192
	v_mfma_f32_32x32x16_bf16 v[96:111], v[100:103], v[160:163], 0
	v_exp_f32_e32 v228, v148
	v_exp_f32_e32 v229, v149
	v_exp_f32_e32 v230, v150
	v_exp_f32_e32 v231, v151
	v_mfma_f32_32x32x16_bf16 v[112:127], v[182:185], v[164:167], v[112:127]
	ds_read_b128 v[148:151], v213
	v_exp_f32_e32 v232, v152
	v_exp_f32_e32 v233, v153
	v_exp_f32_e32 v234, v154
	v_exp_f32_e32 v235, v155
	v_cvt_pk_bf16_f32 v144, v224, v225
	v_cvt_pk_bf16_f32 v145, v226, v227
	v_cvt_pk_bf16_f32 v146, v228, v229
	v_cvt_pk_bf16_f32 v147, v230, v231
	v_pk_add_f32 v[154:155], v[230:231], v[226:227]
	v_pk_add_f32 v[152:153], v[228:229], v[224:225]
	v_mfma_f32_32x32x16_bf16 v[96:111], v[186:189], v[164:167], v[96:111]
	ds_read_b128 v[182:185], v213 offset:8192
	v_exp_f32_e32 v156, v156
	v_exp_f32_e32 v157, v157
	v_exp_f32_e32 v158, v158
	v_exp_f32_e32 v159, v159
	s_waitcnt lgkmcnt(0)
	v_mfma_f32_32x32x16_bf16 v[112:127], v[216:219], v[168:171], v[112:127]
	v_add_f32_e64 v154, v234, v154
	v_add_f32_e64 v155, v235, v155
	v_add_f32_e64 v152, v232, v152
	v_add_f32_e64 v153, v233, v153
	v_exp_f32_e32 v186, v128
	v_exp_f32_e32 v187, v129
	v_exp_f32_e32 v188, v130
	v_exp_f32_e32 v189, v131
	v_cvt_pk_bf16_f32 v128, v232, v233
	v_cvt_pk_bf16_f32 v129, v234, v235
	v_cvt_pk_bf16_f32 v130, v156, v157
	v_cvt_pk_bf16_f32 v131, v158, v159
	v_pk_add_f32 v[154:155], v[158:159], v[154:155]
	v_pk_add_f32 v[152:153], v[156:157], v[152:153]
	v_mfma_f32_32x32x16_bf16 v[96:111], v[220:223], v[168:171], v[96:111]
	v_exp_f32_e32 v156, v132
	v_exp_f32_e32 v157, v133
	v_exp_f32_e32 v158, v134
	v_exp_f32_e32 v159, v135
	v_mfma_f32_32x32x16_bf16 v[112:127], v[148:151], v[172:175], v[112:127]
	v_exp_f32_e32 v216, v136
	v_exp_f32_e32 v217, v137
	v_exp_f32_e32 v218, v138
	v_exp_f32_e32 v219, v139
	v_pk_add_f32 v[138:139], v[188:189], v[154:155]
	v_pk_add_f32 v[136:137], v[186:187], v[152:153]
	v_cvt_pk_bf16_f32 v132, v186, v187
	v_cvt_pk_bf16_f32 v133, v188, v189
	v_cvt_pk_bf16_f32 v134, v156, v157
	v_cvt_pk_bf16_f32 v135, v158, v159
	v_pk_add_f32 v[150:151], v[158:159], v[138:139]
	v_pk_add_f32 v[148:149], v[156:157], v[136:137]
	v_mfma_f32_32x32x16_bf16 v[96:111], v[182:185], v[172:175], v[96:111]
	v_exp_f32_e32 v152, v140
	v_exp_f32_e32 v153, v141
	v_exp_f32_e32 v154, v142
	v_exp_f32_e32 v155, v143
	v_pk_add_f32 v[142:143], v[218:219], v[150:151]
	v_pk_add_f32 v[140:141], v[216:217], v[148:149]
	v_cvt_pk_bf16_f32 v136, v216, v217
	v_cvt_pk_bf16_f32 v137, v218, v219
	v_cvt_pk_bf16_f32 v138, v152, v153
	v_cvt_pk_bf16_f32 v139, v154, v155
	v_pk_add_f32 v[142:143], v[154:155], v[142:143]
	v_pk_add_f32 v[140:141], v[152:153], v[140:141]
	s_waitcnt vmcnt(4) lgkmcnt(0)
	v_add_f32_e32 v148, v176, v177
	v_add_f32_e32 v149, v178, v179
	v_add_f32_e32 v148, v148, v149
	v_add_f32_e32 v140, v140, v141
	v_add_f32_e32 v141, v142, v143
	s_barrier
	v_add_f32_e32 v148, v180, v148
	v_add_f32_e32 v140, v140, v141
	v_add_f32_e32 v180, v148, v140
	s_add_u32 s98, s98, 0x30000
	s_addc_u32 s99, s99, 0
	s_add_u32 s100, s100, 0x100
	s_addc_u32 s101, s101, 0
	s_add_i32 s49, s58, 0
	s_mov_b32 m0, s49
	s_nop 0
	global_load_lds_dwordx4 v198, s[98:99]
	s_add_i32 m0, s49, 0x400
	s_nop 0
	global_load_lds_dwordx4 v194, s[98:99]
	s_add_i32 s49, s58, 0xc000
	s_add_i32 m0, s49, 0xc000
	s_nop 0
	global_load_lds_dwordx4 v196, s[100:101]
	s_add_i32 m0, s49, 0xc400
	s_nop 0
	global_load_lds_dwordx4 v192, s[100:101]
	ds_read_b128 v[140:143], v206 offset:49152
	ds_read_b128 v[148:151], v206 offset:53248
	ds_read_b128 v[152:155], v206 offset:57344
	ds_read_b128 v[156:159], v206 offset:61440
	s_waitcnt lgkmcnt(0)
	v_mfma_f32_32x32x16_bf16 v[80:95], v[140:143], v[144:147], v[80:95]
	ds_read_b128 v[140:143], v207 offset:49152
	v_mfma_f32_32x32x16_bf16 v[64:79], v[148:151], v[144:147], v[64:79]
	ds_read_b128 v[148:151], v207 offset:53248
	v_mfma_f32_32x32x16_bf16 v[16:31], v[152:155], v[144:147], v[16:31]
	ds_read_b128 v[152:155], v207 offset:57344
	v_mfma_f32_32x32x16_bf16 v[0:15], v[156:159], v[144:147], v[0:15]
	ds_read_b128 v[144:147], v207 offset:61440
	s_waitcnt lgkmcnt(0)
	v_mfma_f32_32x32x16_bf16 v[80:95], v[140:143], v[128:131], v[80:95]
	ds_read_b128 v[140:143], v208 offset:49152
	v_mfma_f32_32x32x16_bf16 v[64:79], v[148:151], v[128:131], v[64:79]
	ds_read_b128 v[148:151], v208 offset:53248
	v_mfma_f32_32x32x16_bf16 v[16:31], v[152:155], v[128:131], v[16:31]
	ds_read_b128 v[152:155], v208 offset:57344
	v_mfma_f32_32x32x16_bf16 v[0:15], v[144:147], v[128:131], v[0:15]
	ds_read_b128 v[128:131], v208 offset:61440
	s_waitcnt lgkmcnt(0)
	v_mfma_f32_32x32x16_bf16 v[80:95], v[140:143], v[132:135], v[80:95]
	ds_read_b128 v[140:143], v209 offset:49152
	v_mfma_f32_32x32x16_bf16 v[64:79], v[148:151], v[132:135], v[64:79]
	ds_read_b128 v[144:147], v209 offset:53248
	v_mfma_f32_32x32x16_bf16 v[16:31], v[152:155], v[132:135], v[16:31]
	ds_read_b128 v[148:151], v209 offset:57344
	v_mfma_f32_32x32x16_bf16 v[0:15], v[128:131], v[132:135], v[0:15]
	ds_read_b128 v[128:131], v209 offset:61440
	s_waitcnt lgkmcnt(0)
	v_mfma_f32_32x32x16_bf16 v[80:95], v[140:143], v[136:139], v[80:95]
	ds_read_b128 v[132:135], v205 offset:16384
	v_mfma_f32_32x32x16_bf16 v[64:79], v[144:147], v[136:139], v[64:79]
	ds_read_b128 v[140:143], v205 offset:24576
	v_mfma_f32_32x32x16_bf16 v[16:31], v[148:151], v[136:139], v[16:31]
	ds_read_b128 v[176:179], v211 offset:16384
	v_mfma_f32_32x32x16_bf16 v[0:15], v[128:131], v[136:139], v[0:15]
	ds_read_b128 v[182:185], v211 offset:24576
	s_waitcnt lgkmcnt(0)
	v_mfma_f32_32x32x16_bf16 v[144:159], v[132:135], v[160:163], 0
	ds_read_b128 v[186:189], v212 offset:16384
	v_exp_f32_e32 v220, v112
	v_exp_f32_e32 v221, v113
	v_exp_f32_e32 v222, v114
	v_exp_f32_e32 v223, v115
	v_mfma_f32_32x32x16_bf16 v[128:143], v[140:143], v[160:163], 0
	ds_read_b128 v[216:219], v212 offset:24576
	v_exp_f32_e32 v224, v116
	v_exp_f32_e32 v225, v117
	v_exp_f32_e32 v226, v118
	v_exp_f32_e32 v227, v119
	v_mfma_f32_32x32x16_bf16 v[144:159], v[176:179], v[164:167], v[144:159]
	ds_read_b128 v[116:119], v213 offset:16384
	v_exp_f32_e32 v228, v120
	v_exp_f32_e32 v229, v121
	v_exp_f32_e32 v230, v122
	v_exp_f32_e32 v231, v123
	v_cvt_pk_bf16_f32 v112, v220, v221
	v_cvt_pk_bf16_f32 v113, v222, v223
	v_cvt_pk_bf16_f32 v114, v224, v225
	v_cvt_pk_bf16_f32 v115, v226, v227
	v_pk_add_f32 v[122:123], v[226:227], v[222:223]
	v_pk_add_f32 v[120:121], v[224:225], v[220:221]
	v_mfma_f32_32x32x16_bf16 v[128:143], v[182:185], v[164:167], v[128:143]
	ds_read_b128 v[176:179], v213 offset:24576
	v_exp_f32_e32 v124, v124
	v_exp_f32_e32 v125, v125
	v_exp_f32_e32 v126, v126
	v_exp_f32_e32 v127, v127
	s_waitcnt lgkmcnt(0)
	v_mfma_f32_32x32x16_bf16 v[144:159], v[186:189], v[168:171], v[144:159]
	v_add_f32_e64 v122, v230, v122
	v_add_f32_e64 v123, v231, v123
	v_add_f32_e64 v120, v228, v120
	v_add_f32_e64 v121, v229, v121
	v_exp_f32_e32 v182, v96
	v_exp_f32_e32 v183, v97
	v_exp_f32_e32 v184, v98
	v_exp_f32_e32 v185, v99
	v_cvt_pk_bf16_f32 v96, v228, v229
	v_cvt_pk_bf16_f32 v97, v230, v231
	v_cvt_pk_bf16_f32 v98, v124, v125
	v_cvt_pk_bf16_f32 v99, v126, v127
	v_pk_add_f32 v[122:123], v[126:127], v[122:123]
	v_pk_add_f32 v[120:121], v[124:125], v[120:121]
	v_mfma_f32_32x32x16_bf16 v[128:143], v[216:219], v[168:171], v[128:143]
	v_exp_f32_e32 v124, v100
	v_exp_f32_e32 v125, v101
	v_exp_f32_e32 v126, v102
	v_exp_f32_e32 v127, v103
	v_mfma_f32_32x32x16_bf16 v[144:159], v[116:119], v[172:175], v[144:159]
	v_exp_f32_e32 v186, v104
	v_exp_f32_e32 v187, v105
	v_exp_f32_e32 v188, v106
	v_exp_f32_e32 v189, v107
	v_pk_add_f32 v[106:107], v[184:185], v[122:123]
	v_pk_add_f32 v[104:105], v[182:183], v[120:121]
	v_cvt_pk_bf16_f32 v100, v182, v183
	v_cvt_pk_bf16_f32 v101, v184, v185
	v_cvt_pk_bf16_f32 v102, v124, v125
	v_cvt_pk_bf16_f32 v103, v126, v127
	v_pk_add_f32 v[118:119], v[126:127], v[106:107]
	v_pk_add_f32 v[116:117], v[124:125], v[104:105]
	v_mfma_f32_32x32x16_bf16 v[128:143], v[176:179], v[172:175], v[128:143]
	v_exp_f32_e32 v120, v108
	v_exp_f32_e32 v121, v109
	v_exp_f32_e32 v122, v110
	v_exp_f32_e32 v123, v111
	v_pk_add_f32 v[110:111], v[188:189], v[118:119]
	v_pk_add_f32 v[108:109], v[186:187], v[116:117]
	v_cvt_pk_bf16_f32 v104, v186, v187
	v_cvt_pk_bf16_f32 v105, v188, v189
	v_cvt_pk_bf16_f32 v106, v120, v121
	v_cvt_pk_bf16_f32 v107, v122, v123
	v_pk_add_f32 v[178:179], v[122:123], v[110:111]
	v_pk_add_f32 v[176:177], v[120:121], v[108:109]
	s_waitcnt vmcnt(4) lgkmcnt(0)
	s_barrier
	s_add_u32 s70, s98, 0x18000
	s_addc_u32 s71, s99, 0
	s_add_i32 s68, 0x4000, s57
	s_mov_b32 m0, s68
	s_nop 0
	global_load_lds_dwordx4 v198, s[70:71]
	s_add_i32 m0, s68, 0x400
	s_nop 0
	global_load_lds_dwordx4 v194, s[70:71]
	s_add_u32 s2, s100, 0x80
	s_addc_u32 s3, s101, 0
	s_add_i32 s49, s58, 0
	s_add_i32 m0, s49, 0xc000
	s_nop 0
	global_load_lds_dwordx4 v196, s[2:3]
	s_add_i32 m0, s49, 0xc400
	s_nop 0
	global_load_lds_dwordx4 v192, s[2:3]
	ds_read_b128 v[108:111], v236
	ds_read_b128 v[116:119], v236 offset:4096
	ds_read_b128 v[120:123], v236 offset:8192
	ds_read_b128 v[124:127], v236 offset:12288
	s_waitcnt lgkmcnt(0)
	v_mfma_f32_32x32x16_bf16 v[80:95], v[108:111], v[112:115], v[80:95]
	ds_read_b128 v[108:111], v237
	v_mfma_f32_32x32x16_bf16 v[64:79], v[116:119], v[112:115], v[64:79]
	ds_read_b128 v[116:119], v237 offset:4096
	v_mfma_f32_32x32x16_bf16 v[16:31], v[120:123], v[112:115], v[16:31]
	ds_read_b128 v[120:123], v237 offset:8192
	v_mfma_f32_32x32x16_bf16 v[0:15], v[124:127], v[112:115], v[0:15]
	ds_read_b128 v[112:115], v237 offset:12288
	s_waitcnt lgkmcnt(0)
	v_mfma_f32_32x32x16_bf16 v[80:95], v[108:111], v[96:99], v[80:95]
	ds_read_b128 v[108:111], v238
	v_mfma_f32_32x32x16_bf16 v[64:79], v[116:119], v[96:99], v[64:79]
	ds_read_b128 v[116:119], v238 offset:4096
	v_mfma_f32_32x32x16_bf16 v[16:31], v[120:123], v[96:99], v[16:31]
	ds_read_b128 v[120:123], v238 offset:8192
	v_mfma_f32_32x32x16_bf16 v[0:15], v[112:115], v[96:99], v[0:15]
	ds_read_b128 v[96:99], v238 offset:12288
	s_waitcnt lgkmcnt(0)
	v_mfma_f32_32x32x16_bf16 v[80:95], v[108:111], v[100:103], v[80:95]
	ds_read_b128 v[108:111], v239
	v_mfma_f32_32x32x16_bf16 v[64:79], v[116:119], v[100:103], v[64:79]
	ds_read_b128 v[112:115], v239 offset:4096
	v_mfma_f32_32x32x16_bf16 v[16:31], v[120:123], v[100:103], v[16:31]
	ds_read_b128 v[116:119], v239 offset:8192
	v_mfma_f32_32x32x16_bf16 v[0:15], v[96:99], v[100:103], v[0:15]
	ds_read_b128 v[120:123], v239 offset:12288
	s_waitcnt lgkmcnt(0)
	v_mfma_f32_32x32x16_bf16 v[80:95], v[108:111], v[104:107], v[80:95]
	ds_read_b128 v[96:99], v205 offset:32768
	v_mfma_f32_32x32x16_bf16 v[64:79], v[112:115], v[104:107], v[64:79]
	ds_read_b128 v[100:103], v205 offset:40960
	v_mfma_f32_32x32x16_bf16 v[16:31], v[116:119], v[104:107], v[16:31]
	ds_read_b128 v[182:185], v211 offset:32768
	v_mfma_f32_32x32x16_bf16 v[0:15], v[120:123], v[104:107], v[0:15]
	ds_read_b128 v[186:189], v211 offset:40960
	s_waitcnt lgkmcnt(0)
	v_mfma_f32_32x32x16_bf16 v[112:127], v[96:99], v[160:163], 0
	ds_read_b128 v[216:219], v212 offset:32768
	v_exp_f32_e32 v224, v144
	v_exp_f32_e32 v225, v145
	v_exp_f32_e32 v226, v146
	v_exp_f32_e32 v227, v147
	ds_read_b128 v[220:223], v212 offset:40960
	v_mfma_f32_32x32x16_bf16 v[96:111], v[100:103], v[160:163], 0
	v_exp_f32_e32 v228, v148
	v_exp_f32_e32 v229, v149
	v_exp_f32_e32 v230, v150
	v_exp_f32_e32 v231, v151
	v_mfma_f32_32x32x16_bf16 v[112:127], v[182:185], v[164:167], v[112:127]
	ds_read_b128 v[148:151], v213 offset:32768
	v_exp_f32_e32 v232, v152
	v_exp_f32_e32 v233, v153
	v_exp_f32_e32 v234, v154
	v_exp_f32_e32 v235, v155
	v_cvt_pk_bf16_f32 v144, v224, v225
	v_cvt_pk_bf16_f32 v145, v226, v227
	v_cvt_pk_bf16_f32 v146, v228, v229
	v_cvt_pk_bf16_f32 v147, v230, v231
	v_pk_add_f32 v[154:155], v[230:231], v[226:227]
	v_pk_add_f32 v[152:153], v[228:229], v[224:225]
	v_mfma_f32_32x32x16_bf16 v[96:111], v[186:189], v[164:167], v[96:111]
	ds_read_b128 v[182:185], v213 offset:40960
	v_exp_f32_e32 v156, v156
	v_exp_f32_e32 v157, v157
	v_exp_f32_e32 v158, v158
	v_exp_f32_e32 v159, v159
	s_waitcnt lgkmcnt(0)
	v_mfma_f32_32x32x16_bf16 v[112:127], v[216:219], v[168:171], v[112:127]
	v_add_f32_e64 v154, v234, v154
	v_add_f32_e64 v155, v235, v155
	v_add_f32_e64 v152, v232, v152
	v_add_f32_e64 v153, v233, v153
	v_exp_f32_e32 v186, v128
	v_exp_f32_e32 v187, v129
	v_exp_f32_e32 v188, v130
	v_exp_f32_e32 v189, v131
	v_cvt_pk_bf16_f32 v128, v232, v233
	v_cvt_pk_bf16_f32 v129, v234, v235
	v_cvt_pk_bf16_f32 v130, v156, v157
	v_cvt_pk_bf16_f32 v131, v158, v159
	v_pk_add_f32 v[154:155], v[158:159], v[154:155]
	v_pk_add_f32 v[152:153], v[156:157], v[152:153]
	v_mfma_f32_32x32x16_bf16 v[96:111], v[220:223], v[168:171], v[96:111]
	v_exp_f32_e32 v156, v132
	v_exp_f32_e32 v157, v133
	v_exp_f32_e32 v158, v134
	v_exp_f32_e32 v159, v135
	v_mfma_f32_32x32x16_bf16 v[112:127], v[148:151], v[172:175], v[112:127]
	v_exp_f32_e32 v216, v136
	v_exp_f32_e32 v217, v137
	v_exp_f32_e32 v218, v138
	v_exp_f32_e32 v219, v139
	v_pk_add_f32 v[138:139], v[188:189], v[154:155]
	v_pk_add_f32 v[136:137], v[186:187], v[152:153]
	v_cvt_pk_bf16_f32 v132, v186, v187
	v_cvt_pk_bf16_f32 v133, v188, v189
	v_cvt_pk_bf16_f32 v134, v156, v157
	v_cvt_pk_bf16_f32 v135, v158, v159
	v_pk_add_f32 v[150:151], v[158:159], v[138:139]
	v_pk_add_f32 v[148:149], v[156:157], v[136:137]
	v_mfma_f32_32x32x16_bf16 v[96:111], v[182:185], v[172:175], v[96:111]
	v_exp_f32_e32 v152, v140
	v_exp_f32_e32 v153, v141
	v_exp_f32_e32 v154, v142
	v_exp_f32_e32 v155, v143
	v_pk_add_f32 v[142:143], v[218:219], v[150:151]
	v_pk_add_f32 v[140:141], v[216:217], v[148:149]
	v_cvt_pk_bf16_f32 v136, v216, v217
	v_cvt_pk_bf16_f32 v137, v218, v219
	v_cvt_pk_bf16_f32 v138, v152, v153
	v_cvt_pk_bf16_f32 v139, v154, v155
	v_pk_add_f32 v[142:143], v[154:155], v[142:143]
	v_pk_add_f32 v[140:141], v[152:153], v[140:141]
	s_waitcnt vmcnt(4) lgkmcnt(0)
	v_add_f32_e32 v148, v176, v177
	v_add_f32_e32 v149, v178, v179
	v_add_f32_e32 v148, v148, v149
	v_add_f32_e32 v140, v140, v141
	v_add_f32_e32 v141, v142, v143
	s_barrier
	v_add_f32_e32 v148, v180, v148
	v_add_f32_e32 v140, v140, v141
	v_add_f32_e32 v180, v148, v140
	s_add_u32 s98, s98, 0x30000
	s_addc_u32 s99, s99, 0
	s_add_u32 s100, s100, 0x100
	s_addc_u32 s101, s101, 0
	s_add_i32 s49, s58, 0x8000
	s_mov_b32 m0, s49
	s_nop 0
	global_load_lds_dwordx4 v198, s[98:99]
	s_add_i32 m0, s49, 0x400
	s_nop 0
	global_load_lds_dwordx4 v194, s[98:99]
	s_add_i32 s49, s58, 0x4000
	s_add_i32 m0, s49, 0xc000
	s_nop 0
	global_load_lds_dwordx4 v196, s[100:101]
	s_add_i32 m0, s49, 0xc400
	s_nop 0
	global_load_lds_dwordx4 v192, s[100:101]
	ds_read_b128 v[140:143], v236 offset:16384
	ds_read_b128 v[148:151], v236 offset:20480
	ds_read_b128 v[152:155], v236 offset:24576
	ds_read_b128 v[156:159], v236 offset:28672
	s_waitcnt lgkmcnt(0)
	v_mfma_f32_32x32x16_bf16 v[80:95], v[140:143], v[144:147], v[80:95]
	ds_read_b128 v[140:143], v237 offset:16384
	v_mfma_f32_32x32x16_bf16 v[64:79], v[148:151], v[144:147], v[64:79]
	ds_read_b128 v[148:151], v237 offset:20480
	v_mfma_f32_32x32x16_bf16 v[16:31], v[152:155], v[144:147], v[16:31]
	ds_read_b128 v[152:155], v237 offset:24576
	v_mfma_f32_32x32x16_bf16 v[0:15], v[156:159], v[144:147], v[0:15]
	ds_read_b128 v[144:147], v237 offset:28672
	s_waitcnt lgkmcnt(0)
	v_mfma_f32_32x32x16_bf16 v[80:95], v[140:143], v[128:131], v[80:95]
	ds_read_b128 v[140:143], v238 offset:16384
	v_mfma_f32_32x32x16_bf16 v[64:79], v[148:151], v[128:131], v[64:79]
	ds_read_b128 v[148:151], v238 offset:20480
	v_mfma_f32_32x32x16_bf16 v[16:31], v[152:155], v[128:131], v[16:31]
	ds_read_b128 v[152:155], v238 offset:24576
	v_mfma_f32_32x32x16_bf16 v[0:15], v[144:147], v[128:131], v[0:15]
	ds_read_b128 v[128:131], v238 offset:28672
	s_waitcnt lgkmcnt(0)
	v_mfma_f32_32x32x16_bf16 v[80:95], v[140:143], v[132:135], v[80:95]
	ds_read_b128 v[140:143], v239 offset:16384
	v_mfma_f32_32x32x16_bf16 v[64:79], v[148:151], v[132:135], v[64:79]
	ds_read_b128 v[144:147], v239 offset:20480
	v_mfma_f32_32x32x16_bf16 v[16:31], v[152:155], v[132:135], v[16:31]
	ds_read_b128 v[148:151], v239 offset:24576
	v_mfma_f32_32x32x16_bf16 v[0:15], v[128:131], v[132:135], v[0:15]
	ds_read_b128 v[128:131], v239 offset:28672
	s_waitcnt lgkmcnt(0)
	v_mfma_f32_32x32x16_bf16 v[80:95], v[140:143], v[136:139], v[80:95]
	ds_read_b128 v[132:135], v205
	v_mfma_f32_32x32x16_bf16 v[64:79], v[144:147], v[136:139], v[64:79]
	ds_read_b128 v[140:143], v205 offset:8192
	v_mfma_f32_32x32x16_bf16 v[16:31], v[148:151], v[136:139], v[16:31]
	ds_read_b128 v[176:179], v211
	v_mfma_f32_32x32x16_bf16 v[0:15], v[128:131], v[136:139], v[0:15]
	ds_read_b128 v[182:185], v211 offset:8192
	s_waitcnt lgkmcnt(0)
	v_mfma_f32_32x32x16_bf16 v[144:159], v[132:135], v[160:163], 0
	ds_read_b128 v[186:189], v212
	v_exp_f32_e32 v220, v112
	v_exp_f32_e32 v221, v113
	v_exp_f32_e32 v222, v114
	v_exp_f32_e32 v223, v115
	v_mfma_f32_32x32x16_bf16 v[128:143], v[140:143], v[160:163], 0
	ds_read_b128 v[216:219], v212 offset:8192
	v_exp_f32_e32 v224, v116
	v_exp_f32_e32 v225, v117
	v_exp_f32_e32 v226, v118
	v_exp_f32_e32 v227, v119
	v_mfma_f32_32x32x16_bf16 v[144:159], v[176:179], v[164:167], v[144:159]
	ds_read_b128 v[116:119], v213
	v_exp_f32_e32 v228, v120
	v_exp_f32_e32 v229, v121
	v_exp_f32_e32 v230, v122
	v_exp_f32_e32 v231, v123
	v_cvt_pk_bf16_f32 v112, v220, v221
	v_cvt_pk_bf16_f32 v113, v222, v223
	v_cvt_pk_bf16_f32 v114, v224, v225
	v_cvt_pk_bf16_f32 v115, v226, v227
	v_pk_add_f32 v[122:123], v[226:227], v[222:223]
	v_pk_add_f32 v[120:121], v[224:225], v[220:221]
	v_mfma_f32_32x32x16_bf16 v[128:143], v[182:185], v[164:167], v[128:143]
	ds_read_b128 v[176:179], v213 offset:8192
	v_exp_f32_e32 v124, v124
	v_exp_f32_e32 v125, v125
	v_exp_f32_e32 v126, v126
	v_exp_f32_e32 v127, v127
	s_waitcnt lgkmcnt(0)
	v_mfma_f32_32x32x16_bf16 v[144:159], v[186:189], v[168:171], v[144:159]
	v_add_f32_e64 v122, v230, v122
	v_add_f32_e64 v123, v231, v123
	v_add_f32_e64 v120, v228, v120
	v_add_f32_e64 v121, v229, v121
	v_exp_f32_e32 v182, v96
	v_exp_f32_e32 v183, v97
	v_exp_f32_e32 v184, v98
	v_exp_f32_e32 v185, v99
	v_cvt_pk_bf16_f32 v96, v228, v229
	v_cvt_pk_bf16_f32 v97, v230, v231
	v_cvt_pk_bf16_f32 v98, v124, v125
	v_cvt_pk_bf16_f32 v99, v126, v127
	v_pk_add_f32 v[122:123], v[126:127], v[122:123]
	v_pk_add_f32 v[120:121], v[124:125], v[120:121]
	v_mfma_f32_32x32x16_bf16 v[128:143], v[216:219], v[168:171], v[128:143]
	v_exp_f32_e32 v124, v100
	v_exp_f32_e32 v125, v101
	v_exp_f32_e32 v126, v102
	v_exp_f32_e32 v127, v103
	v_mfma_f32_32x32x16_bf16 v[144:159], v[116:119], v[172:175], v[144:159]
	v_exp_f32_e32 v186, v104
	v_exp_f32_e32 v187, v105
	v_exp_f32_e32 v188, v106
	v_exp_f32_e32 v189, v107
	v_pk_add_f32 v[106:107], v[184:185], v[122:123]
	v_pk_add_f32 v[104:105], v[182:183], v[120:121]
	v_cvt_pk_bf16_f32 v100, v182, v183
	v_cvt_pk_bf16_f32 v101, v184, v185
	v_cvt_pk_bf16_f32 v102, v124, v125
	v_cvt_pk_bf16_f32 v103, v126, v127
	v_pk_add_f32 v[118:119], v[126:127], v[106:107]
	v_pk_add_f32 v[116:117], v[124:125], v[104:105]
	v_mfma_f32_32x32x16_bf16 v[128:143], v[176:179], v[172:175], v[128:143]
	v_exp_f32_e32 v120, v108
	v_exp_f32_e32 v121, v109
	v_exp_f32_e32 v122, v110
	v_exp_f32_e32 v123, v111
	v_pk_add_f32 v[110:111], v[188:189], v[118:119]
	v_pk_add_f32 v[108:109], v[186:187], v[116:117]
	v_cvt_pk_bf16_f32 v104, v186, v187
	v_cvt_pk_bf16_f32 v105, v188, v189
	v_cvt_pk_bf16_f32 v106, v120, v121
	v_cvt_pk_bf16_f32 v107, v122, v123
	v_pk_add_f32 v[178:179], v[122:123], v[110:111]
	v_pk_add_f32 v[176:177], v[120:121], v[108:109]
	s_waitcnt vmcnt(4) lgkmcnt(0)
	s_barrier
	s_add_u32 s70, s98, 0x18000
	s_addc_u32 s71, s99, 0
	s_add_i32 s68, 0, s57
	s_mov_b32 m0, s68
	s_nop 0
	global_load_lds_dwordx4 v198, s[70:71]
	s_add_i32 m0, s68, 0x400
	s_nop 0
	global_load_lds_dwordx4 v194, s[70:71]
	s_add_u32 s2, s100, 0x80
	s_addc_u32 s3, s101, 0
	s_add_i32 s49, s58, 0x8000
	s_add_i32 m0, s49, 0xc000
	s_nop 0
	global_load_lds_dwordx4 v196, s[2:3]
	s_add_i32 m0, s49, 0xc400
	s_nop 0
	global_load_lds_dwordx4 v192, s[2:3]
	ds_read_b128 v[108:111], v236 offset:32768
	ds_read_b128 v[116:119], v236 offset:36864
	ds_read_b128 v[120:123], v236 offset:40960
	ds_read_b128 v[124:127], v236 offset:45056
	s_waitcnt lgkmcnt(0)
	v_mfma_f32_32x32x16_bf16 v[80:95], v[108:111], v[112:115], v[80:95]
	ds_read_b128 v[108:111], v237 offset:32768
	v_mfma_f32_32x32x16_bf16 v[64:79], v[116:119], v[112:115], v[64:79]
	ds_read_b128 v[116:119], v237 offset:36864
	v_mfma_f32_32x32x16_bf16 v[16:31], v[120:123], v[112:115], v[16:31]
	ds_read_b128 v[120:123], v237 offset:40960
	v_mfma_f32_32x32x16_bf16 v[0:15], v[124:127], v[112:115], v[0:15]
	ds_read_b128 v[112:115], v237 offset:45056
	s_waitcnt lgkmcnt(0)
	v_mfma_f32_32x32x16_bf16 v[80:95], v[108:111], v[96:99], v[80:95]
	ds_read_b128 v[108:111], v238 offset:32768
	v_mfma_f32_32x32x16_bf16 v[64:79], v[116:119], v[96:99], v[64:79]
	ds_read_b128 v[116:119], v238 offset:36864
	v_mfma_f32_32x32x16_bf16 v[16:31], v[120:123], v[96:99], v[16:31]
	ds_read_b128 v[120:123], v238 offset:40960
	v_mfma_f32_32x32x16_bf16 v[0:15], v[112:115], v[96:99], v[0:15]
	ds_read_b128 v[96:99], v238 offset:45056
	s_waitcnt lgkmcnt(0)
	v_mfma_f32_32x32x16_bf16 v[80:95], v[108:111], v[100:103], v[80:95]
	ds_read_b128 v[108:111], v239 offset:32768
	v_mfma_f32_32x32x16_bf16 v[64:79], v[116:119], v[100:103], v[64:79]
	ds_read_b128 v[112:115], v239 offset:36864
	v_mfma_f32_32x32x16_bf16 v[16:31], v[120:123], v[100:103], v[16:31]
	ds_read_b128 v[116:119], v239 offset:40960
	v_mfma_f32_32x32x16_bf16 v[0:15], v[96:99], v[100:103], v[0:15]
	ds_read_b128 v[120:123], v239 offset:45056
	s_waitcnt lgkmcnt(0)
	v_mfma_f32_32x32x16_bf16 v[80:95], v[108:111], v[104:107], v[80:95]
	ds_read_b128 v[96:99], v205 offset:16384
	v_mfma_f32_32x32x16_bf16 v[64:79], v[112:115], v[104:107], v[64:79]
	ds_read_b128 v[100:103], v205 offset:24576
	v_mfma_f32_32x32x16_bf16 v[16:31], v[116:119], v[104:107], v[16:31]
	ds_read_b128 v[182:185], v211 offset:16384
	v_mfma_f32_32x32x16_bf16 v[0:15], v[120:123], v[104:107], v[0:15]
	ds_read_b128 v[186:189], v211 offset:24576
	s_waitcnt lgkmcnt(0)
	v_mfma_f32_32x32x16_bf16 v[112:127], v[96:99], v[160:163], 0
	ds_read_b128 v[216:219], v212 offset:16384
	v_exp_f32_e32 v224, v144
	v_exp_f32_e32 v225, v145
	v_exp_f32_e32 v226, v146
	v_exp_f32_e32 v227, v147
	ds_read_b128 v[220:223], v212 offset:24576
	v_mfma_f32_32x32x16_bf16 v[96:111], v[100:103], v[160:163], 0
	v_exp_f32_e32 v228, v148
	v_exp_f32_e32 v229, v149
	v_exp_f32_e32 v230, v150
	v_exp_f32_e32 v231, v151
	v_mfma_f32_32x32x16_bf16 v[112:127], v[182:185], v[164:167], v[112:127]
	ds_read_b128 v[148:151], v213 offset:16384
	v_exp_f32_e32 v232, v152
	v_exp_f32_e32 v233, v153
	v_exp_f32_e32 v234, v154
	v_exp_f32_e32 v235, v155
	v_cvt_pk_bf16_f32 v144, v224, v225
	v_cvt_pk_bf16_f32 v145, v226, v227
	v_cvt_pk_bf16_f32 v146, v228, v229
	v_cvt_pk_bf16_f32 v147, v230, v231
	v_pk_add_f32 v[154:155], v[230:231], v[226:227]
	v_pk_add_f32 v[152:153], v[228:229], v[224:225]
	v_mfma_f32_32x32x16_bf16 v[96:111], v[186:189], v[164:167], v[96:111]
	ds_read_b128 v[182:185], v213 offset:24576
	v_exp_f32_e32 v156, v156
	v_exp_f32_e32 v157, v157
	v_exp_f32_e32 v158, v158
	v_exp_f32_e32 v159, v159
	s_waitcnt lgkmcnt(0)
	v_mfma_f32_32x32x16_bf16 v[112:127], v[216:219], v[168:171], v[112:127]
	v_add_f32_e64 v154, v234, v154
	v_add_f32_e64 v155, v235, v155
	v_add_f32_e64 v152, v232, v152
	v_add_f32_e64 v153, v233, v153
	v_exp_f32_e32 v186, v128
	v_exp_f32_e32 v187, v129
	v_exp_f32_e32 v188, v130
	v_exp_f32_e32 v189, v131
	v_cvt_pk_bf16_f32 v128, v232, v233
	v_cvt_pk_bf16_f32 v129, v234, v235
	v_cvt_pk_bf16_f32 v130, v156, v157
	v_cvt_pk_bf16_f32 v131, v158, v159
	v_pk_add_f32 v[154:155], v[158:159], v[154:155]
	v_pk_add_f32 v[152:153], v[156:157], v[152:153]
	v_mfma_f32_32x32x16_bf16 v[96:111], v[220:223], v[168:171], v[96:111]
	v_exp_f32_e32 v156, v132
	v_exp_f32_e32 v157, v133
	v_exp_f32_e32 v158, v134
	v_exp_f32_e32 v159, v135
	v_mfma_f32_32x32x16_bf16 v[112:127], v[148:151], v[172:175], v[112:127]
	v_exp_f32_e32 v216, v136
	v_exp_f32_e32 v217, v137
	v_exp_f32_e32 v218, v138
	v_exp_f32_e32 v219, v139
	v_pk_add_f32 v[138:139], v[188:189], v[154:155]
	v_pk_add_f32 v[136:137], v[186:187], v[152:153]
	v_cvt_pk_bf16_f32 v132, v186, v187
	v_cvt_pk_bf16_f32 v133, v188, v189
	v_cvt_pk_bf16_f32 v134, v156, v157
	v_cvt_pk_bf16_f32 v135, v158, v159
	v_pk_add_f32 v[150:151], v[158:159], v[138:139]
	v_pk_add_f32 v[148:149], v[156:157], v[136:137]
	v_mfma_f32_32x32x16_bf16 v[96:111], v[182:185], v[172:175], v[96:111]
	v_exp_f32_e32 v152, v140
	v_exp_f32_e32 v153, v141
	v_exp_f32_e32 v154, v142
	v_exp_f32_e32 v155, v143
	v_pk_add_f32 v[142:143], v[218:219], v[150:151]
	v_pk_add_f32 v[140:141], v[216:217], v[148:149]
	v_cvt_pk_bf16_f32 v136, v216, v217
	v_cvt_pk_bf16_f32 v137, v218, v219
	v_cvt_pk_bf16_f32 v138, v152, v153
	v_cvt_pk_bf16_f32 v139, v154, v155
	v_pk_add_f32 v[142:143], v[154:155], v[142:143]
	v_pk_add_f32 v[140:141], v[152:153], v[140:141]
	s_waitcnt vmcnt(4) lgkmcnt(0)
	v_add_f32_e32 v148, v176, v177
	v_add_f32_e32 v149, v178, v179
	v_add_f32_e32 v148, v148, v149
	v_add_f32_e32 v140, v140, v141
	v_add_f32_e32 v141, v142, v143
	s_barrier
	v_add_f32_e32 v148, v180, v148
	v_add_f32_e32 v140, v140, v141
	v_add_f32_e32 v180, v148, v140
	s_add_u32 s98, s98, 0x30000
	s_addc_u32 s99, s99, 0
	s_add_u32 s100, s100, 0x100
	s_addc_u32 s101, s101, 0
	s_add_i32 s47, s47, 12
	s_addk_i32 s41, 0x300
	s_add_i32 s46, s46, 0x30000
	s_cmp_lt_u32 s47, 50
	s_cbranch_scc1 .Lst1_u6_loop
	s_cmp_lt_u32 s47, 60
	s_cbranch_scc1 .Lst1_single
